# GEMM K-loops: waves 0-3 take each phase's counted vmcnt wait before the post-MFMA barrier instead of the pre-MFMA barrier (their DMA pieces are first read one barrier later); waves 4-7 unchanged
# baseline (speedup 1.0000x reference)
; #define PG8_STAGE(bufoff, gbase, voff) do { _Pragma("unroll") for (int _i = 0; _i < 2; ++_i) \
;         __builtin_amdgcn_global_load_lds((const unsigned*)((const char*)(gbase) + (voff)[_i]), (LAS unsigned*)(lds + (bufoff) + ldsw + _i * 8192), 16, 0, 0); } while (0)
; #define PG8_LDA(dst, b, h) do { _Pragma("unroll") for (int m = 0; m < 4; ++m) _Pragma("unroll") for (int k = 0; k < 2; ++k) dst[m][k] = *(const LAS bf16x8*)(lds + PG8_SA(b, h) + aoff + m * 2048 + k * 1024); } while (0)
; #define PG8_LDB(dst, b, h) do { _Pragma("unroll") for (int n = 0; n < 2; ++n) _Pragma("unroll") for (int k = 0; k < 2; ++k) dst[n][k] = *(const LAS bf16x8*)(lds + PG8_SB(b, h) + boff + n * 2048 + k * 1024); } while (0)
; #define PG8_MMA(ai, bj, At, Bt) do { __builtin_amdgcn_s_setprio(1); _Pragma("unroll") for (int m = 0; m < 4; ++m) _Pragma("unroll") for (int n = 0; n < 2; ++n) _Pragma("unroll") for (int k = 0; k < 2; ++k) \
;         acc[ai][bj][m][n] = __builtin_amdgcn_mfma_f32_16x16x32_bf16(Bt[n][k], At[m][k], acc[ai][bj][m][n], 0, 0, 0); __builtin_amdgcn_s_setprio(0); } while (0)
; template <class Epi, class Sched, bool ALIGN_EPI>
; __device__ __forceinline__ void gemm_phase(LAS unsigned char* lds, const int wid, const int lda_, const int ldb_, const int K_, const Sched& S, const Epi& E) {
;     ...
;         const bool has_next = S.next(ui + 1, nxt);
;         const int nt = S.nt(cur);
;         const char* nA = has_next ? S.a(nxt) : cA; const char* nB = has_next ? S.b(nxt) : cB;
; #pragma unroll 1
;         for (int t = 0; t < nt; t += 2) {
;             const bool last = (t == nt - 2);
;             const char* a1 = cA + (size_t)(t + 1) * kstep;
;             const char* a2 = last ? nA : cA + (size_t)(t + 2) * kstep; const char* b2 = last ? nB : cB + (size_t)(t + 2) * kstep;
;             const char* a3 = a2 + kstep; const char* b3 = b2 + kstep;
;             PG8_LDB(B0, 0, 0); PG8_LDB(B1, 0, 1); PG8_SCHED; PG8_LDA(At, 0, 0); PG8_STAGE(PG8_SA(1, 1), a1 + hstepA, voffA);
;             PG8_WAIT_V(8); PG8_WAIT_L(0); PG8_BAR; PG8_MMA(0, 0, At, B0); PG8_MMA(0, 1, At, B1); PG8_BAR; PG8_SCHED;
;             PG8_LDA(At, 0, 1); PG8_STAGE(PG8_SB(0, 0), b2, voffB); PG8_STAGE(PG8_SB(0, 1), b2 + hstepB, voffB); PG8_STAGE(PG8_SA(0, 0), a2, voffA);
;             PG8_WAIT_V(8); PG8_WAIT_L(0); PG8_BAR; PG8_MMA(1, 0, At, B0); PG8_MMA(1, 1, At, B1); PG8_BAR; PG8_SCHED;
.LBB0_298:
	s_ashr_i32 s37, s36, 31
	s_xor_b64 s[40:41], s[4:5], -1
	s_lshl_b64 s[38:39], s[36:37], 20
	v_readlane_b32 s42, v253, 52
	v_readlane_b32 s43, v253, 53
	s_add_u32 s38, s42, s38
	s_addc_u32 s39, s43, s39
	s_and_b64 s[42:43], s[4:5], exec
	s_cselect_b32 s31, s39, s47
	s_cselect_b32 s37, s38, s46
	s_ashr_i32 s35, s34, 31
	s_lshl_b64 s[42:43], s[34:35], 20
	s_add_u32 s42, s7, s42
	s_addc_u32 s43, s14, s43
	s_and_b64 s[4:5], s[4:5], exec
	s_cselect_b32 s4, s43, s49
	s_cselect_b32 s5, s42, s48
	s_add_u32 s50, s46, 0x80
	s_addc_u32 s51, s47, 0
	s_add_u32 s35, s48, 0x100
	v_lshl_add_u64 v[156:157], s[50:51], 0, v[152:153]
	v_lshl_add_u64 v[158:159], s[50:51], 0, v[154:155]
	s_addc_u32 s45, s49, 0
	s_mov_b32 s76, -2
	s_mov_b64 s[48:49], 0
	s_add_u32 s17, s46, s48
	s_addc_u32 s27, s47, s49
	s_add_u32 s17, s17, 0x100
	s_addc_u32 s27, s27, 0
	s_add_u32 s77, s35, s48
	s_addc_u32 s78, s45, s49
	s_add_i32 s80, 0, 0x10000
	s_cmpk_eq_i32 s48, 0xf00
	s_cselect_b32 s51, s31, s27
	s_cselect_b32 s50, s37, s17
	v_add_u32_e32 v141, s80, v135
	s_cselect_b32 s79, s4, s78
	s_cselect_b32 s78, s5, s77
	s_add_i32 s17, 0, 0x14000
	ds_read_b128 v[160:163], v141
	ds_read_b128 v[164:167], v141 offset:1024
	ds_read_b128 v[168:171], v141 offset:2048
	ds_read_b128 v[172:175], v141 offset:3072
	v_add_u32_e32 v141, s17, v135
	ds_read_b128 v[180:183], v141
	ds_read_b128 v[184:187], v141 offset:1024
	ds_read_b128 v[188:191], v141 offset:2048
	ds_read_b128 v[192:195], v141 offset:3072
	v_lshl_add_u64 v[228:229], v[158:159], 0, s[48:49]
	s_add_i32 m0, s16, 0xc000
	ds_read_b128 v[196:199], v139
	ds_read_b128 v[200:203], v139 offset:1024
	ds_read_b128 v[204:207], v139 offset:2048
	ds_read_b128 v[208:211], v139 offset:3072
	ds_read_b128 v[212:215], v139 offset:4096
	ds_read_b128 v[216:219], v139 offset:5120
	ds_read_b128 v[220:223], v139 offset:6144
	ds_read_b128 v[224:227], v139 offset:7168
	global_load_lds_dwordx4 v[228:229], off
	v_lshl_add_u64 v[228:229], v[156:157], 0, s[48:49]
	s_add_i32 m0, s16, 0xe000
	s_nop 0
	global_load_lds_dwordx4 v[228:229], off
	v_readlane_b32 s101, v252, 58
	s_nop 3
	s_bitcmp1_b32 s101, 0
	s_cbranch_scc0 .Lvw_299_0
	s_waitcnt vmcnt(8)
.Lvw_299_0:
	s_waitcnt lgkmcnt(0)
	s_barrier
	s_setprio 0
	s_waitcnt lgkmcnt(0)
	v_mfma_f32_16x16x32_bf16 v[124:127], v[160:163], v[196:199], 0
	v_mfma_f32_16x16x32_bf16 v[120:123], v[168:171], v[196:199], 0
	v_mfma_f32_16x16x32_bf16 v[116:119], v[160:163], v[204:207], 0
	v_mfma_f32_16x16x32_bf16 v[112:115], v[168:171], v[204:207], 0
	v_mfma_f32_16x16x32_bf16 v[100:103], v[160:163], v[212:215], 0
	v_mfma_f32_16x16x32_bf16 v[96:99], v[168:171], v[212:215], 0
	v_mfma_f32_16x16x32_bf16 v[84:87], v[160:163], v[220:223], 0
	v_mfma_f32_16x16x32_bf16 v[80:83], v[168:171], v[220:223], 0
	v_mfma_f32_16x16x32_bf16 v[124:127], v[164:167], v[200:203], v[124:127]
	v_mfma_f32_16x16x32_bf16 v[120:123], v[172:175], v[200:203], v[120:123]
	v_mfma_f32_16x16x32_bf16 v[116:119], v[164:167], v[208:211], v[116:119]
	v_mfma_f32_16x16x32_bf16 v[112:115], v[172:175], v[208:211], v[112:115]
	v_mfma_f32_16x16x32_bf16 v[100:103], v[164:167], v[216:219], v[100:103]
	v_mfma_f32_16x16x32_bf16 v[96:99], v[172:175], v[216:219], v[96:99]
	v_mfma_f32_16x16x32_bf16 v[84:87], v[164:167], v[224:227], v[84:87]
	v_mfma_f32_16x16x32_bf16 v[80:83], v[172:175], v[224:227], v[80:83]
	v_mfma_f32_16x16x32_bf16 v[108:111], v[180:183], v[196:199], 0
	v_mfma_f32_16x16x32_bf16 v[104:107], v[188:191], v[196:199], 0
	v_mfma_f32_16x16x32_bf16 v[92:95], v[180:183], v[204:207], 0
	v_mfma_f32_16x16x32_bf16 v[88:91], v[188:191], v[204:207], 0
	v_mfma_f32_16x16x32_bf16 v[76:79], v[180:183], v[212:215], 0
	v_mfma_f32_16x16x32_bf16 v[72:75], v[188:191], v[212:215], 0
	v_mfma_f32_16x16x32_bf16 v[68:71], v[180:183], v[220:223], 0
	v_mfma_f32_16x16x32_bf16 v[64:67], v[188:191], v[220:223], 0
	v_mfma_f32_16x16x32_bf16 v[108:111], v[184:187], v[200:203], v[108:111]
	v_mfma_f32_16x16x32_bf16 v[104:107], v[192:195], v[200:203], v[104:107]
	v_mfma_f32_16x16x32_bf16 v[92:95], v[184:187], v[208:211], v[92:95]
	v_mfma_f32_16x16x32_bf16 v[88:91], v[192:195], v[208:211], v[88:91]
	v_mfma_f32_16x16x32_bf16 v[76:79], v[184:187], v[216:219], v[76:79]
	v_mfma_f32_16x16x32_bf16 v[72:75], v[192:195], v[216:219], v[72:75]
	v_mfma_f32_16x16x32_bf16 v[68:71], v[184:187], v[224:227], v[68:71]
	v_mfma_f32_16x16x32_bf16 v[64:67], v[192:195], v[224:227], v[64:67]
	s_waitcnt vmcnt(8)
	s_barrier
	s_add_i32 s27, s80, s3
	v_lshl_add_u64 v[228:229], s[78:79], 0, v[176:177]
	s_mov_b32 m0, s27
	ds_read_b128 v[196:199], v139 offset:16384
	ds_read_b128 v[200:203], v139 offset:17408
	ds_read_b128 v[204:207], v139 offset:18432
	ds_read_b128 v[208:211], v139 offset:19456
	ds_read_b128 v[212:215], v139 offset:20480
	ds_read_b128 v[216:219], v139 offset:21504
	ds_read_b128 v[220:223], v139 offset:22528
	ds_read_b128 v[224:227], v139 offset:23552
	global_load_lds_dwordx4 v[228:229], off
	s_add_i32 m0, s27, 0x2000
	v_lshl_add_u64 v[230:231], s[78:79], 0, v[128:129]
	s_add_u32 s78, s78, s10
	s_addc_u32 s79, s79, s11
	s_add_i32 s17, s17, s3
	global_load_lds_dwordx4 v[230:231], off
	v_lshl_add_u64 v[232:233], s[78:79], 0, v[176:177]
	s_mov_b32 m0, s17
	v_lshl_add_u64 v[234:235], s[78:79], 0, v[128:129]
	global_load_lds_dwordx4 v[232:233], off
	s_add_i32 m0, s17, 0x2000
	v_lshl_add_u64 v[236:237], s[50:51], 0, v[132:133]
	global_load_lds_dwordx4 v[234:235], off
	s_mov_b32 m0, s16
	v_lshl_add_u64 v[246:247], s[50:51], 0, v[130:131]
	global_load_lds_dwordx4 v[236:237], off
	s_mov_b32 m0, s15
	s_nop 0
	global_load_lds_dwordx4 v[246:247], off
	s_bitcmp1_b32 s101, 0
	s_cbranch_scc0 .Lvw_299_1
	s_waitcnt vmcnt(8)
; #define PG8_STAGE(bufoff, gbase, voff) do { _Pragma("unroll") for (int _i = 0; _i < 2; ++_i) \
;         __builtin_amdgcn_global_load_lds((const unsigned*)((const char*)(gbase) + (voff)[_i]), (LAS unsigned*)(lds + (bufoff) + ldsw + _i * 8192), 16, 0, 0); } while (0)
; #define PG8_LDA(dst, b, h) do { _Pragma("unroll") for (int m = 0; m < 4; ++m) _Pragma("unroll") for (int k = 0; k < 2; ++k) dst[m][k] = *(const LAS bf16x8*)(lds + PG8_SA(b, h) + aoff + m * 2048 + k * 1024); } while (0)
; #define PG8_LDB(dst, b, h) do { _Pragma("unroll") for (int n = 0; n < 2; ++n) _Pragma("unroll") for (int k = 0; k < 2; ++k) dst[n][k] = *(const LAS bf16x8*)(lds + PG8_SB(b, h) + boff + n * 2048 + k * 1024); } while (0)
; #define PG8_MMA(ai, bj, At, Bt) do { __builtin_amdgcn_s_setprio(1); _Pragma("unroll") for (int m = 0; m < 4; ++m) _Pragma("unroll") for (int n = 0; n < 2; ++n) _Pragma("unroll") for (int k = 0; k < 2; ++k) \
;         acc[ai][bj][m][n] = __builtin_amdgcn_mfma_f32_16x16x32_bf16(Bt[n][k], At[m][k], acc[ai][bj][m][n], 0, 0, 0); __builtin_amdgcn_s_setprio(0); } while (0)
; #define PG8_WAIT_V(n) asm volatile("s_waitcnt vmcnt(" #n ")" ::: "memory")
; #define PG8_WAIT_L(n) asm volatile("s_waitcnt lgkmcnt(" #n ")" ::: "memory")
; #define PG8_BAR __builtin_amdgcn_s_barrier()
; #define PG8_SCHED __builtin_amdgcn_sched_barrier(0)
; template <class Epi, class Sched, bool ALIGN_EPI>
; __device__ __forceinline__ void gemm_phase(LAS unsigned char* lds, const int wid, const int lda_, const int ldb_, const int K_, const Sched& S, const Epi& E) {
;     ...
;             PG8_LDB(B0, 0, 0); PG8_LDB(B1, 0, 1); PG8_SCHED; PG8_LDA(At, 0, 0); PG8_STAGE(PG8_SA(1, 1), a1 + hstepA, voffA);
;             PG8_WAIT_V(8); PG8_WAIT_L(0); PG8_BAR; PG8_MMA(0, 0, At, B0); PG8_MMA(0, 1, At, B1); PG8_BAR; PG8_SCHED;
;             PG8_LDA(At, 0, 1); PG8_STAGE(PG8_SB(0, 0), b2, voffB); PG8_STAGE(PG8_SB(0, 1), b2 + hstepB, voffB); PG8_STAGE(PG8_SA(0, 0), a2, voffA);
;             PG8_WAIT_V(8); PG8_WAIT_L(0); PG8_BAR; PG8_MMA(1, 0, At, B0); PG8_MMA(1, 1, At, B1); PG8_BAR; PG8_SCHED;
.Lvw_299_1:
	s_waitcnt lgkmcnt(0)
	s_barrier
	s_waitcnt lgkmcnt(0)
	v_mfma_f32_16x16x32_bf16 v[60:63], v[160:163], v[196:199], 0
	v_mfma_f32_16x16x32_bf16 v[56:59], v[168:171], v[196:199], 0
	v_mfma_f32_16x16x32_bf16 v[52:55], v[160:163], v[204:207], 0
	v_mfma_f32_16x16x32_bf16 v[48:51], v[168:171], v[204:207], 0
	v_mfma_f32_16x16x32_bf16 v[36:39], v[160:163], v[212:215], 0
	v_mfma_f32_16x16x32_bf16 v[32:35], v[168:171], v[212:215], 0
	v_mfma_f32_16x16x32_bf16 v[20:23], v[160:163], v[220:223], 0
	v_mfma_f32_16x16x32_bf16 v[16:19], v[168:171], v[220:223], 0
	v_mfma_f32_16x16x32_bf16 v[60:63], v[164:167], v[200:203], v[60:63]
	v_mfma_f32_16x16x32_bf16 v[56:59], v[172:175], v[200:203], v[56:59]
	v_mfma_f32_16x16x32_bf16 v[52:55], v[164:167], v[208:211], v[52:55]
	v_mfma_f32_16x16x32_bf16 v[48:51], v[172:175], v[208:211], v[48:51]
	v_mfma_f32_16x16x32_bf16 v[36:39], v[164:167], v[216:219], v[36:39]
	v_mfma_f32_16x16x32_bf16 v[32:35], v[172:175], v[216:219], v[32:35]
	v_mfma_f32_16x16x32_bf16 v[20:23], v[164:167], v[224:227], v[20:23]
	v_mfma_f32_16x16x32_bf16 v[16:19], v[172:175], v[224:227], v[16:19]
	v_mfma_f32_16x16x32_bf16 v[44:47], v[180:183], v[196:199], 0
	v_mfma_f32_16x16x32_bf16 v[40:43], v[188:191], v[196:199], 0
	v_mfma_f32_16x16x32_bf16 v[28:31], v[180:183], v[204:207], 0
	v_mfma_f32_16x16x32_bf16 v[24:27], v[188:191], v[204:207], 0
	v_mfma_f32_16x16x32_bf16 v[12:15], v[180:183], v[212:215], 0
	v_mfma_f32_16x16x32_bf16 v[8:11], v[188:191], v[212:215], 0
	v_mfma_f32_16x16x32_bf16 v[4:7], v[180:183], v[220:223], 0
	v_mfma_f32_16x16x32_bf16 v[0:3], v[188:191], v[220:223], 0
	v_mfma_f32_16x16x32_bf16 v[44:47], v[184:187], v[200:203], v[44:47]
	v_mfma_f32_16x16x32_bf16 v[40:43], v[192:195], v[200:203], v[40:43]
	v_mfma_f32_16x16x32_bf16 v[28:31], v[184:187], v[208:211], v[28:31]
	v_mfma_f32_16x16x32_bf16 v[24:27], v[192:195], v[208:211], v[24:27]
	v_mfma_f32_16x16x32_bf16 v[12:15], v[184:187], v[216:219], v[12:15]
	v_mfma_f32_16x16x32_bf16 v[8:11], v[192:195], v[216:219], v[8:11]
	v_mfma_f32_16x16x32_bf16 v[4:7], v[184:187], v[224:227], v[4:7]
	v_mfma_f32_16x16x32_bf16 v[0:3], v[192:195], v[224:227], v[0:3]
	s_waitcnt vmcnt(8)
	s_barrier
	s_branch .Lgemm_join_299
.LBB0_299:
	s_add_u32 s17, s46, s48
	s_addc_u32 s27, s47, s49
	s_add_u32 s17, s17, 0x100
	s_addc_u32 s27, s27, 0
	s_add_u32 s77, s35, s48
	s_addc_u32 s78, s45, s49
	s_add_i32 s80, 0, 0x10000
	s_cmpk_eq_i32 s48, 0xf00
	s_cselect_b32 s51, s31, s27
	s_cselect_b32 s50, s37, s17
	v_add_u32_e32 v141, s80, v135
	s_cselect_b32 s79, s4, s78
	s_cselect_b32 s78, s5, s77
	s_add_i32 s17, 0, 0x14000
	ds_read_b128 v[160:163], v141
	ds_read_b128 v[164:167], v141 offset:1024
	ds_read_b128 v[168:171], v141 offset:2048
	ds_read_b128 v[172:175], v141 offset:3072
	v_add_u32_e32 v141, s17, v135
	ds_read_b128 v[180:183], v141
	ds_read_b128 v[184:187], v141 offset:1024
	ds_read_b128 v[188:191], v141 offset:2048
	ds_read_b128 v[192:195], v141 offset:3072
	v_lshl_add_u64 v[228:229], v[158:159], 0, s[48:49]
	s_add_i32 m0, s16, 0xc000
	ds_read_b128 v[196:199], v139
	ds_read_b128 v[200:203], v139 offset:1024
	ds_read_b128 v[204:207], v139 offset:2048
	ds_read_b128 v[208:211], v139 offset:3072
	ds_read_b128 v[212:215], v139 offset:4096
	ds_read_b128 v[216:219], v139 offset:5120
	ds_read_b128 v[220:223], v139 offset:6144
	ds_read_b128 v[224:227], v139 offset:7168
	global_load_lds_dwordx4 v[228:229], off
	v_lshl_add_u64 v[228:229], v[156:157], 0, s[48:49]
	s_add_i32 m0, s16, 0xe000
	s_nop 0
	global_load_lds_dwordx4 v[228:229], off
	s_bitcmp1_b32 s101, 0
	s_cbranch_scc0 .Lvw_299_2
	s_waitcnt vmcnt(8)
.Lvw_299_2:
	s_waitcnt lgkmcnt(0)
	s_barrier
	s_waitcnt lgkmcnt(0)
	v_mfma_f32_16x16x32_bf16 v[124:127], v[160:163], v[196:199], v[124:127]
	v_mfma_f32_16x16x32_bf16 v[120:123], v[168:171], v[196:199], v[120:123]
	v_mfma_f32_16x16x32_bf16 v[116:119], v[160:163], v[204:207], v[116:119]
	v_mfma_f32_16x16x32_bf16 v[112:115], v[168:171], v[204:207], v[112:115]
	v_mfma_f32_16x16x32_bf16 v[100:103], v[160:163], v[212:215], v[100:103]
	v_mfma_f32_16x16x32_bf16 v[96:99], v[168:171], v[212:215], v[96:99]
	v_mfma_f32_16x16x32_bf16 v[84:87], v[160:163], v[220:223], v[84:87]
	v_mfma_f32_16x16x32_bf16 v[80:83], v[168:171], v[220:223], v[80:83]
	v_mfma_f32_16x16x32_bf16 v[124:127], v[164:167], v[200:203], v[124:127]
	v_mfma_f32_16x16x32_bf16 v[120:123], v[172:175], v[200:203], v[120:123]
	v_mfma_f32_16x16x32_bf16 v[116:119], v[164:167], v[208:211], v[116:119]
	v_mfma_f32_16x16x32_bf16 v[112:115], v[172:175], v[208:211], v[112:115]
	v_mfma_f32_16x16x32_bf16 v[100:103], v[164:167], v[216:219], v[100:103]
	v_mfma_f32_16x16x32_bf16 v[96:99], v[172:175], v[216:219], v[96:99]
	v_mfma_f32_16x16x32_bf16 v[84:87], v[164:167], v[224:227], v[84:87]
	v_mfma_f32_16x16x32_bf16 v[80:83], v[172:175], v[224:227], v[80:83]
	v_mfma_f32_16x16x32_bf16 v[108:111], v[180:183], v[196:199], v[108:111]
	v_mfma_f32_16x16x32_bf16 v[104:107], v[188:191], v[196:199], v[104:107]
	v_mfma_f32_16x16x32_bf16 v[92:95], v[180:183], v[204:207], v[92:95]
	v_mfma_f32_16x16x32_bf16 v[88:91], v[188:191], v[204:207], v[88:91]
	v_mfma_f32_16x16x32_bf16 v[76:79], v[180:183], v[212:215], v[76:79]
	v_mfma_f32_16x16x32_bf16 v[72:75], v[188:191], v[212:215], v[72:75]
	v_mfma_f32_16x16x32_bf16 v[68:71], v[180:183], v[220:223], v[68:71]
	v_mfma_f32_16x16x32_bf16 v[64:67], v[188:191], v[220:223], v[64:67]
	v_mfma_f32_16x16x32_bf16 v[108:111], v[184:187], v[200:203], v[108:111]
	v_mfma_f32_16x16x32_bf16 v[104:107], v[192:195], v[200:203], v[104:107]
	v_mfma_f32_16x16x32_bf16 v[92:95], v[184:187], v[208:211], v[92:95]
	v_mfma_f32_16x16x32_bf16 v[88:91], v[192:195], v[208:211], v[88:91]
	v_mfma_f32_16x16x32_bf16 v[76:79], v[184:187], v[216:219], v[76:79]
	v_mfma_f32_16x16x32_bf16 v[72:75], v[192:195], v[216:219], v[72:75]
	v_mfma_f32_16x16x32_bf16 v[68:71], v[184:187], v[224:227], v[68:71]
	v_mfma_f32_16x16x32_bf16 v[64:67], v[192:195], v[224:227], v[64:67]
	s_waitcnt vmcnt(8)
	s_barrier
; #define PG8_STAGE(bufoff, gbase, voff) do { _Pragma("unroll") for (int _i = 0; _i < 2; ++_i) \
;         __builtin_amdgcn_global_load_lds((const unsigned*)((const char*)(gbase) + (voff)[_i]), (LAS unsigned*)(lds + (bufoff) + ldsw + _i * 8192), 16, 0, 0); } while (0)
; #define PG8_LDA(dst, b, h) do { _Pragma("unroll") for (int m = 0; m < 4; ++m) _Pragma("unroll") for (int k = 0; k < 2; ++k) dst[m][k] = *(const LAS bf16x8*)(lds + PG8_SA(b, h) + aoff + m * 2048 + k * 1024); } while (0)
; #define PG8_LDB(dst, b, h) do { _Pragma("unroll") for (int n = 0; n < 2; ++n) _Pragma("unroll") for (int k = 0; k < 2; ++k) dst[n][k] = *(const LAS bf16x8*)(lds + PG8_SB(b, h) + boff + n * 2048 + k * 1024); } while (0)
; #define PG8_MMA(ai, bj, At, Bt) do { __builtin_amdgcn_s_setprio(1); _Pragma("unroll") for (int m = 0; m < 4; ++m) _Pragma("unroll") for (int n = 0; n < 2; ++n) _Pragma("unroll") for (int k = 0; k < 2; ++k) \
;         acc[ai][bj][m][n] = __builtin_amdgcn_mfma_f32_16x16x32_bf16(Bt[n][k], At[m][k], acc[ai][bj][m][n], 0, 0, 0); __builtin_amdgcn_s_setprio(0); } while (0)
; #define PG8_WAIT_V(n) asm volatile("s_waitcnt vmcnt(" #n ")" ::: "memory")
; #define PG8_WAIT_L(n) asm volatile("s_waitcnt lgkmcnt(" #n ")" ::: "memory")
; #define PG8_BAR __builtin_amdgcn_s_barrier()
; #define PG8_SCHED __builtin_amdgcn_sched_barrier(0)
; template <class Epi, class Sched, bool ALIGN_EPI>
; __device__ __forceinline__ void gemm_phase(LAS unsigned char* lds, const int wid, const int lda_, const int ldb_, const int K_, const Sched& S, const Epi& E) {
;     ...
;             PG8_LDA(At, 0, 1); PG8_STAGE(PG8_SB(0, 0), b2, voffB); PG8_STAGE(PG8_SB(0, 1), b2 + hstepB, voffB); PG8_STAGE(PG8_SA(0, 0), a2, voffA);
;             PG8_WAIT_V(8); PG8_WAIT_L(0); PG8_BAR; PG8_MMA(1, 0, At, B0); PG8_MMA(1, 1, At, B1); PG8_BAR; PG8_SCHED;
;             PG8_LDB(B0, 1, 0); PG8_LDB(B1, 1, 1); PG8_SCHED; PG8_LDA(At, 1, 0); PG8_STAGE(PG8_SA(0, 1), a2 + hstepA, voffA);
;             PG8_WAIT_V(8); PG8_WAIT_L(0); PG8_BAR; PG8_MMA(0, 0, At, B0); PG8_MMA(0, 1, At, B1); PG8_BAR; PG8_SCHED;
	s_add_i32 s27, s80, s3
	v_lshl_add_u64 v[228:229], s[78:79], 0, v[176:177]
	s_mov_b32 m0, s27
	ds_read_b128 v[196:199], v139 offset:16384
	ds_read_b128 v[200:203], v139 offset:17408
	ds_read_b128 v[204:207], v139 offset:18432
	ds_read_b128 v[208:211], v139 offset:19456
	ds_read_b128 v[212:215], v139 offset:20480
	ds_read_b128 v[216:219], v139 offset:21504
	ds_read_b128 v[220:223], v139 offset:22528
	ds_read_b128 v[224:227], v139 offset:23552
	global_load_lds_dwordx4 v[228:229], off
	s_add_i32 m0, s27, 0x2000
	v_lshl_add_u64 v[230:231], s[78:79], 0, v[128:129]
	s_add_u32 s78, s78, s10
	s_addc_u32 s79, s79, s11
	s_add_i32 s17, s17, s3
	global_load_lds_dwordx4 v[230:231], off
	v_lshl_add_u64 v[232:233], s[78:79], 0, v[176:177]
	s_mov_b32 m0, s17
	v_lshl_add_u64 v[234:235], s[78:79], 0, v[128:129]
	global_load_lds_dwordx4 v[232:233], off
	s_add_i32 m0, s17, 0x2000
	v_lshl_add_u64 v[236:237], s[50:51], 0, v[132:133]
	global_load_lds_dwordx4 v[234:235], off
	s_mov_b32 m0, s16
	v_lshl_add_u64 v[246:247], s[50:51], 0, v[130:131]
	global_load_lds_dwordx4 v[236:237], off
	s_mov_b32 m0, s15
	s_nop 0
	global_load_lds_dwordx4 v[246:247], off
	s_bitcmp1_b32 s101, 0
	s_cbranch_scc0 .Lvw_299_3
	s_waitcnt vmcnt(8)
.Lvw_299_3:
	s_waitcnt lgkmcnt(0)
	s_barrier
	s_waitcnt lgkmcnt(0)
	v_mfma_f32_16x16x32_bf16 v[60:63], v[160:163], v[196:199], v[60:63]
	v_mfma_f32_16x16x32_bf16 v[56:59], v[168:171], v[196:199], v[56:59]
	v_mfma_f32_16x16x32_bf16 v[52:55], v[160:163], v[204:207], v[52:55]
	v_mfma_f32_16x16x32_bf16 v[48:51], v[168:171], v[204:207], v[48:51]
	v_mfma_f32_16x16x32_bf16 v[36:39], v[160:163], v[212:215], v[36:39]
	v_mfma_f32_16x16x32_bf16 v[32:35], v[168:171], v[212:215], v[32:35]
	v_mfma_f32_16x16x32_bf16 v[20:23], v[160:163], v[220:223], v[20:23]
	v_mfma_f32_16x16x32_bf16 v[16:19], v[168:171], v[220:223], v[16:19]
	v_mfma_f32_16x16x32_bf16 v[60:63], v[164:167], v[200:203], v[60:63]
	v_mfma_f32_16x16x32_bf16 v[56:59], v[172:175], v[200:203], v[56:59]
	v_mfma_f32_16x16x32_bf16 v[52:55], v[164:167], v[208:211], v[52:55]
	v_mfma_f32_16x16x32_bf16 v[48:51], v[172:175], v[208:211], v[48:51]
	v_mfma_f32_16x16x32_bf16 v[36:39], v[164:167], v[216:219], v[36:39]
	v_mfma_f32_16x16x32_bf16 v[32:35], v[172:175], v[216:219], v[32:35]
	v_mfma_f32_16x16x32_bf16 v[20:23], v[164:167], v[224:227], v[20:23]
	v_mfma_f32_16x16x32_bf16 v[16:19], v[172:175], v[224:227], v[16:19]
	v_mfma_f32_16x16x32_bf16 v[44:47], v[180:183], v[196:199], v[44:47]
	v_mfma_f32_16x16x32_bf16 v[40:43], v[188:191], v[196:199], v[40:43]
	v_mfma_f32_16x16x32_bf16 v[28:31], v[180:183], v[204:207], v[28:31]
	v_mfma_f32_16x16x32_bf16 v[24:27], v[188:191], v[204:207], v[24:27]
	v_mfma_f32_16x16x32_bf16 v[12:15], v[180:183], v[212:215], v[12:15]
	v_mfma_f32_16x16x32_bf16 v[8:11], v[188:191], v[212:215], v[8:11]
	v_mfma_f32_16x16x32_bf16 v[4:7], v[180:183], v[220:223], v[4:7]
	v_mfma_f32_16x16x32_bf16 v[0:3], v[188:191], v[220:223], v[0:3]
	v_mfma_f32_16x16x32_bf16 v[44:47], v[184:187], v[200:203], v[44:47]
	v_mfma_f32_16x16x32_bf16 v[40:43], v[192:195], v[200:203], v[40:43]
	v_mfma_f32_16x16x32_bf16 v[28:31], v[184:187], v[208:211], v[28:31]
	v_mfma_f32_16x16x32_bf16 v[24:27], v[192:195], v[208:211], v[24:27]
	v_mfma_f32_16x16x32_bf16 v[12:15], v[184:187], v[216:219], v[12:15]
	v_mfma_f32_16x16x32_bf16 v[8:11], v[192:195], v[216:219], v[8:11]
	v_mfma_f32_16x16x32_bf16 v[4:7], v[184:187], v[224:227], v[4:7]
	v_mfma_f32_16x16x32_bf16 v[0:3], v[192:195], v[224:227], v[0:3]
	s_waitcnt vmcnt(8)
	s_barrier
.Lgemm_join_299:
	s_add_i32 s17, 0, 0x18000
	v_add_u32_e32 v141, s17, v135
	s_add_i32 s27, 0, 0x1c000
	ds_read_b128 v[160:163], v141
	ds_read_b128 v[164:167], v141 offset:1024
	ds_read_b128 v[168:171], v141 offset:2048
	ds_read_b128 v[172:175], v141 offset:3072
	v_add_u32_e32 v141, s27, v135
	ds_read_b128 v[180:183], v141
	ds_read_b128 v[184:187], v141 offset:1024
	ds_read_b128 v[188:191], v141 offset:2048
	ds_read_b128 v[192:195], v141 offset:3072
	s_add_u32 s50, s50, s0
	s_addc_u32 s51, s51, s1
	s_mov_b32 m0, s26
	v_lshl_add_u64 v[248:249], s[50:51], 0, v[132:133]
	ds_read_b128 v[196:199], v139 offset:32768
	ds_read_b128 v[200:203], v139 offset:33792
	ds_read_b128 v[204:207], v139 offset:34816
	ds_read_b128 v[208:211], v139 offset:35840
	ds_read_b128 v[212:215], v139 offset:36864
	ds_read_b128 v[216:219], v139 offset:37888
	ds_read_b128 v[220:223], v139 offset:38912
	ds_read_b128 v[224:227], v139 offset:39936
	global_load_lds_dwordx4 v[248:249], off
	v_lshl_add_u64 v[248:249], s[50:51], 0, v[130:131]
	s_mov_b32 m0, s72
	s_nop 0
	global_load_lds_dwordx4 v[248:249], off
	s_bitcmp1_b32 s101, 0
	s_cbranch_scc0 .Lvw_299_4
	s_waitcnt vmcnt(8)
; #define PG8_STAGE(bufoff, gbase, voff) do { _Pragma("unroll") for (int _i = 0; _i < 2; ++_i) \
;         __builtin_amdgcn_global_load_lds((const unsigned*)((const char*)(gbase) + (voff)[_i]), (LAS unsigned*)(lds + (bufoff) + ldsw + _i * 8192), 16, 0, 0); } while (0)
; #define PG8_LDA(dst, b, h) do { _Pragma("unroll") for (int m = 0; m < 4; ++m) _Pragma("unroll") for (int k = 0; k < 2; ++k) dst[m][k] = *(const LAS bf16x8*)(lds + PG8_SA(b, h) + aoff + m * 2048 + k * 1024); } while (0)
; #define PG8_MMA(ai, bj, At, Bt) do { __builtin_amdgcn_s_setprio(1); _Pragma("unroll") for (int m = 0; m < 4; ++m) _Pragma("unroll") for (int n = 0; n < 2; ++n) _Pragma("unroll") for (int k = 0; k < 2; ++k) \
;         acc[ai][bj][m][n] = __builtin_amdgcn_mfma_f32_16x16x32_bf16(Bt[n][k], At[m][k], acc[ai][bj][m][n], 0, 0, 0); __builtin_amdgcn_s_setprio(0); } while (0)
; #define PG8_WAIT_V(n) asm volatile("s_waitcnt vmcnt(" #n ")" ::: "memory")
; #define PG8_WAIT_L(n) asm volatile("s_waitcnt lgkmcnt(" #n ")" ::: "memory")
; #define PG8_BAR __builtin_amdgcn_s_barrier()
; #define PG8_SCHED __builtin_amdgcn_sched_barrier(0)
; template <class Epi, class Sched, bool ALIGN_EPI>
; __device__ __forceinline__ void gemm_phase(LAS unsigned char* lds, const int wid, const int lda_, const int ldb_, const int K_, const Sched& S, const Epi& E) {
;     ...
;             PG8_WAIT_V(8); PG8_WAIT_L(0); PG8_BAR; PG8_MMA(0, 0, At, B0); PG8_MMA(0, 1, At, B1); PG8_BAR; PG8_SCHED;
;             PG8_LDA(At, 1, 1); PG8_STAGE(PG8_SB(1, 0), b3, voffB); PG8_STAGE(PG8_SB(1, 1), b3 + hstepB, voffB); PG8_STAGE(PG8_SA(1, 0), a3, voffA);
;             PG8_WAIT_V(8); PG8_WAIT_L(0); PG8_BAR; PG8_MMA(1, 0, At, B0); PG8_MMA(1, 1, At, B1); PG8_BAR; PG8_SCHED;
;         }
;         if constexpr (ALIGN_EPI) { if (wr == 0) PG8_BAR; }
;         E(acc, cur, S, wr, wc, fr, fq);
;     __device__ __forceinline__ void out(const pg8::Unit& u, char*& o, int& ldo, int& kind) const {
;         if (u.pn < 24) { o = (char*)ws + WS_XBCP + ((size_t)u.pm * 256 * XBC + (size_t)u.pn * 256) * 2; ldo = XBC; kind = 0; }
;         else if (u.pn < 40) { o = (char*)ws + WS_Z + ((size_t)u.pm * 256 * DI + (size_t)(u.pn - 24) * 256) * 2; ldo = DI; kind = 0; }
;         else { o = (char*)ws + WS_DT + (size_t)u.pm * 256 * 128 * 4; ldo = 128; kind = 1; } }
.Lvw_299_4:
	s_waitcnt lgkmcnt(0)
	s_barrier
	s_waitcnt lgkmcnt(0)
	v_mfma_f32_16x16x32_bf16 v[124:127], v[160:163], v[196:199], v[124:127]
	v_mfma_f32_16x16x32_bf16 v[120:123], v[168:171], v[196:199], v[120:123]
	v_mfma_f32_16x16x32_bf16 v[116:119], v[160:163], v[204:207], v[116:119]
	v_mfma_f32_16x16x32_bf16 v[112:115], v[168:171], v[204:207], v[112:115]
	v_mfma_f32_16x16x32_bf16 v[100:103], v[160:163], v[212:215], v[100:103]
	v_mfma_f32_16x16x32_bf16 v[96:99], v[168:171], v[212:215], v[96:99]
	v_mfma_f32_16x16x32_bf16 v[84:87], v[160:163], v[220:223], v[84:87]
	v_mfma_f32_16x16x32_bf16 v[80:83], v[168:171], v[220:223], v[80:83]
	v_mfma_f32_16x16x32_bf16 v[124:127], v[164:167], v[200:203], v[124:127]
	v_mfma_f32_16x16x32_bf16 v[120:123], v[172:175], v[200:203], v[120:123]
	v_mfma_f32_16x16x32_bf16 v[116:119], v[164:167], v[208:211], v[116:119]
	v_mfma_f32_16x16x32_bf16 v[112:115], v[172:175], v[208:211], v[112:115]
	v_mfma_f32_16x16x32_bf16 v[100:103], v[164:167], v[216:219], v[100:103]
	v_mfma_f32_16x16x32_bf16 v[96:99], v[172:175], v[216:219], v[96:99]
	v_mfma_f32_16x16x32_bf16 v[84:87], v[164:167], v[224:227], v[84:87]
	v_mfma_f32_16x16x32_bf16 v[80:83], v[172:175], v[224:227], v[80:83]
	v_mfma_f32_16x16x32_bf16 v[108:111], v[180:183], v[196:199], v[108:111]
	v_mfma_f32_16x16x32_bf16 v[104:107], v[188:191], v[196:199], v[104:107]
	v_mfma_f32_16x16x32_bf16 v[92:95], v[180:183], v[204:207], v[92:95]
	v_mfma_f32_16x16x32_bf16 v[88:91], v[188:191], v[204:207], v[88:91]
	v_mfma_f32_16x16x32_bf16 v[76:79], v[180:183], v[212:215], v[76:79]
	v_mfma_f32_16x16x32_bf16 v[72:75], v[188:191], v[212:215], v[72:75]
	v_mfma_f32_16x16x32_bf16 v[68:71], v[180:183], v[220:223], v[68:71]
	v_mfma_f32_16x16x32_bf16 v[64:67], v[188:191], v[220:223], v[64:67]
	v_mfma_f32_16x16x32_bf16 v[108:111], v[184:187], v[200:203], v[108:111]
	v_mfma_f32_16x16x32_bf16 v[104:107], v[192:195], v[200:203], v[104:107]
	v_mfma_f32_16x16x32_bf16 v[92:95], v[184:187], v[208:211], v[92:95]
	v_mfma_f32_16x16x32_bf16 v[88:91], v[192:195], v[208:211], v[88:91]
	v_mfma_f32_16x16x32_bf16 v[76:79], v[184:187], v[216:219], v[76:79]
	v_mfma_f32_16x16x32_bf16 v[72:75], v[192:195], v[216:219], v[72:75]
	v_mfma_f32_16x16x32_bf16 v[68:71], v[184:187], v[224:227], v[68:71]
	v_mfma_f32_16x16x32_bf16 v[64:67], v[192:195], v[224:227], v[64:67]
	s_waitcnt vmcnt(8)
	s_barrier
	s_add_i32 s17, s17, s3
	v_lshl_add_u64 v[228:229], v[228:229], 0, s[24:25]
	s_mov_b32 m0, s17
	ds_read_b128 v[196:199], v139 offset:49152
	ds_read_b128 v[200:203], v139 offset:50176
	ds_read_b128 v[204:207], v139 offset:51200
	ds_read_b128 v[208:211], v139 offset:52224
	ds_read_b128 v[212:215], v139 offset:53248
	ds_read_b128 v[216:219], v139 offset:54272
	ds_read_b128 v[220:223], v139 offset:55296
	ds_read_b128 v[224:227], v139 offset:56320
	global_load_lds_dwordx4 v[228:229], off
	v_lshl_add_u64 v[228:229], v[230:231], 0, s[24:25]
	s_add_i32 m0, s17, 0x2000
	s_add_i32 s17, s27, s3
	global_load_lds_dwordx4 v[228:229], off
	v_lshl_add_u64 v[228:229], v[232:233], 0, s[24:25]
	s_mov_b32 m0, s17
	s_nop 0
	global_load_lds_dwordx4 v[228:229], off
	v_lshl_add_u64 v[228:229], v[234:235], 0, s[24:25]
	s_add_i32 m0, s17, 0x2000
	s_nop 0
	global_load_lds_dwordx4 v[228:229], off
	v_lshl_add_u64 v[228:229], v[236:237], 0, s[24:25]
	s_mov_b32 m0, s73
	s_nop 0
	global_load_lds_dwordx4 v[228:229], off
	v_lshl_add_u64 v[228:229], v[246:247], 0, s[24:25]
	s_mov_b32 m0, s74
	s_nop 0
	global_load_lds_dwordx4 v[228:229], off
	s_bitcmp1_b32 s101, 0
	s_cbranch_scc0 .Lvw_299_5
	s_waitcnt vmcnt(8)
.Lvw_299_5:
	s_waitcnt lgkmcnt(0)
	s_barrier
	s_waitcnt lgkmcnt(0)
	v_mfma_f32_16x16x32_bf16 v[60:63], v[160:163], v[196:199], v[60:63]
	v_mfma_f32_16x16x32_bf16 v[56:59], v[168:171], v[196:199], v[56:59]
	v_mfma_f32_16x16x32_bf16 v[52:55], v[160:163], v[204:207], v[52:55]
	v_mfma_f32_16x16x32_bf16 v[48:51], v[168:171], v[204:207], v[48:51]
	v_mfma_f32_16x16x32_bf16 v[36:39], v[160:163], v[212:215], v[36:39]
	v_mfma_f32_16x16x32_bf16 v[32:35], v[168:171], v[212:215], v[32:35]
	v_mfma_f32_16x16x32_bf16 v[20:23], v[160:163], v[220:223], v[20:23]
	v_mfma_f32_16x16x32_bf16 v[16:19], v[168:171], v[220:223], v[16:19]
	v_mfma_f32_16x16x32_bf16 v[60:63], v[164:167], v[200:203], v[60:63]
	v_mfma_f32_16x16x32_bf16 v[56:59], v[172:175], v[200:203], v[56:59]
	v_mfma_f32_16x16x32_bf16 v[52:55], v[164:167], v[208:211], v[52:55]
	v_mfma_f32_16x16x32_bf16 v[48:51], v[172:175], v[208:211], v[48:51]
	v_mfma_f32_16x16x32_bf16 v[36:39], v[164:167], v[216:219], v[36:39]
	v_mfma_f32_16x16x32_bf16 v[32:35], v[172:175], v[216:219], v[32:35]
	v_mfma_f32_16x16x32_bf16 v[20:23], v[164:167], v[224:227], v[20:23]
	v_mfma_f32_16x16x32_bf16 v[16:19], v[172:175], v[224:227], v[16:19]
	v_mfma_f32_16x16x32_bf16 v[44:47], v[180:183], v[196:199], v[44:47]
	v_mfma_f32_16x16x32_bf16 v[40:43], v[188:191], v[196:199], v[40:43]
	v_mfma_f32_16x16x32_bf16 v[28:31], v[180:183], v[204:207], v[28:31]
	v_mfma_f32_16x16x32_bf16 v[24:27], v[188:191], v[204:207], v[24:27]
	v_mfma_f32_16x16x32_bf16 v[12:15], v[180:183], v[212:215], v[12:15]
	v_mfma_f32_16x16x32_bf16 v[8:11], v[188:191], v[212:215], v[8:11]
	v_mfma_f32_16x16x32_bf16 v[4:7], v[180:183], v[220:223], v[4:7]
	v_mfma_f32_16x16x32_bf16 v[0:3], v[188:191], v[220:223], v[0:3]
	v_mfma_f32_16x16x32_bf16 v[44:47], v[184:187], v[200:203], v[44:47]
	v_mfma_f32_16x16x32_bf16 v[40:43], v[192:195], v[200:203], v[40:43]
	v_mfma_f32_16x16x32_bf16 v[28:31], v[184:187], v[208:211], v[28:31]
	v_mfma_f32_16x16x32_bf16 v[24:27], v[192:195], v[208:211], v[24:27]
	v_mfma_f32_16x16x32_bf16 v[12:15], v[184:187], v[216:219], v[12:15]
	v_mfma_f32_16x16x32_bf16 v[8:11], v[192:195], v[216:219], v[8:11]
	v_mfma_f32_16x16x32_bf16 v[4:7], v[184:187], v[224:227], v[4:7]
	v_mfma_f32_16x16x32_bf16 v[0:3], v[192:195], v[224:227], v[0:3]
	s_waitcnt vmcnt(8)
	s_barrier
	s_add_i32 s76, s76, 2
	s_add_u32 s48, s48, 0x100
	s_addc_u32 s49, s49, 0
	s_cmp_gt_u32 s76, 29
	s_cbranch_scc0 .LBB0_299
	s_setprio 2
	s_sub_u32 s100, s30, 24
	s_cmp_lt_u32 s100, 16
	s_cselect_b32 s100, 1, 0
	s_ashr_i32 s45, s44, 31
	s_cmp_gt_i32 s30, 23
	s_mov_b64 s[48:49], -1
	s_cbranch_scc0 .LBB0_305
	s_cmp_gt_u32 s30, 39
	s_mov_b64 s[4:5], -1
	s_cbranch_scc0 .LBB0_303
	s_lshl_b64 s[4:5], s[44:45], 17
	v_readlane_b32 s46, v252, 60
	v_readlane_b32 s47, v252, 61
	s_add_u32 s46, s46, s4
	s_addc_u32 s47, s47, s5
	s_mov_b64 s[4:5], 0

; #define PG8_STAGE(bufoff, gbase, voff) do { _Pragma("unroll") for (int _i = 0; _i < 2; ++_i) \
;         __builtin_amdgcn_global_load_lds((const unsigned*)((const char*)(gbase) + (voff)[_i]), (LAS unsigned*)(lds + (bufoff) + ldsw + _i * 8192), 16, 0, 0); } while (0)
; #define PG8_LDA(dst, b, h) do { _Pragma("unroll") for (int m = 0; m < 4; ++m) _Pragma("unroll") for (int k = 0; k < 2; ++k) dst[m][k] = *(const LAS bf16x8*)(lds + PG8_SA(b, h) + aoff + m * 2048 + k * 1024); } while (0)
; #define PG8_LDB(dst, b, h) do { _Pragma("unroll") for (int n = 0; n < 2; ++n) _Pragma("unroll") for (int k = 0; k < 2; ++k) dst[n][k] = *(const LAS bf16x8*)(lds + PG8_SB(b, h) + boff + n * 2048 + k * 1024); } while (0)
; #define PG8_MMA(ai, bj, At, Bt) do { __builtin_amdgcn_s_setprio(1); _Pragma("unroll") for (int m = 0; m < 4; ++m) _Pragma("unroll") for (int n = 0; n < 2; ++n) _Pragma("unroll") for (int k = 0; k < 2; ++k) \
;         acc[ai][bj][m][n] = __builtin_amdgcn_mfma_f32_16x16x32_bf16(Bt[n][k], At[m][k], acc[ai][bj][m][n], 0, 0, 0); __builtin_amdgcn_s_setprio(0); } while (0)
; #define PG8_WAIT_V(n) asm volatile("s_waitcnt vmcnt(" #n ")" ::: "memory")
; #define PG8_WAIT_L(n) asm volatile("s_waitcnt lgkmcnt(" #n ")" ::: "memory")
; #define PG8_BAR __builtin_amdgcn_s_barrier()
; #define PG8_SCHED __builtin_amdgcn_sched_barrier(0)
; template <class Epi, class Sched, bool ALIGN_EPI>
; __device__ __forceinline__ void gemm_phase(LAS unsigned char* lds, const int wid, const int lda_, const int ldb_, const int K_, const Sched& S, const Epi& E) {
;     ...
;         const bool has_next = S.next(ui + 1, nxt);
;         const int nt = S.nt(cur);
;         const char* nA = has_next ? S.a(nxt) : cA; const char* nB = has_next ? S.b(nxt) : cB;
; #pragma unroll 1
;         for (int t = 0; t < nt; t += 2) {
;             const bool last = (t == nt - 2);
;             const char* a1 = cA + (size_t)(t + 1) * kstep;
;             const char* a2 = last ? nA : cA + (size_t)(t + 2) * kstep; const char* b2 = last ? nB : cB + (size_t)(t + 2) * kstep;
;             const char* a3 = a2 + kstep; const char* b3 = b2 + kstep;
;             PG8_LDB(B0, 0, 0); PG8_LDB(B1, 0, 1); PG8_SCHED; PG8_LDA(At, 0, 0); PG8_STAGE(PG8_SA(1, 1), a1 + hstepA, voffA);
;             PG8_WAIT_V(8); PG8_WAIT_L(0); PG8_BAR; PG8_MMA(0, 0, At, B0); PG8_MMA(0, 1, At, B1); PG8_BAR; PG8_SCHED;
.LBB0_670:
	s_xor_b64 s[44:45], s[4:5], -1
	s_cmp_gt_i32 s38, -1
	s_cselect_b64 s[50:51], -1, 0
	s_cmp_lt_i32 s38, 0
	s_cselect_b32 s35, 64, 16
	s_max_i32 s17, s75, 0
	s_ashr_i32 s43, s42, 31
	s_lshl_b32 s17, s17, 11
	s_lshl_b64 s[46:47], s[42:43], 21
	v_readlane_b32 s48, v252, 62
	v_readlane_b32 s49, v252, 63
	s_add_u32 s27, s48, s46
	s_addc_u32 s37, s49, s47
	s_add_u32 s46, s27, s17
	s_addc_u32 s47, s37, 0
	s_and_b64 s[48:49], s[4:5], exec
	s_cselect_b32 s37, s47, s95
	s_cselect_b32 s39, s46, s94
	s_ashr_i32 s41, s40, 31
	s_lshl_b64 s[48:49], s[40:41], 21
	s_add_u32 s27, s6, s48
	s_addc_u32 s41, s7, s49
	s_add_u32 s48, s27, s17
	s_addc_u32 s49, s41, 0
	s_and_b64 s[4:5], s[4:5], exec
	s_cselect_b32 s4, s49, s97
	s_cselect_b32 s5, s48, s96
	s_add_i32 s41, s35, -2
	s_add_u32 s94, s94, 0x80
	s_addc_u32 s95, s95, 0
	s_add_u32 s43, s96, 0x100
	s_mov_b32 s77, 0
	s_addc_u32 s76, s97, 0
	s_add_i32 s78, s77, 2
	s_add_u32 s17, s94, 0x80
	s_addc_u32 s27, s95, 0
	s_add_i32 s79, 0, 0x10000
	s_cmp_eq_u32 s41, s77
	s_cselect_b32 s97, s37, s27
	s_cselect_b32 s96, s39, s17
	v_add_u32_e32 v141, s79, v135
	s_cselect_b32 s81, s4, s76
	s_cselect_b32 s80, s5, s43
	s_add_i32 s17, 0, 0x14000
	ds_read_b128 v[156:159], v141
	ds_read_b128 v[160:163], v141 offset:1024
	ds_read_b128 v[164:167], v141 offset:2048
	ds_read_b128 v[168:171], v141 offset:3072
	v_add_u32_e32 v141, s17, v135
	ds_read_b128 v[172:175], v141
	ds_read_b128 v[180:183], v141 offset:1024
	ds_read_b128 v[184:187], v141 offset:2048
	ds_read_b128 v[188:191], v141 offset:3072
	v_lshl_add_u64 v[224:225], s[94:95], 0, v[152:153]
	s_add_i32 m0, s16, 0xc000
	ds_read_b128 v[192:195], v139
	ds_read_b128 v[196:199], v139 offset:1024
	ds_read_b128 v[200:203], v139 offset:2048
	ds_read_b128 v[204:207], v139 offset:3072
	ds_read_b128 v[208:211], v139 offset:4096
	ds_read_b128 v[212:215], v139 offset:5120
	ds_read_b128 v[216:219], v139 offset:6144
	ds_read_b128 v[220:223], v139 offset:7168
	global_load_lds_dwordx4 v[224:225], off
	v_lshl_add_u64 v[224:225], s[94:95], 0, v[154:155]
	s_add_i32 m0, s16, 0xe000
	s_nop 0
	global_load_lds_dwordx4 v[224:225], off
	v_readlane_b32 s101, v252, 58
	s_nop 3
	s_bitcmp1_b32 s101, 0
	s_cbranch_scc0 .Lvw_671_0
	s_waitcnt vmcnt(8)
.Lvw_671_0:
	s_waitcnt lgkmcnt(0)
	s_barrier
	s_setprio 0
	s_waitcnt lgkmcnt(0)
	v_mfma_f32_16x16x32_bf16 v[124:127], v[156:159], v[192:195], 0
	v_mfma_f32_16x16x32_bf16 v[120:123], v[164:167], v[192:195], 0
	v_mfma_f32_16x16x32_bf16 v[116:119], v[156:159], v[200:203], 0
	v_mfma_f32_16x16x32_bf16 v[112:115], v[164:167], v[200:203], 0
	v_mfma_f32_16x16x32_bf16 v[100:103], v[156:159], v[208:211], 0
	v_mfma_f32_16x16x32_bf16 v[96:99], v[164:167], v[208:211], 0
	v_mfma_f32_16x16x32_bf16 v[84:87], v[156:159], v[216:219], 0
	v_mfma_f32_16x16x32_bf16 v[80:83], v[164:167], v[216:219], 0
	v_mfma_f32_16x16x32_bf16 v[124:127], v[160:163], v[196:199], v[124:127]
	v_mfma_f32_16x16x32_bf16 v[120:123], v[168:171], v[196:199], v[120:123]
	v_mfma_f32_16x16x32_bf16 v[116:119], v[160:163], v[204:207], v[116:119]
	v_mfma_f32_16x16x32_bf16 v[112:115], v[168:171], v[204:207], v[112:115]
	v_mfma_f32_16x16x32_bf16 v[100:103], v[160:163], v[212:215], v[100:103]
	v_mfma_f32_16x16x32_bf16 v[96:99], v[168:171], v[212:215], v[96:99]
	v_mfma_f32_16x16x32_bf16 v[84:87], v[160:163], v[220:223], v[84:87]
	v_mfma_f32_16x16x32_bf16 v[80:83], v[168:171], v[220:223], v[80:83]
	v_mfma_f32_16x16x32_bf16 v[108:111], v[172:175], v[192:195], 0
	v_mfma_f32_16x16x32_bf16 v[104:107], v[184:187], v[192:195], 0
	v_mfma_f32_16x16x32_bf16 v[92:95], v[172:175], v[200:203], 0
	v_mfma_f32_16x16x32_bf16 v[88:91], v[184:187], v[200:203], 0
	v_mfma_f32_16x16x32_bf16 v[76:79], v[172:175], v[208:211], 0
	v_mfma_f32_16x16x32_bf16 v[72:75], v[184:187], v[208:211], 0
	v_mfma_f32_16x16x32_bf16 v[68:71], v[172:175], v[216:219], 0
	v_mfma_f32_16x16x32_bf16 v[64:67], v[184:187], v[216:219], 0
	v_mfma_f32_16x16x32_bf16 v[108:111], v[180:183], v[196:199], v[108:111]
	v_mfma_f32_16x16x32_bf16 v[104:107], v[188:191], v[196:199], v[104:107]
	v_mfma_f32_16x16x32_bf16 v[92:95], v[180:183], v[204:207], v[92:95]
	v_mfma_f32_16x16x32_bf16 v[88:91], v[188:191], v[204:207], v[88:91]
	v_mfma_f32_16x16x32_bf16 v[76:79], v[180:183], v[212:215], v[76:79]
	v_mfma_f32_16x16x32_bf16 v[72:75], v[188:191], v[212:215], v[72:75]
	v_mfma_f32_16x16x32_bf16 v[68:71], v[180:183], v[220:223], v[68:71]
	v_mfma_f32_16x16x32_bf16 v[64:67], v[188:191], v[220:223], v[64:67]
	s_waitcnt vmcnt(8)
	s_barrier
	s_add_i32 s27, s79, s3
	v_lshl_add_u64 v[224:225], s[80:81], 0, v[176:177]
	s_mov_b32 m0, s27
	ds_read_b128 v[192:195], v139 offset:16384
	ds_read_b128 v[196:199], v139 offset:17408
	ds_read_b128 v[200:203], v139 offset:18432
	ds_read_b128 v[204:207], v139 offset:19456
	ds_read_b128 v[208:211], v139 offset:20480
	ds_read_b128 v[212:215], v139 offset:21504
	ds_read_b128 v[216:219], v139 offset:22528
	ds_read_b128 v[220:223], v139 offset:23552
	global_load_lds_dwordx4 v[224:225], off
	s_add_i32 m0, s27, 0x2000
	v_lshl_add_u64 v[226:227], s[80:81], 0, v[132:133]
	s_add_u32 s80, s80, s30
	s_addc_u32 s81, s81, s31
	s_add_i32 s17, s17, s3
	global_load_lds_dwordx4 v[226:227], off
	v_lshl_add_u64 v[228:229], s[80:81], 0, v[176:177]
	s_mov_b32 m0, s17
	v_lshl_add_u64 v[230:231], s[80:81], 0, v[132:133]
	global_load_lds_dwordx4 v[228:229], off
	s_add_i32 m0, s17, 0x2000
	v_lshl_add_u64 v[232:233], s[96:97], 0, v[128:129]
	global_load_lds_dwordx4 v[230:231], off
	s_mov_b32 m0, s16
	v_lshl_add_u64 v[234:235], s[96:97], 0, v[130:131]
	global_load_lds_dwordx4 v[232:233], off
	s_mov_b32 m0, s14
	s_nop 0
	global_load_lds_dwordx4 v[234:235], off
	s_bitcmp1_b32 s101, 0
	s_cbranch_scc0 .Lvw_671_1
	s_waitcnt vmcnt(8)
; #define PG8_STAGE(bufoff, gbase, voff) do { _Pragma("unroll") for (int _i = 0; _i < 2; ++_i) \
;         __builtin_amdgcn_global_load_lds((const unsigned*)((const char*)(gbase) + (voff)[_i]), (LAS unsigned*)(lds + (bufoff) + ldsw + _i * 8192), 16, 0, 0); } while (0)
; #define PG8_LDA(dst, b, h) do { _Pragma("unroll") for (int m = 0; m < 4; ++m) _Pragma("unroll") for (int k = 0; k < 2; ++k) dst[m][k] = *(const LAS bf16x8*)(lds + PG8_SA(b, h) + aoff + m * 2048 + k * 1024); } while (0)
; #define PG8_LDB(dst, b, h) do { _Pragma("unroll") for (int n = 0; n < 2; ++n) _Pragma("unroll") for (int k = 0; k < 2; ++k) dst[n][k] = *(const LAS bf16x8*)(lds + PG8_SB(b, h) + boff + n * 2048 + k * 1024); } while (0)
; #define PG8_MMA(ai, bj, At, Bt) do { __builtin_amdgcn_s_setprio(1); _Pragma("unroll") for (int m = 0; m < 4; ++m) _Pragma("unroll") for (int n = 0; n < 2; ++n) _Pragma("unroll") for (int k = 0; k < 2; ++k) \
;         acc[ai][bj][m][n] = __builtin_amdgcn_mfma_f32_16x16x32_bf16(Bt[n][k], At[m][k], acc[ai][bj][m][n], 0, 0, 0); __builtin_amdgcn_s_setprio(0); } while (0)
; #define PG8_WAIT_V(n) asm volatile("s_waitcnt vmcnt(" #n ")" ::: "memory")
; #define PG8_WAIT_L(n) asm volatile("s_waitcnt lgkmcnt(" #n ")" ::: "memory")
; #define PG8_BAR __builtin_amdgcn_s_barrier()
; #define PG8_SCHED __builtin_amdgcn_sched_barrier(0)
; template <class Epi, class Sched, bool ALIGN_EPI>
; __device__ __forceinline__ void gemm_phase(LAS unsigned char* lds, const int wid, const int lda_, const int ldb_, const int K_, const Sched& S, const Epi& E) {
;     ...
;             PG8_LDB(B0, 0, 0); PG8_LDB(B1, 0, 1); PG8_SCHED; PG8_LDA(At, 0, 0); PG8_STAGE(PG8_SA(1, 1), a1 + hstepA, voffA);
;             PG8_WAIT_V(8); PG8_WAIT_L(0); PG8_BAR; PG8_MMA(0, 0, At, B0); PG8_MMA(0, 1, At, B1); PG8_BAR; PG8_SCHED;
;             PG8_LDA(At, 0, 1); PG8_STAGE(PG8_SB(0, 0), b2, voffB); PG8_STAGE(PG8_SB(0, 1), b2 + hstepB, voffB); PG8_STAGE(PG8_SA(0, 0), a2, voffA);
;             PG8_WAIT_V(8); PG8_WAIT_L(0); PG8_BAR; PG8_MMA(1, 0, At, B0); PG8_MMA(1, 1, At, B1); PG8_BAR; PG8_SCHED;
.Lvw_671_1:
	s_waitcnt lgkmcnt(0)
	s_barrier
	s_waitcnt lgkmcnt(0)
	v_mfma_f32_16x16x32_bf16 v[60:63], v[156:159], v[192:195], 0
	v_mfma_f32_16x16x32_bf16 v[56:59], v[164:167], v[192:195], 0
	v_mfma_f32_16x16x32_bf16 v[52:55], v[156:159], v[200:203], 0
	v_mfma_f32_16x16x32_bf16 v[48:51], v[164:167], v[200:203], 0
	v_mfma_f32_16x16x32_bf16 v[36:39], v[156:159], v[208:211], 0
	v_mfma_f32_16x16x32_bf16 v[32:35], v[164:167], v[208:211], 0
	v_mfma_f32_16x16x32_bf16 v[20:23], v[156:159], v[216:219], 0
	v_mfma_f32_16x16x32_bf16 v[16:19], v[164:167], v[216:219], 0
	v_mfma_f32_16x16x32_bf16 v[60:63], v[160:163], v[196:199], v[60:63]
	v_mfma_f32_16x16x32_bf16 v[56:59], v[168:171], v[196:199], v[56:59]
	v_mfma_f32_16x16x32_bf16 v[52:55], v[160:163], v[204:207], v[52:55]
	v_mfma_f32_16x16x32_bf16 v[48:51], v[168:171], v[204:207], v[48:51]
	v_mfma_f32_16x16x32_bf16 v[36:39], v[160:163], v[212:215], v[36:39]
	v_mfma_f32_16x16x32_bf16 v[32:35], v[168:171], v[212:215], v[32:35]
	v_mfma_f32_16x16x32_bf16 v[20:23], v[160:163], v[220:223], v[20:23]
	v_mfma_f32_16x16x32_bf16 v[16:19], v[168:171], v[220:223], v[16:19]
	v_mfma_f32_16x16x32_bf16 v[44:47], v[172:175], v[192:195], 0
	v_mfma_f32_16x16x32_bf16 v[40:43], v[184:187], v[192:195], 0
	v_mfma_f32_16x16x32_bf16 v[28:31], v[172:175], v[200:203], 0
	v_mfma_f32_16x16x32_bf16 v[24:27], v[184:187], v[200:203], 0
	v_mfma_f32_16x16x32_bf16 v[12:15], v[172:175], v[208:211], 0
	v_mfma_f32_16x16x32_bf16 v[8:11], v[184:187], v[208:211], 0
	v_mfma_f32_16x16x32_bf16 v[4:7], v[172:175], v[216:219], 0
	v_mfma_f32_16x16x32_bf16 v[0:3], v[184:187], v[216:219], 0
	v_mfma_f32_16x16x32_bf16 v[44:47], v[180:183], v[196:199], v[44:47]
	v_mfma_f32_16x16x32_bf16 v[40:43], v[188:191], v[196:199], v[40:43]
	v_mfma_f32_16x16x32_bf16 v[28:31], v[180:183], v[204:207], v[28:31]
	v_mfma_f32_16x16x32_bf16 v[24:27], v[188:191], v[204:207], v[24:27]
	v_mfma_f32_16x16x32_bf16 v[12:15], v[180:183], v[212:215], v[12:15]
	v_mfma_f32_16x16x32_bf16 v[8:11], v[188:191], v[212:215], v[8:11]
	v_mfma_f32_16x16x32_bf16 v[4:7], v[180:183], v[220:223], v[4:7]
	v_mfma_f32_16x16x32_bf16 v[0:3], v[188:191], v[220:223], v[0:3]
	s_waitcnt vmcnt(8)
	s_barrier
	s_branch .Lgemm_join_671
.LBB0_671:
	s_add_i32 s78, s77, 2
	s_add_u32 s17, s94, 0x80
	s_addc_u32 s27, s95, 0
	s_add_i32 s79, 0, 0x10000
	s_cmp_eq_u32 s41, s77
	s_cselect_b32 s97, s37, s27
	s_cselect_b32 s96, s39, s17
	v_add_u32_e32 v141, s79, v135
	s_cselect_b32 s81, s4, s76
	s_cselect_b32 s80, s5, s43
	s_add_i32 s17, 0, 0x14000
	ds_read_b128 v[156:159], v141
	ds_read_b128 v[160:163], v141 offset:1024
	ds_read_b128 v[164:167], v141 offset:2048
	ds_read_b128 v[168:171], v141 offset:3072
	v_add_u32_e32 v141, s17, v135
	ds_read_b128 v[172:175], v141
	ds_read_b128 v[180:183], v141 offset:1024
	ds_read_b128 v[184:187], v141 offset:2048
	ds_read_b128 v[188:191], v141 offset:3072
	v_lshl_add_u64 v[224:225], s[94:95], 0, v[152:153]
	s_add_i32 m0, s16, 0xc000
	ds_read_b128 v[192:195], v139
	ds_read_b128 v[196:199], v139 offset:1024
	ds_read_b128 v[200:203], v139 offset:2048
	ds_read_b128 v[204:207], v139 offset:3072
	ds_read_b128 v[208:211], v139 offset:4096
	ds_read_b128 v[212:215], v139 offset:5120
	ds_read_b128 v[216:219], v139 offset:6144
	ds_read_b128 v[220:223], v139 offset:7168
	global_load_lds_dwordx4 v[224:225], off
	v_lshl_add_u64 v[224:225], s[94:95], 0, v[154:155]
	s_add_i32 m0, s16, 0xe000
	s_nop 0
	global_load_lds_dwordx4 v[224:225], off
	s_bitcmp1_b32 s101, 0
	s_cbranch_scc0 .Lvw_671_2
	s_waitcnt vmcnt(8)
.Lvw_671_2:
	s_waitcnt lgkmcnt(0)
	s_barrier
	s_waitcnt lgkmcnt(0)
	v_mfma_f32_16x16x32_bf16 v[124:127], v[156:159], v[192:195], v[124:127]
	v_mfma_f32_16x16x32_bf16 v[120:123], v[164:167], v[192:195], v[120:123]
	v_mfma_f32_16x16x32_bf16 v[116:119], v[156:159], v[200:203], v[116:119]
	v_mfma_f32_16x16x32_bf16 v[112:115], v[164:167], v[200:203], v[112:115]
	v_mfma_f32_16x16x32_bf16 v[100:103], v[156:159], v[208:211], v[100:103]
	v_mfma_f32_16x16x32_bf16 v[96:99], v[164:167], v[208:211], v[96:99]
	v_mfma_f32_16x16x32_bf16 v[84:87], v[156:159], v[216:219], v[84:87]
	v_mfma_f32_16x16x32_bf16 v[80:83], v[164:167], v[216:219], v[80:83]
	v_mfma_f32_16x16x32_bf16 v[124:127], v[160:163], v[196:199], v[124:127]
	v_mfma_f32_16x16x32_bf16 v[120:123], v[168:171], v[196:199], v[120:123]
	v_mfma_f32_16x16x32_bf16 v[116:119], v[160:163], v[204:207], v[116:119]
	v_mfma_f32_16x16x32_bf16 v[112:115], v[168:171], v[204:207], v[112:115]
	v_mfma_f32_16x16x32_bf16 v[100:103], v[160:163], v[212:215], v[100:103]
	v_mfma_f32_16x16x32_bf16 v[96:99], v[168:171], v[212:215], v[96:99]
	v_mfma_f32_16x16x32_bf16 v[84:87], v[160:163], v[220:223], v[84:87]
	v_mfma_f32_16x16x32_bf16 v[80:83], v[168:171], v[220:223], v[80:83]
	v_mfma_f32_16x16x32_bf16 v[108:111], v[172:175], v[192:195], v[108:111]
	v_mfma_f32_16x16x32_bf16 v[104:107], v[184:187], v[192:195], v[104:107]
	v_mfma_f32_16x16x32_bf16 v[92:95], v[172:175], v[200:203], v[92:95]
	v_mfma_f32_16x16x32_bf16 v[88:91], v[184:187], v[200:203], v[88:91]
	v_mfma_f32_16x16x32_bf16 v[76:79], v[172:175], v[208:211], v[76:79]
	v_mfma_f32_16x16x32_bf16 v[72:75], v[184:187], v[208:211], v[72:75]
	v_mfma_f32_16x16x32_bf16 v[68:71], v[172:175], v[216:219], v[68:71]
	v_mfma_f32_16x16x32_bf16 v[64:67], v[184:187], v[216:219], v[64:67]
	v_mfma_f32_16x16x32_bf16 v[108:111], v[180:183], v[196:199], v[108:111]
	v_mfma_f32_16x16x32_bf16 v[104:107], v[188:191], v[196:199], v[104:107]
	v_mfma_f32_16x16x32_bf16 v[92:95], v[180:183], v[204:207], v[92:95]
	v_mfma_f32_16x16x32_bf16 v[88:91], v[188:191], v[204:207], v[88:91]
	v_mfma_f32_16x16x32_bf16 v[76:79], v[180:183], v[212:215], v[76:79]
	v_mfma_f32_16x16x32_bf16 v[72:75], v[188:191], v[212:215], v[72:75]
	v_mfma_f32_16x16x32_bf16 v[68:71], v[180:183], v[220:223], v[68:71]
	v_mfma_f32_16x16x32_bf16 v[64:67], v[188:191], v[220:223], v[64:67]
	s_waitcnt vmcnt(8)
	s_barrier
; #define PG8_STAGE(bufoff, gbase, voff) do { _Pragma("unroll") for (int _i = 0; _i < 2; ++_i) \
;         __builtin_amdgcn_global_load_lds((const unsigned*)((const char*)(gbase) + (voff)[_i]), (LAS unsigned*)(lds + (bufoff) + ldsw + _i * 8192), 16, 0, 0); } while (0)
; #define PG8_LDA(dst, b, h) do { _Pragma("unroll") for (int m = 0; m < 4; ++m) _Pragma("unroll") for (int k = 0; k < 2; ++k) dst[m][k] = *(const LAS bf16x8*)(lds + PG8_SA(b, h) + aoff + m * 2048 + k * 1024); } while (0)
; #define PG8_LDB(dst, b, h) do { _Pragma("unroll") for (int n = 0; n < 2; ++n) _Pragma("unroll") for (int k = 0; k < 2; ++k) dst[n][k] = *(const LAS bf16x8*)(lds + PG8_SB(b, h) + boff + n * 2048 + k * 1024); } while (0)
; #define PG8_MMA(ai, bj, At, Bt) do { __builtin_amdgcn_s_setprio(1); _Pragma("unroll") for (int m = 0; m < 4; ++m) _Pragma("unroll") for (int n = 0; n < 2; ++n) _Pragma("unroll") for (int k = 0; k < 2; ++k) \
;         acc[ai][bj][m][n] = __builtin_amdgcn_mfma_f32_16x16x32_bf16(Bt[n][k], At[m][k], acc[ai][bj][m][n], 0, 0, 0); __builtin_amdgcn_s_setprio(0); } while (0)
; #define PG8_WAIT_V(n) asm volatile("s_waitcnt vmcnt(" #n ")" ::: "memory")
; #define PG8_WAIT_L(n) asm volatile("s_waitcnt lgkmcnt(" #n ")" ::: "memory")
; #define PG8_BAR __builtin_amdgcn_s_barrier()
; #define PG8_SCHED __builtin_amdgcn_sched_barrier(0)
; template <class Epi, class Sched, bool ALIGN_EPI>
; __device__ __forceinline__ void gemm_phase(LAS unsigned char* lds, const int wid, const int lda_, const int ldb_, const int K_, const Sched& S, const Epi& E) {
;     ...
;             PG8_LDA(At, 0, 1); PG8_STAGE(PG8_SB(0, 0), b2, voffB); PG8_STAGE(PG8_SB(0, 1), b2 + hstepB, voffB); PG8_STAGE(PG8_SA(0, 0), a2, voffA);
;             PG8_WAIT_V(8); PG8_WAIT_L(0); PG8_BAR; PG8_MMA(1, 0, At, B0); PG8_MMA(1, 1, At, B1); PG8_BAR; PG8_SCHED;
;             PG8_LDB(B0, 1, 0); PG8_LDB(B1, 1, 1); PG8_SCHED; PG8_LDA(At, 1, 0); PG8_STAGE(PG8_SA(0, 1), a2 + hstepA, voffA);
;             PG8_WAIT_V(8); PG8_WAIT_L(0); PG8_BAR; PG8_MMA(0, 0, At, B0); PG8_MMA(0, 1, At, B1); PG8_BAR; PG8_SCHED;
	s_add_i32 s27, s79, s3
	v_lshl_add_u64 v[224:225], s[80:81], 0, v[176:177]
	s_mov_b32 m0, s27
	ds_read_b128 v[192:195], v139 offset:16384
	ds_read_b128 v[196:199], v139 offset:17408
	ds_read_b128 v[200:203], v139 offset:18432
	ds_read_b128 v[204:207], v139 offset:19456
	ds_read_b128 v[208:211], v139 offset:20480
	ds_read_b128 v[212:215], v139 offset:21504
	ds_read_b128 v[216:219], v139 offset:22528
	ds_read_b128 v[220:223], v139 offset:23552
	global_load_lds_dwordx4 v[224:225], off
	s_add_i32 m0, s27, 0x2000
	v_lshl_add_u64 v[226:227], s[80:81], 0, v[132:133]
	s_add_u32 s80, s80, s30
	s_addc_u32 s81, s81, s31
	s_add_i32 s17, s17, s3
	global_load_lds_dwordx4 v[226:227], off
	v_lshl_add_u64 v[228:229], s[80:81], 0, v[176:177]
	s_mov_b32 m0, s17
	v_lshl_add_u64 v[230:231], s[80:81], 0, v[132:133]
	global_load_lds_dwordx4 v[228:229], off
	s_add_i32 m0, s17, 0x2000
	v_lshl_add_u64 v[232:233], s[96:97], 0, v[128:129]
	global_load_lds_dwordx4 v[230:231], off
	s_mov_b32 m0, s16
	v_lshl_add_u64 v[234:235], s[96:97], 0, v[130:131]
	global_load_lds_dwordx4 v[232:233], off
	s_mov_b32 m0, s14
	s_nop 0
	global_load_lds_dwordx4 v[234:235], off
	s_bitcmp1_b32 s101, 0
	s_cbranch_scc0 .Lvw_671_3
	s_waitcnt vmcnt(8)
.Lvw_671_3:
	s_waitcnt lgkmcnt(0)
	s_barrier
	s_waitcnt lgkmcnt(0)
	v_mfma_f32_16x16x32_bf16 v[60:63], v[156:159], v[192:195], v[60:63]
	v_mfma_f32_16x16x32_bf16 v[56:59], v[164:167], v[192:195], v[56:59]
	v_mfma_f32_16x16x32_bf16 v[52:55], v[156:159], v[200:203], v[52:55]
	v_mfma_f32_16x16x32_bf16 v[48:51], v[164:167], v[200:203], v[48:51]
	v_mfma_f32_16x16x32_bf16 v[36:39], v[156:159], v[208:211], v[36:39]
	v_mfma_f32_16x16x32_bf16 v[32:35], v[164:167], v[208:211], v[32:35]
	v_mfma_f32_16x16x32_bf16 v[20:23], v[156:159], v[216:219], v[20:23]
	v_mfma_f32_16x16x32_bf16 v[16:19], v[164:167], v[216:219], v[16:19]
	v_mfma_f32_16x16x32_bf16 v[60:63], v[160:163], v[196:199], v[60:63]
	v_mfma_f32_16x16x32_bf16 v[56:59], v[168:171], v[196:199], v[56:59]
	v_mfma_f32_16x16x32_bf16 v[52:55], v[160:163], v[204:207], v[52:55]
	v_mfma_f32_16x16x32_bf16 v[48:51], v[168:171], v[204:207], v[48:51]
	v_mfma_f32_16x16x32_bf16 v[36:39], v[160:163], v[212:215], v[36:39]
	v_mfma_f32_16x16x32_bf16 v[32:35], v[168:171], v[212:215], v[32:35]
	v_mfma_f32_16x16x32_bf16 v[20:23], v[160:163], v[220:223], v[20:23]
	v_mfma_f32_16x16x32_bf16 v[16:19], v[168:171], v[220:223], v[16:19]
	v_mfma_f32_16x16x32_bf16 v[44:47], v[172:175], v[192:195], v[44:47]
	v_mfma_f32_16x16x32_bf16 v[40:43], v[184:187], v[192:195], v[40:43]
	v_mfma_f32_16x16x32_bf16 v[28:31], v[172:175], v[200:203], v[28:31]
	v_mfma_f32_16x16x32_bf16 v[24:27], v[184:187], v[200:203], v[24:27]
	v_mfma_f32_16x16x32_bf16 v[12:15], v[172:175], v[208:211], v[12:15]
	v_mfma_f32_16x16x32_bf16 v[8:11], v[184:187], v[208:211], v[8:11]
	v_mfma_f32_16x16x32_bf16 v[4:7], v[172:175], v[216:219], v[4:7]
	v_mfma_f32_16x16x32_bf16 v[0:3], v[184:187], v[216:219], v[0:3]
	v_mfma_f32_16x16x32_bf16 v[44:47], v[180:183], v[196:199], v[44:47]
	v_mfma_f32_16x16x32_bf16 v[40:43], v[188:191], v[196:199], v[40:43]
	v_mfma_f32_16x16x32_bf16 v[28:31], v[180:183], v[204:207], v[28:31]
	v_mfma_f32_16x16x32_bf16 v[24:27], v[188:191], v[204:207], v[24:27]
	v_mfma_f32_16x16x32_bf16 v[12:15], v[180:183], v[212:215], v[12:15]
	v_mfma_f32_16x16x32_bf16 v[8:11], v[188:191], v[212:215], v[8:11]
	v_mfma_f32_16x16x32_bf16 v[4:7], v[180:183], v[220:223], v[4:7]
	v_mfma_f32_16x16x32_bf16 v[0:3], v[188:191], v[220:223], v[0:3]
	s_waitcnt vmcnt(8)
	s_barrier
.Lgemm_join_671:
	s_add_i32 s17, 0, 0x18000
	v_add_u32_e32 v141, s17, v135
	s_add_i32 s27, 0, 0x1c000
	ds_read_b128 v[156:159], v141
	ds_read_b128 v[160:163], v141 offset:1024
	ds_read_b128 v[164:167], v141 offset:2048
	ds_read_b128 v[168:171], v141 offset:3072
	v_add_u32_e32 v141, s27, v135
	ds_read_b128 v[172:175], v141
	ds_read_b128 v[180:183], v141 offset:1024
	ds_read_b128 v[184:187], v141 offset:2048
	ds_read_b128 v[188:191], v141 offset:3072
	s_add_u32 s80, s96, s10
	s_addc_u32 s81, s97, s11
	s_mov_b32 m0, s15
	v_lshl_add_u64 v[236:237], s[80:81], 0, v[128:129]
	ds_read_b128 v[192:195], v139 offset:32768
	ds_read_b128 v[196:199], v139 offset:33792
	ds_read_b128 v[200:203], v139 offset:34816
	ds_read_b128 v[204:207], v139 offset:35840
	ds_read_b128 v[208:211], v139 offset:36864
	ds_read_b128 v[212:215], v139 offset:37888
	ds_read_b128 v[216:219], v139 offset:38912
	ds_read_b128 v[220:223], v139 offset:39936
	global_load_lds_dwordx4 v[236:237], off
	v_lshl_add_u64 v[236:237], s[80:81], 0, v[130:131]
	s_mov_b32 m0, s26
	s_nop 0
	global_load_lds_dwordx4 v[236:237], off
	s_bitcmp1_b32 s101, 0
	s_cbranch_scc0 .Lvw_671_4
	s_waitcnt vmcnt(8)
; #define PG8_STAGE(bufoff, gbase, voff) do { _Pragma("unroll") for (int _i = 0; _i < 2; ++_i) \
;         __builtin_amdgcn_global_load_lds((const unsigned*)((const char*)(gbase) + (voff)[_i]), (LAS unsigned*)(lds + (bufoff) + ldsw + _i * 8192), 16, 0, 0); } while (0)
; #define PG8_LDA(dst, b, h) do { _Pragma("unroll") for (int m = 0; m < 4; ++m) _Pragma("unroll") for (int k = 0; k < 2; ++k) dst[m][k] = *(const LAS bf16x8*)(lds + PG8_SA(b, h) + aoff + m * 2048 + k * 1024); } while (0)
; #define PG8_MMA(ai, bj, At, Bt) do { __builtin_amdgcn_s_setprio(1); _Pragma("unroll") for (int m = 0; m < 4; ++m) _Pragma("unroll") for (int n = 0; n < 2; ++n) _Pragma("unroll") for (int k = 0; k < 2; ++k) \
;         acc[ai][bj][m][n] = __builtin_amdgcn_mfma_f32_16x16x32_bf16(Bt[n][k], At[m][k], acc[ai][bj][m][n], 0, 0, 0); __builtin_amdgcn_s_setprio(0); } while (0)
; #define PG8_WAIT_V(n) asm volatile("s_waitcnt vmcnt(" #n ")" ::: "memory")
; #define PG8_WAIT_L(n) asm volatile("s_waitcnt lgkmcnt(" #n ")" ::: "memory")
; #define PG8_BAR __builtin_amdgcn_s_barrier()
; #define PG8_SCHED __builtin_amdgcn_sched_barrier(0)
; template <class Epi, class Sched, bool ALIGN_EPI>
; __device__ __forceinline__ void gemm_phase(LAS unsigned char* lds, const int wid, const int lda_, const int ldb_, const int K_, const Sched& S, const Epi& E) {
;     ...
;             PG8_WAIT_V(8); PG8_WAIT_L(0); PG8_BAR; PG8_MMA(0, 0, At, B0); PG8_MMA(0, 1, At, B1); PG8_BAR; PG8_SCHED;
;             PG8_LDA(At, 1, 1); PG8_STAGE(PG8_SB(1, 0), b3, voffB); PG8_STAGE(PG8_SB(1, 1), b3 + hstepB, voffB); PG8_STAGE(PG8_SA(1, 0), a3, voffA);
;             PG8_WAIT_V(8); PG8_WAIT_L(0); PG8_BAR; PG8_MMA(1, 0, At, B0); PG8_MMA(1, 1, At, B1); PG8_BAR; PG8_SCHED;
;         }
;         if constexpr (ALIGN_EPI) { if (wr == 0) PG8_BAR; }
;         E(acc, cur, S, wr, wc, fr, fq);
;     __device__ __forceinline__ void out(const pg8::Unit& u, char*& o, int& ldo, int& kind) const { ldo = D;
;         if (u.kq < 0) { o = (char*)ws + YOFF + ((size_t)u.pm * 256 * D + (size_t)u.pn * 256) * 2; kind = 0; }
;         else { o = (char*)ws + WS_PART + (((size_t)u.kq * MCTX + (size_t)(u.pm - 64) * 256) * D + (size_t)u.pn * 256) * 2; kind = 0; } }
.Lvw_671_4:
	s_waitcnt lgkmcnt(0)
	s_barrier
	s_waitcnt lgkmcnt(0)
	v_mfma_f32_16x16x32_bf16 v[124:127], v[156:159], v[192:195], v[124:127]
	v_mfma_f32_16x16x32_bf16 v[120:123], v[164:167], v[192:195], v[120:123]
	v_mfma_f32_16x16x32_bf16 v[116:119], v[156:159], v[200:203], v[116:119]
	v_mfma_f32_16x16x32_bf16 v[112:115], v[164:167], v[200:203], v[112:115]
	v_mfma_f32_16x16x32_bf16 v[100:103], v[156:159], v[208:211], v[100:103]
	v_mfma_f32_16x16x32_bf16 v[96:99], v[164:167], v[208:211], v[96:99]
	v_mfma_f32_16x16x32_bf16 v[84:87], v[156:159], v[216:219], v[84:87]
	v_mfma_f32_16x16x32_bf16 v[80:83], v[164:167], v[216:219], v[80:83]
	v_mfma_f32_16x16x32_bf16 v[124:127], v[160:163], v[196:199], v[124:127]
	v_mfma_f32_16x16x32_bf16 v[120:123], v[168:171], v[196:199], v[120:123]
	v_mfma_f32_16x16x32_bf16 v[116:119], v[160:163], v[204:207], v[116:119]
	v_mfma_f32_16x16x32_bf16 v[112:115], v[168:171], v[204:207], v[112:115]
	v_mfma_f32_16x16x32_bf16 v[100:103], v[160:163], v[212:215], v[100:103]
	v_mfma_f32_16x16x32_bf16 v[96:99], v[168:171], v[212:215], v[96:99]
	v_mfma_f32_16x16x32_bf16 v[84:87], v[160:163], v[220:223], v[84:87]
	v_mfma_f32_16x16x32_bf16 v[80:83], v[168:171], v[220:223], v[80:83]
	v_mfma_f32_16x16x32_bf16 v[108:111], v[172:175], v[192:195], v[108:111]
	v_mfma_f32_16x16x32_bf16 v[104:107], v[184:187], v[192:195], v[104:107]
	v_mfma_f32_16x16x32_bf16 v[92:95], v[172:175], v[200:203], v[92:95]
	v_mfma_f32_16x16x32_bf16 v[88:91], v[184:187], v[200:203], v[88:91]
	v_mfma_f32_16x16x32_bf16 v[76:79], v[172:175], v[208:211], v[76:79]
	v_mfma_f32_16x16x32_bf16 v[72:75], v[184:187], v[208:211], v[72:75]
	v_mfma_f32_16x16x32_bf16 v[68:71], v[172:175], v[216:219], v[68:71]
	v_mfma_f32_16x16x32_bf16 v[64:67], v[184:187], v[216:219], v[64:67]
	v_mfma_f32_16x16x32_bf16 v[108:111], v[180:183], v[196:199], v[108:111]
	v_mfma_f32_16x16x32_bf16 v[104:107], v[188:191], v[196:199], v[104:107]
	v_mfma_f32_16x16x32_bf16 v[92:95], v[180:183], v[204:207], v[92:95]
	v_mfma_f32_16x16x32_bf16 v[88:91], v[188:191], v[204:207], v[88:91]
	v_mfma_f32_16x16x32_bf16 v[76:79], v[180:183], v[212:215], v[76:79]
	v_mfma_f32_16x16x32_bf16 v[72:75], v[188:191], v[212:215], v[72:75]
	v_mfma_f32_16x16x32_bf16 v[68:71], v[180:183], v[220:223], v[68:71]
	v_mfma_f32_16x16x32_bf16 v[64:67], v[188:191], v[220:223], v[64:67]
	s_waitcnt vmcnt(8)
	s_barrier
	s_add_i32 s17, s17, s3
	v_lshl_add_u64 v[224:225], v[224:225], 0, s[24:25]
	s_mov_b32 m0, s17
	ds_read_b128 v[192:195], v139 offset:49152
	ds_read_b128 v[196:199], v139 offset:50176
	ds_read_b128 v[200:203], v139 offset:51200
	ds_read_b128 v[204:207], v139 offset:52224
	ds_read_b128 v[208:211], v139 offset:53248
	ds_read_b128 v[212:215], v139 offset:54272
	ds_read_b128 v[216:219], v139 offset:55296
	ds_read_b128 v[220:223], v139 offset:56320
	global_load_lds_dwordx4 v[224:225], off
	v_lshl_add_u64 v[224:225], v[226:227], 0, s[24:25]
	s_add_i32 m0, s17, 0x2000
	s_add_i32 s17, s27, s3
	global_load_lds_dwordx4 v[224:225], off
	v_lshl_add_u64 v[224:225], v[228:229], 0, s[24:25]
	s_mov_b32 m0, s17
	s_nop 0
	global_load_lds_dwordx4 v[224:225], off
	v_lshl_add_u64 v[224:225], v[230:231], 0, s[24:25]
	s_add_i32 m0, s17, 0x2000
	s_nop 0
	global_load_lds_dwordx4 v[224:225], off
	v_lshl_add_u64 v[224:225], v[232:233], 0, s[24:25]
	s_mov_b32 m0, s72
	s_nop 0
	global_load_lds_dwordx4 v[224:225], off
	v_lshl_add_u64 v[224:225], v[234:235], 0, s[24:25]
	s_mov_b32 m0, s73
	s_nop 0
	global_load_lds_dwordx4 v[224:225], off
	s_bitcmp1_b32 s101, 0
	s_cbranch_scc0 .Lvw_671_5
	s_waitcnt vmcnt(8)
.Lvw_671_5:
	s_waitcnt lgkmcnt(0)
	s_barrier
	s_waitcnt lgkmcnt(0)
	v_mfma_f32_16x16x32_bf16 v[60:63], v[156:159], v[192:195], v[60:63]
	v_mfma_f32_16x16x32_bf16 v[56:59], v[164:167], v[192:195], v[56:59]
	v_mfma_f32_16x16x32_bf16 v[52:55], v[156:159], v[200:203], v[52:55]
	v_mfma_f32_16x16x32_bf16 v[48:51], v[164:167], v[200:203], v[48:51]
	v_mfma_f32_16x16x32_bf16 v[36:39], v[156:159], v[208:211], v[36:39]
	v_mfma_f32_16x16x32_bf16 v[32:35], v[164:167], v[208:211], v[32:35]
	v_mfma_f32_16x16x32_bf16 v[20:23], v[156:159], v[216:219], v[20:23]
	v_mfma_f32_16x16x32_bf16 v[16:19], v[164:167], v[216:219], v[16:19]
	v_mfma_f32_16x16x32_bf16 v[60:63], v[160:163], v[196:199], v[60:63]
	v_mfma_f32_16x16x32_bf16 v[56:59], v[168:171], v[196:199], v[56:59]
	v_mfma_f32_16x16x32_bf16 v[52:55], v[160:163], v[204:207], v[52:55]
	v_mfma_f32_16x16x32_bf16 v[48:51], v[168:171], v[204:207], v[48:51]
	v_mfma_f32_16x16x32_bf16 v[36:39], v[160:163], v[212:215], v[36:39]
	v_mfma_f32_16x16x32_bf16 v[32:35], v[168:171], v[212:215], v[32:35]
	v_mfma_f32_16x16x32_bf16 v[20:23], v[160:163], v[220:223], v[20:23]
	v_mfma_f32_16x16x32_bf16 v[16:19], v[168:171], v[220:223], v[16:19]
	v_mfma_f32_16x16x32_bf16 v[44:47], v[172:175], v[192:195], v[44:47]
	v_mfma_f32_16x16x32_bf16 v[40:43], v[184:187], v[192:195], v[40:43]
	v_mfma_f32_16x16x32_bf16 v[28:31], v[172:175], v[200:203], v[28:31]
	v_mfma_f32_16x16x32_bf16 v[24:27], v[184:187], v[200:203], v[24:27]
	v_mfma_f32_16x16x32_bf16 v[12:15], v[172:175], v[208:211], v[12:15]
	v_mfma_f32_16x16x32_bf16 v[8:11], v[184:187], v[208:211], v[8:11]
	v_mfma_f32_16x16x32_bf16 v[4:7], v[172:175], v[216:219], v[4:7]
	v_mfma_f32_16x16x32_bf16 v[0:3], v[184:187], v[216:219], v[0:3]
	v_mfma_f32_16x16x32_bf16 v[44:47], v[180:183], v[196:199], v[44:47]
	v_mfma_f32_16x16x32_bf16 v[40:43], v[188:191], v[196:199], v[40:43]
	v_mfma_f32_16x16x32_bf16 v[28:31], v[180:183], v[204:207], v[28:31]
	v_mfma_f32_16x16x32_bf16 v[24:27], v[188:191], v[204:207], v[24:27]
	v_mfma_f32_16x16x32_bf16 v[12:15], v[180:183], v[212:215], v[12:15]
	v_mfma_f32_16x16x32_bf16 v[8:11], v[188:191], v[212:215], v[8:11]
	v_mfma_f32_16x16x32_bf16 v[4:7], v[180:183], v[220:223], v[4:7]
	v_mfma_f32_16x16x32_bf16 v[0:3], v[188:191], v[220:223], v[0:3]
	s_waitcnt vmcnt(8)
	s_barrier
	s_add_u32 s94, s94, 0x100
	s_addc_u32 s95, s95, 0
	s_add_u32 s43, s43, 0x100
	s_addc_u32 s76, s76, 0
	s_cmp_ge_u32 s78, s35
	s_mov_b32 s77, s78
	s_cbranch_scc0 .LBB0_671
	s_setprio 2
	s_mov_b64 s[94:95], -1
	s_and_b64 vcc, exec, s[50:51]
	s_cbranch_vccz .LBB0_674
	s_mov_b32 s39, s92
	s_ashr_i32 s35, s34, 31
	s_ashr_i32 s37, s36, 31
	s_lshl_b64 s[4:5], s[34:35], 20
	s_lshl_b64 s[50:51], s[36:37], 9
	s_lshl_b64 s[38:39], s[38:39], 23
	v_readlane_b32 s76, v251, 28
	v_readlane_b32 s77, v251, 29
	s_add_u32 s17, s76, s50
	s_addc_u32 s27, s77, s51
	s_add_u32 s17, s17, s38
	s_addc_u32 s27, s27, s39
	s_add_u32 s4, s17, s4
	s_addc_u32 s5, s27, s5
	s_add_u32 s4, s4, 0xfc000000
	s_addc_u32 s5, s5, -1
	s_mov_b64 s[94:95], 0

; #define PG8_STAGE(bufoff, gbase, voff) do { _Pragma("unroll") for (int _i = 0; _i < 2; ++_i) \
;         __builtin_amdgcn_global_load_lds((const unsigned*)((const char*)(gbase) + (voff)[_i]), (LAS unsigned*)(lds + (bufoff) + ldsw + _i * 8192), 16, 0, 0); } while (0)
; #define PG8_LDA(dst, b, h) do { _Pragma("unroll") for (int m = 0; m < 4; ++m) _Pragma("unroll") for (int k = 0; k < 2; ++k) dst[m][k] = *(const LAS bf16x8*)(lds + PG8_SA(b, h) + aoff + m * 2048 + k * 1024); } while (0)
; #define PG8_LDB(dst, b, h) do { _Pragma("unroll") for (int n = 0; n < 2; ++n) _Pragma("unroll") for (int k = 0; k < 2; ++k) dst[n][k] = *(const LAS bf16x8*)(lds + PG8_SB(b, h) + boff + n * 2048 + k * 1024); } while (0)
; #define PG8_WAIT_V(n) asm volatile("s_waitcnt vmcnt(" #n ")" ::: "memory")
; #define PG8_WAIT_L(n) asm volatile("s_waitcnt lgkmcnt(" #n ")" ::: "memory")
; #define PG8_BAR __builtin_amdgcn_s_barrier()
; template <class Epi, class Sched, bool ALIGN_EPI>
; __device__ __forceinline__ void gemm_phase(LAS unsigned char* lds, const int wid, const int lda_, const int ldb_, const int K_, const Sched& S, const Epi& E) {
;     ...
;         const bool has_next = S.next(ui + 1, nxt);
;         const int nt = S.nt(cur);
;         const char* nA = has_next ? S.a(nxt) : cA; const char* nB = has_next ? S.b(nxt) : cB;
; #pragma unroll 1
;         for (int t = 0; t < nt; t += 2) {
;             const bool last = (t == nt - 2);
;             const char* a1 = cA + (size_t)(t + 1) * kstep;
;             const char* a2 = last ? nA : cA + (size_t)(t + 2) * kstep; const char* b2 = last ? nB : cB + (size_t)(t + 2) * kstep;
;             const char* a3 = a2 + kstep; const char* b3 = b2 + kstep;
;             PG8_LDB(B0, 0, 0); PG8_LDB(B1, 0, 1); PG8_SCHED; PG8_LDA(At, 0, 0); PG8_STAGE(PG8_SA(1, 1), a1 + hstepA, voffA);
;             PG8_WAIT_V(8); PG8_WAIT_L(0); PG8_BAR; PG8_MMA(0, 0, At, B0); PG8_MMA(0, 1, At, B1); PG8_BAR; PG8_SCHED;
;     __device__ __forceinline__ bool next(int i, pg8::Unit& u) const { return pg8::tile2d<72>(i, 16, u); }
;     __device__ __forceinline__ const char* a(const pg8::Unit& u) const { return (const char*)ws + WS_W1 + (size_t)(u.pm & 1) * 256 * 256 * 2; }
;     __device__ __forceinline__ const char* b(const pg8::Unit& u) const { return (const char*)ws + WS_A + ((size_t)u.pn * 256 * D + (size_t)(u.pm >> 1) * 256) * 2; }
.LBB0_696:
	v_mov_b64_e32 v[0:1], 0x480
	v_cmp_lt_i64_e32 vcc, s[4:5], v[0:1]
	s_lshl_b32 s4, s73, 17
	s_and_b32 s4, s4, 0x20000
	v_readlane_b32 s5, v253, 31
	s_add_u32 s34, s5, s4
	v_readlane_b32 s4, v253, 32
	s_addc_u32 s35, s4, 0
	s_and_b64 s[4:5], vcc, exec
	s_cselect_b32 s4, s35, s45
	s_cselect_b32 s5, s34, s44
	s_ashr_i32 s36, s73, 1
	s_ashr_i32 s31, s30, 31
	s_ashr_i32 s37, s36, 31
	s_lshl_b64 s[36:37], s[36:37], 9
	s_lshl_b64 s[42:43], s[30:31], 20
	v_readlane_b32 s46, v253, 52
	v_readlane_b32 s47, v253, 53
	s_add_u32 s31, s46, s42
	s_addc_u32 s42, s47, s43
	s_add_u32 s36, s31, s36
	s_addc_u32 s37, s42, s37
	s_and_b64 s[42:43], vcc, exec
	s_cselect_b32 s31, s37, s41
	s_cselect_b32 s76, s36, s40
	s_mov_b64 s[50:51], 0
	s_mov_b64 s[46:47], -1
	s_mov_b64 s[48:49], 0
	s_add_u32 s77, s44, s50
	s_addc_u32 s78, s45, s51
	s_add_u32 s79, s77, 0x100
	s_addc_u32 s80, s78, 0
	s_and_b64 s[42:43], s[48:49], exec
	s_cselect_b32 s95, s4, s80
	s_cselect_b32 s94, s5, s79
	s_add_u32 s42, s40, s50
	s_addc_u32 s43, s41, s51
	s_add_u32 s50, s42, 0x100
	s_addc_u32 s51, s43, 0
	s_add_i32 s93, 0, 0x10000
	s_and_b64 s[42:43], s[48:49], exec
	s_cselect_b32 s51, s31, s51
	s_cselect_b32 s50, s76, s50
	s_add_i32 s42, 0, 0x14000
	v_add_u32_e32 v141, s93, v135
	s_add_u32 vcc_lo, s77, s0
	ds_read_b128 v[152:155], v141
	ds_read_b128 v[156:159], v141 offset:1024
	ds_read_b128 v[160:163], v141 offset:2048
	ds_read_b128 v[164:167], v141 offset:3072
	v_add_u32_e32 v141, s42, v135
	s_addc_u32 vcc_hi, s78, s1
	s_add_i32 s87, s93, s3
	ds_read_b128 v[168:171], v141
	ds_read_b128 v[172:175], v141 offset:1024
	ds_read_b128 v[180:183], v141 offset:2048
	ds_read_b128 v[184:187], v141 offset:3072
	s_add_i32 m0, s16, 0xc000
	s_add_i32 s27, s16, 0xe000
	s_add_i32 s80, s87, 0x2000
	s_add_u32 s96, s50, s10
	s_addc_u32 s97, s51, s11
	s_add_i32 s86, s42, s3
	s_add_i32 s81, s86, 0x2000
	s_add_i32 s79, 0, 0x18000
	s_add_i32 s78, 0, 0x1c000
	s_add_u32 s48, s94, s0
	s_addc_u32 s49, s95, s1
	s_add_i32 s77, s79, s3
	s_add_i32 s93, s78, s3
	s_add_i32 s43, s77, 0x2000
	s_add_i32 s42, s93, 0x2000
	v_lshl_add_u64 v[220:221], vcc, 0, v[132:133]
	v_lshl_add_u64 v[220:221], v[220:221], 0, s[24:25]
	ds_read_b128 v[188:191], v139
	ds_read_b128 v[192:195], v139 offset:1024
	ds_read_b128 v[196:199], v139 offset:2048
	ds_read_b128 v[200:203], v139 offset:3072
	ds_read_b128 v[204:207], v139 offset:4096
	ds_read_b128 v[208:211], v139 offset:5120
	ds_read_b128 v[212:215], v139 offset:6144
	ds_read_b128 v[216:219], v139 offset:7168
	global_load_lds_dwordx4 v[220:221], off
	v_lshl_add_u64 v[220:221], vcc, 0, v[130:131]
	v_lshl_add_u64 v[220:221], v[220:221], 0, s[24:25]
	s_mov_b32 m0, s27
	s_nop 0
	global_load_lds_dwordx4 v[220:221], off
	v_readlane_b32 s101, v252, 58
	s_nop 3
	s_bitcmp1_b32 s101, 0
	s_cbranch_scc0 .Lvw_697_0
	s_waitcnt vmcnt(8)
.Lvw_697_0:
	s_waitcnt lgkmcnt(0)
	s_barrier
	s_setprio 0
	s_waitcnt lgkmcnt(0)
	v_mfma_f32_16x16x32_bf16 v[124:127], v[152:155], v[188:191], 0
	v_mfma_f32_16x16x32_bf16 v[120:123], v[160:163], v[188:191], 0
	v_mfma_f32_16x16x32_bf16 v[116:119], v[152:155], v[196:199], 0
	v_mfma_f32_16x16x32_bf16 v[112:115], v[160:163], v[196:199], 0
	v_mfma_f32_16x16x32_bf16 v[100:103], v[152:155], v[204:207], 0
	v_mfma_f32_16x16x32_bf16 v[96:99], v[160:163], v[204:207], 0
	v_mfma_f32_16x16x32_bf16 v[84:87], v[152:155], v[212:215], 0
	v_mfma_f32_16x16x32_bf16 v[80:83], v[160:163], v[212:215], 0
	v_mfma_f32_16x16x32_bf16 v[124:127], v[156:159], v[192:195], v[124:127]
	v_mfma_f32_16x16x32_bf16 v[120:123], v[164:167], v[192:195], v[120:123]
	v_mfma_f32_16x16x32_bf16 v[116:119], v[156:159], v[200:203], v[116:119]
	v_mfma_f32_16x16x32_bf16 v[112:115], v[164:167], v[200:203], v[112:115]
	v_mfma_f32_16x16x32_bf16 v[100:103], v[156:159], v[208:211], v[100:103]
	v_mfma_f32_16x16x32_bf16 v[96:99], v[164:167], v[208:211], v[96:99]
	v_mfma_f32_16x16x32_bf16 v[84:87], v[156:159], v[216:219], v[84:87]
	v_mfma_f32_16x16x32_bf16 v[80:83], v[164:167], v[216:219], v[80:83]
	v_mfma_f32_16x16x32_bf16 v[108:111], v[168:171], v[188:191], 0
	v_mfma_f32_16x16x32_bf16 v[104:107], v[180:183], v[188:191], 0
	v_mfma_f32_16x16x32_bf16 v[92:95], v[168:171], v[196:199], 0
	v_mfma_f32_16x16x32_bf16 v[88:91], v[180:183], v[196:199], 0
	v_mfma_f32_16x16x32_bf16 v[76:79], v[168:171], v[204:207], 0
	v_mfma_f32_16x16x32_bf16 v[72:75], v[180:183], v[204:207], 0
	v_mfma_f32_16x16x32_bf16 v[68:71], v[168:171], v[212:215], 0
	v_mfma_f32_16x16x32_bf16 v[64:67], v[180:183], v[212:215], 0
	v_mfma_f32_16x16x32_bf16 v[108:111], v[172:175], v[192:195], v[108:111]
	v_mfma_f32_16x16x32_bf16 v[104:107], v[184:187], v[192:195], v[104:107]
	v_mfma_f32_16x16x32_bf16 v[92:95], v[172:175], v[200:203], v[92:95]
	v_mfma_f32_16x16x32_bf16 v[88:91], v[184:187], v[200:203], v[88:91]
	v_mfma_f32_16x16x32_bf16 v[76:79], v[172:175], v[208:211], v[76:79]
	v_mfma_f32_16x16x32_bf16 v[72:75], v[184:187], v[208:211], v[72:75]
	v_mfma_f32_16x16x32_bf16 v[68:71], v[172:175], v[216:219], v[68:71]
	v_mfma_f32_16x16x32_bf16 v[64:67], v[184:187], v[216:219], v[64:67]
	s_waitcnt vmcnt(8)
	s_barrier
	s_mov_b32 m0, s87
	v_lshl_add_u64 v[220:221], s[50:51], 0, v[176:177]
	ds_read_b128 v[188:191], v139 offset:16384
	ds_read_b128 v[192:195], v139 offset:17408
	ds_read_b128 v[196:199], v139 offset:18432
	ds_read_b128 v[200:203], v139 offset:19456
	ds_read_b128 v[204:207], v139 offset:20480
	ds_read_b128 v[208:211], v139 offset:21504
	ds_read_b128 v[212:215], v139 offset:22528
	ds_read_b128 v[216:219], v139 offset:23552
	global_load_lds_dwordx4 v[220:221], off
	v_lshl_add_u64 v[222:223], s[50:51], 0, v[128:129]
	s_mov_b32 m0, s80
	v_lshl_add_u64 v[224:225], s[96:97], 0, v[176:177]
	global_load_lds_dwordx4 v[222:223], off
	s_mov_b32 m0, s86
	v_lshl_add_u64 v[226:227], s[96:97], 0, v[128:129]
	global_load_lds_dwordx4 v[224:225], off
	s_mov_b32 m0, s81
	v_lshl_add_u64 v[228:229], s[94:95], 0, v[132:133]
	global_load_lds_dwordx4 v[226:227], off
	s_mov_b32 m0, s16
	v_lshl_add_u64 v[230:231], s[94:95], 0, v[130:131]
	global_load_lds_dwordx4 v[228:229], off
	s_mov_b32 m0, s6
	s_nop 0
	global_load_lds_dwordx4 v[230:231], off
	s_bitcmp1_b32 s101, 0
	s_cbranch_scc0 .Lvw_697_1
	s_waitcnt vmcnt(8)
; #define PG8_STAGE(bufoff, gbase, voff) do { _Pragma("unroll") for (int _i = 0; _i < 2; ++_i) \
;         __builtin_amdgcn_global_load_lds((const unsigned*)((const char*)(gbase) + (voff)[_i]), (LAS unsigned*)(lds + (bufoff) + ldsw + _i * 8192), 16, 0, 0); } while (0)
; #define PG8_LDA(dst, b, h) do { _Pragma("unroll") for (int m = 0; m < 4; ++m) _Pragma("unroll") for (int k = 0; k < 2; ++k) dst[m][k] = *(const LAS bf16x8*)(lds + PG8_SA(b, h) + aoff + m * 2048 + k * 1024); } while (0)
; #define PG8_LDB(dst, b, h) do { _Pragma("unroll") for (int n = 0; n < 2; ++n) _Pragma("unroll") for (int k = 0; k < 2; ++k) dst[n][k] = *(const LAS bf16x8*)(lds + PG8_SB(b, h) + boff + n * 2048 + k * 1024); } while (0)
; #define PG8_MMA(ai, bj, At, Bt) do { __builtin_amdgcn_s_setprio(1); _Pragma("unroll") for (int m = 0; m < 4; ++m) _Pragma("unroll") for (int n = 0; n < 2; ++n) _Pragma("unroll") for (int k = 0; k < 2; ++k) \
;         acc[ai][bj][m][n] = __builtin_amdgcn_mfma_f32_16x16x32_bf16(Bt[n][k], At[m][k], acc[ai][bj][m][n], 0, 0, 0); __builtin_amdgcn_s_setprio(0); } while (0)
; #define PG8_WAIT_V(n) asm volatile("s_waitcnt vmcnt(" #n ")" ::: "memory")
; #define PG8_WAIT_L(n) asm volatile("s_waitcnt lgkmcnt(" #n ")" ::: "memory")
; #define PG8_BAR __builtin_amdgcn_s_barrier()
; #define PG8_SCHED __builtin_amdgcn_sched_barrier(0)
; template <class Epi, class Sched, bool ALIGN_EPI>
; __device__ __forceinline__ void gemm_phase(LAS unsigned char* lds, const int wid, const int lda_, const int ldb_, const int K_, const Sched& S, const Epi& E) {
;     ...
;             PG8_LDB(B0, 0, 0); PG8_LDB(B1, 0, 1); PG8_SCHED; PG8_LDA(At, 0, 0); PG8_STAGE(PG8_SA(1, 1), a1 + hstepA, voffA);
;             PG8_WAIT_V(8); PG8_WAIT_L(0); PG8_BAR; PG8_MMA(0, 0, At, B0); PG8_MMA(0, 1, At, B1); PG8_BAR; PG8_SCHED;
;             PG8_LDA(At, 0, 1); PG8_STAGE(PG8_SB(0, 0), b2, voffB); PG8_STAGE(PG8_SB(0, 1), b2 + hstepB, voffB); PG8_STAGE(PG8_SA(0, 0), a2, voffA);
;             PG8_WAIT_V(8); PG8_WAIT_L(0); PG8_BAR; PG8_MMA(1, 0, At, B0); PG8_MMA(1, 1, At, B1); PG8_BAR; PG8_SCHED;
.Lvw_697_1:
	s_waitcnt lgkmcnt(0)
	s_barrier
	s_waitcnt lgkmcnt(0)
	v_mfma_f32_16x16x32_bf16 v[60:63], v[152:155], v[188:191], 0
	v_mfma_f32_16x16x32_bf16 v[56:59], v[160:163], v[188:191], 0
	v_mfma_f32_16x16x32_bf16 v[52:55], v[152:155], v[196:199], 0
	v_mfma_f32_16x16x32_bf16 v[48:51], v[160:163], v[196:199], 0
	v_mfma_f32_16x16x32_bf16 v[36:39], v[152:155], v[204:207], 0
	v_mfma_f32_16x16x32_bf16 v[32:35], v[160:163], v[204:207], 0
	v_mfma_f32_16x16x32_bf16 v[20:23], v[152:155], v[212:215], 0
	v_mfma_f32_16x16x32_bf16 v[16:19], v[160:163], v[212:215], 0
	v_mfma_f32_16x16x32_bf16 v[60:63], v[156:159], v[192:195], v[60:63]
	v_mfma_f32_16x16x32_bf16 v[56:59], v[164:167], v[192:195], v[56:59]
	v_mfma_f32_16x16x32_bf16 v[52:55], v[156:159], v[200:203], v[52:55]
	v_mfma_f32_16x16x32_bf16 v[48:51], v[164:167], v[200:203], v[48:51]
	v_mfma_f32_16x16x32_bf16 v[36:39], v[156:159], v[208:211], v[36:39]
	v_mfma_f32_16x16x32_bf16 v[32:35], v[164:167], v[208:211], v[32:35]
	v_mfma_f32_16x16x32_bf16 v[20:23], v[156:159], v[216:219], v[20:23]
	v_mfma_f32_16x16x32_bf16 v[16:19], v[164:167], v[216:219], v[16:19]
	v_mfma_f32_16x16x32_bf16 v[44:47], v[168:171], v[188:191], 0
	v_mfma_f32_16x16x32_bf16 v[40:43], v[180:183], v[188:191], 0
	v_mfma_f32_16x16x32_bf16 v[28:31], v[168:171], v[196:199], 0
	v_mfma_f32_16x16x32_bf16 v[24:27], v[180:183], v[196:199], 0
	v_mfma_f32_16x16x32_bf16 v[12:15], v[168:171], v[204:207], 0
	v_mfma_f32_16x16x32_bf16 v[8:11], v[180:183], v[204:207], 0
	v_mfma_f32_16x16x32_bf16 v[4:7], v[168:171], v[212:215], 0
	v_mfma_f32_16x16x32_bf16 v[0:3], v[180:183], v[212:215], 0
	v_mfma_f32_16x16x32_bf16 v[44:47], v[172:175], v[192:195], v[44:47]
	v_mfma_f32_16x16x32_bf16 v[40:43], v[184:187], v[192:195], v[40:43]
	v_mfma_f32_16x16x32_bf16 v[28:31], v[172:175], v[200:203], v[28:31]
	v_mfma_f32_16x16x32_bf16 v[24:27], v[184:187], v[200:203], v[24:27]
	v_mfma_f32_16x16x32_bf16 v[12:15], v[172:175], v[208:211], v[12:15]
	v_mfma_f32_16x16x32_bf16 v[8:11], v[184:187], v[208:211], v[8:11]
	v_mfma_f32_16x16x32_bf16 v[4:7], v[172:175], v[216:219], v[4:7]
	v_mfma_f32_16x16x32_bf16 v[0:3], v[184:187], v[216:219], v[0:3]
	s_waitcnt vmcnt(8)
	s_barrier
	s_branch .Lgemm_join_697
.LBB0_697:
	s_add_u32 s77, s44, s50
	s_addc_u32 s78, s45, s51
	s_add_u32 s79, s77, 0x100
	s_addc_u32 s80, s78, 0
	s_and_b64 s[42:43], s[48:49], exec
	s_cselect_b32 s95, s4, s80
	s_cselect_b32 s94, s5, s79
	s_add_u32 s42, s40, s50
	s_addc_u32 s43, s41, s51
	s_add_u32 s50, s42, 0x100
	s_addc_u32 s51, s43, 0
	s_add_i32 s93, 0, 0x10000
	s_and_b64 s[42:43], s[48:49], exec
	s_cselect_b32 s51, s31, s51
	s_cselect_b32 s50, s76, s50
	s_add_i32 s42, 0, 0x14000
	v_add_u32_e32 v141, s93, v135
	s_add_u32 vcc_lo, s77, s0
	ds_read_b128 v[152:155], v141
	ds_read_b128 v[156:159], v141 offset:1024
	ds_read_b128 v[160:163], v141 offset:2048
	ds_read_b128 v[164:167], v141 offset:3072
	v_add_u32_e32 v141, s42, v135
	s_addc_u32 vcc_hi, s78, s1
	s_add_i32 s87, s93, s3
	ds_read_b128 v[168:171], v141
	ds_read_b128 v[172:175], v141 offset:1024
	ds_read_b128 v[180:183], v141 offset:2048
	ds_read_b128 v[184:187], v141 offset:3072
	s_add_i32 m0, s16, 0xc000
	s_add_i32 s27, s16, 0xe000
	s_add_i32 s80, s87, 0x2000
	s_add_u32 s96, s50, s10
	s_addc_u32 s97, s51, s11
	s_add_i32 s86, s42, s3
	s_add_i32 s81, s86, 0x2000
	s_add_i32 s79, 0, 0x18000
	s_add_i32 s78, 0, 0x1c000
	s_add_u32 s48, s94, s0
	s_addc_u32 s49, s95, s1
	s_add_i32 s77, s79, s3
	s_add_i32 s93, s78, s3
	s_add_i32 s43, s77, 0x2000
	s_add_i32 s42, s93, 0x2000
	v_lshl_add_u64 v[220:221], vcc, 0, v[132:133]
	v_lshl_add_u64 v[220:221], v[220:221], 0, s[24:25]
	ds_read_b128 v[188:191], v139
	ds_read_b128 v[192:195], v139 offset:1024
	ds_read_b128 v[196:199], v139 offset:2048
	ds_read_b128 v[200:203], v139 offset:3072
	ds_read_b128 v[204:207], v139 offset:4096
	ds_read_b128 v[208:211], v139 offset:5120
	ds_read_b128 v[212:215], v139 offset:6144
	ds_read_b128 v[216:219], v139 offset:7168
	global_load_lds_dwordx4 v[220:221], off
	v_lshl_add_u64 v[220:221], vcc, 0, v[130:131]
	v_lshl_add_u64 v[220:221], v[220:221], 0, s[24:25]
	s_mov_b32 m0, s27
	s_nop 0
	global_load_lds_dwordx4 v[220:221], off
	s_bitcmp1_b32 s101, 0
	s_cbranch_scc0 .Lvw_697_2
	s_waitcnt vmcnt(8)
.Lvw_697_2:
	s_waitcnt lgkmcnt(0)
	s_barrier
	s_waitcnt lgkmcnt(0)
	v_mfma_f32_16x16x32_bf16 v[124:127], v[152:155], v[188:191], v[124:127]
	v_mfma_f32_16x16x32_bf16 v[120:123], v[160:163], v[188:191], v[120:123]
	v_mfma_f32_16x16x32_bf16 v[116:119], v[152:155], v[196:199], v[116:119]
	v_mfma_f32_16x16x32_bf16 v[112:115], v[160:163], v[196:199], v[112:115]
	v_mfma_f32_16x16x32_bf16 v[100:103], v[152:155], v[204:207], v[100:103]
	v_mfma_f32_16x16x32_bf16 v[96:99], v[160:163], v[204:207], v[96:99]
	v_mfma_f32_16x16x32_bf16 v[84:87], v[152:155], v[212:215], v[84:87]
	v_mfma_f32_16x16x32_bf16 v[80:83], v[160:163], v[212:215], v[80:83]
	v_mfma_f32_16x16x32_bf16 v[124:127], v[156:159], v[192:195], v[124:127]
	v_mfma_f32_16x16x32_bf16 v[120:123], v[164:167], v[192:195], v[120:123]
	v_mfma_f32_16x16x32_bf16 v[116:119], v[156:159], v[200:203], v[116:119]
	v_mfma_f32_16x16x32_bf16 v[112:115], v[164:167], v[200:203], v[112:115]
	v_mfma_f32_16x16x32_bf16 v[100:103], v[156:159], v[208:211], v[100:103]
	v_mfma_f32_16x16x32_bf16 v[96:99], v[164:167], v[208:211], v[96:99]
	v_mfma_f32_16x16x32_bf16 v[84:87], v[156:159], v[216:219], v[84:87]
	v_mfma_f32_16x16x32_bf16 v[80:83], v[164:167], v[216:219], v[80:83]
	v_mfma_f32_16x16x32_bf16 v[108:111], v[168:171], v[188:191], v[108:111]
	v_mfma_f32_16x16x32_bf16 v[104:107], v[180:183], v[188:191], v[104:107]
	v_mfma_f32_16x16x32_bf16 v[92:95], v[168:171], v[196:199], v[92:95]
	v_mfma_f32_16x16x32_bf16 v[88:91], v[180:183], v[196:199], v[88:91]
	v_mfma_f32_16x16x32_bf16 v[76:79], v[168:171], v[204:207], v[76:79]
	v_mfma_f32_16x16x32_bf16 v[72:75], v[180:183], v[204:207], v[72:75]
	v_mfma_f32_16x16x32_bf16 v[68:71], v[168:171], v[212:215], v[68:71]
	v_mfma_f32_16x16x32_bf16 v[64:67], v[180:183], v[212:215], v[64:67]
	v_mfma_f32_16x16x32_bf16 v[108:111], v[172:175], v[192:195], v[108:111]
	v_mfma_f32_16x16x32_bf16 v[104:107], v[184:187], v[192:195], v[104:107]
	v_mfma_f32_16x16x32_bf16 v[92:95], v[172:175], v[200:203], v[92:95]
	v_mfma_f32_16x16x32_bf16 v[88:91], v[184:187], v[200:203], v[88:91]
	v_mfma_f32_16x16x32_bf16 v[76:79], v[172:175], v[208:211], v[76:79]
	v_mfma_f32_16x16x32_bf16 v[72:75], v[184:187], v[208:211], v[72:75]
	v_mfma_f32_16x16x32_bf16 v[68:71], v[172:175], v[216:219], v[68:71]
	v_mfma_f32_16x16x32_bf16 v[64:67], v[184:187], v[216:219], v[64:67]
	s_waitcnt vmcnt(8)
	s_barrier
; #define PG8_STAGE(bufoff, gbase, voff) do { _Pragma("unroll") for (int _i = 0; _i < 2; ++_i) \
;         __builtin_amdgcn_global_load_lds((const unsigned*)((const char*)(gbase) + (voff)[_i]), (LAS unsigned*)(lds + (bufoff) + ldsw + _i * 8192), 16, 0, 0); } while (0)
; #define PG8_LDA(dst, b, h) do { _Pragma("unroll") for (int m = 0; m < 4; ++m) _Pragma("unroll") for (int k = 0; k < 2; ++k) dst[m][k] = *(const LAS bf16x8*)(lds + PG8_SA(b, h) + aoff + m * 2048 + k * 1024); } while (0)
; #define PG8_LDB(dst, b, h) do { _Pragma("unroll") for (int n = 0; n < 2; ++n) _Pragma("unroll") for (int k = 0; k < 2; ++k) dst[n][k] = *(const LAS bf16x8*)(lds + PG8_SB(b, h) + boff + n * 2048 + k * 1024); } while (0)
; #define PG8_MMA(ai, bj, At, Bt) do { __builtin_amdgcn_s_setprio(1); _Pragma("unroll") for (int m = 0; m < 4; ++m) _Pragma("unroll") for (int n = 0; n < 2; ++n) _Pragma("unroll") for (int k = 0; k < 2; ++k) \
;         acc[ai][bj][m][n] = __builtin_amdgcn_mfma_f32_16x16x32_bf16(Bt[n][k], At[m][k], acc[ai][bj][m][n], 0, 0, 0); __builtin_amdgcn_s_setprio(0); } while (0)
; #define PG8_WAIT_V(n) asm volatile("s_waitcnt vmcnt(" #n ")" ::: "memory")
; #define PG8_WAIT_L(n) asm volatile("s_waitcnt lgkmcnt(" #n ")" ::: "memory")
; #define PG8_BAR __builtin_amdgcn_s_barrier()
; #define PG8_SCHED __builtin_amdgcn_sched_barrier(0)
; template <class Epi, class Sched, bool ALIGN_EPI>
; __device__ __forceinline__ void gemm_phase(LAS unsigned char* lds, const int wid, const int lda_, const int ldb_, const int K_, const Sched& S, const Epi& E) {
;     ...
;             PG8_LDA(At, 0, 1); PG8_STAGE(PG8_SB(0, 0), b2, voffB); PG8_STAGE(PG8_SB(0, 1), b2 + hstepB, voffB); PG8_STAGE(PG8_SA(0, 0), a2, voffA);
;             PG8_WAIT_V(8); PG8_WAIT_L(0); PG8_BAR; PG8_MMA(1, 0, At, B0); PG8_MMA(1, 1, At, B1); PG8_BAR; PG8_SCHED;
;             PG8_LDB(B0, 1, 0); PG8_LDB(B1, 1, 1); PG8_SCHED; PG8_LDA(At, 1, 0); PG8_STAGE(PG8_SA(0, 1), a2 + hstepA, voffA);
;             PG8_WAIT_V(8); PG8_WAIT_L(0); PG8_BAR; PG8_MMA(0, 0, At, B0); PG8_MMA(0, 1, At, B1); PG8_BAR; PG8_SCHED;
	s_mov_b32 m0, s87
	v_lshl_add_u64 v[220:221], s[50:51], 0, v[176:177]
	ds_read_b128 v[188:191], v139 offset:16384
	ds_read_b128 v[192:195], v139 offset:17408
	ds_read_b128 v[196:199], v139 offset:18432
	ds_read_b128 v[200:203], v139 offset:19456
	ds_read_b128 v[204:207], v139 offset:20480
	ds_read_b128 v[208:211], v139 offset:21504
	ds_read_b128 v[212:215], v139 offset:22528
	ds_read_b128 v[216:219], v139 offset:23552
	global_load_lds_dwordx4 v[220:221], off
	v_lshl_add_u64 v[222:223], s[50:51], 0, v[128:129]
	s_mov_b32 m0, s80
	v_lshl_add_u64 v[224:225], s[96:97], 0, v[176:177]
	global_load_lds_dwordx4 v[222:223], off
	s_mov_b32 m0, s86
	v_lshl_add_u64 v[226:227], s[96:97], 0, v[128:129]
	global_load_lds_dwordx4 v[224:225], off
	s_mov_b32 m0, s81
	v_lshl_add_u64 v[228:229], s[94:95], 0, v[132:133]
	global_load_lds_dwordx4 v[226:227], off
	s_mov_b32 m0, s16
	v_lshl_add_u64 v[230:231], s[94:95], 0, v[130:131]
	global_load_lds_dwordx4 v[228:229], off
	s_mov_b32 m0, s6
	s_nop 0
	global_load_lds_dwordx4 v[230:231], off
	s_bitcmp1_b32 s101, 0
	s_cbranch_scc0 .Lvw_697_3
	s_waitcnt vmcnt(8)
.Lvw_697_3:
	s_waitcnt lgkmcnt(0)
	s_barrier
	s_waitcnt lgkmcnt(0)
	v_mfma_f32_16x16x32_bf16 v[60:63], v[152:155], v[188:191], v[60:63]
	v_mfma_f32_16x16x32_bf16 v[56:59], v[160:163], v[188:191], v[56:59]
	v_mfma_f32_16x16x32_bf16 v[52:55], v[152:155], v[196:199], v[52:55]
	v_mfma_f32_16x16x32_bf16 v[48:51], v[160:163], v[196:199], v[48:51]
	v_mfma_f32_16x16x32_bf16 v[36:39], v[152:155], v[204:207], v[36:39]
	v_mfma_f32_16x16x32_bf16 v[32:35], v[160:163], v[204:207], v[32:35]
	v_mfma_f32_16x16x32_bf16 v[20:23], v[152:155], v[212:215], v[20:23]
	v_mfma_f32_16x16x32_bf16 v[16:19], v[160:163], v[212:215], v[16:19]
	v_mfma_f32_16x16x32_bf16 v[60:63], v[156:159], v[192:195], v[60:63]
	v_mfma_f32_16x16x32_bf16 v[56:59], v[164:167], v[192:195], v[56:59]
	v_mfma_f32_16x16x32_bf16 v[52:55], v[156:159], v[200:203], v[52:55]
	v_mfma_f32_16x16x32_bf16 v[48:51], v[164:167], v[200:203], v[48:51]
	v_mfma_f32_16x16x32_bf16 v[36:39], v[156:159], v[208:211], v[36:39]
	v_mfma_f32_16x16x32_bf16 v[32:35], v[164:167], v[208:211], v[32:35]
	v_mfma_f32_16x16x32_bf16 v[20:23], v[156:159], v[216:219], v[20:23]
	v_mfma_f32_16x16x32_bf16 v[16:19], v[164:167], v[216:219], v[16:19]
	v_mfma_f32_16x16x32_bf16 v[44:47], v[168:171], v[188:191], v[44:47]
	v_mfma_f32_16x16x32_bf16 v[40:43], v[180:183], v[188:191], v[40:43]
	v_mfma_f32_16x16x32_bf16 v[28:31], v[168:171], v[196:199], v[28:31]
	v_mfma_f32_16x16x32_bf16 v[24:27], v[180:183], v[196:199], v[24:27]
	v_mfma_f32_16x16x32_bf16 v[12:15], v[168:171], v[204:207], v[12:15]
	v_mfma_f32_16x16x32_bf16 v[8:11], v[180:183], v[204:207], v[8:11]
	v_mfma_f32_16x16x32_bf16 v[4:7], v[168:171], v[212:215], v[4:7]
	v_mfma_f32_16x16x32_bf16 v[0:3], v[180:183], v[212:215], v[0:3]
	v_mfma_f32_16x16x32_bf16 v[44:47], v[172:175], v[192:195], v[44:47]
	v_mfma_f32_16x16x32_bf16 v[40:43], v[184:187], v[192:195], v[40:43]
	v_mfma_f32_16x16x32_bf16 v[28:31], v[172:175], v[200:203], v[28:31]
	v_mfma_f32_16x16x32_bf16 v[24:27], v[184:187], v[200:203], v[24:27]
	v_mfma_f32_16x16x32_bf16 v[12:15], v[172:175], v[208:211], v[12:15]
	v_mfma_f32_16x16x32_bf16 v[8:11], v[184:187], v[208:211], v[8:11]
	v_mfma_f32_16x16x32_bf16 v[4:7], v[172:175], v[216:219], v[4:7]
	v_mfma_f32_16x16x32_bf16 v[0:3], v[184:187], v[216:219], v[0:3]
	s_waitcnt vmcnt(8)
	s_barrier
.Lgemm_join_697:
	v_add_u32_e32 v141, s79, v135
	ds_read_b128 v[152:155], v141
	ds_read_b128 v[156:159], v141 offset:1024
	ds_read_b128 v[160:163], v141 offset:2048
	ds_read_b128 v[164:167], v141 offset:3072
	v_add_u32_e32 v141, s78, v135
	ds_read_b128 v[168:171], v141
	ds_read_b128 v[172:175], v141 offset:1024
	ds_read_b128 v[180:183], v141 offset:2048
	ds_read_b128 v[184:187], v141 offset:3072
	s_mov_b32 m0, s7
	v_lshl_add_u64 v[232:233], s[48:49], 0, v[132:133]
	ds_read_b128 v[188:191], v139 offset:32768
	ds_read_b128 v[192:195], v139 offset:33792
	ds_read_b128 v[196:199], v139 offset:34816
	ds_read_b128 v[200:203], v139 offset:35840
	ds_read_b128 v[204:207], v139 offset:36864
	ds_read_b128 v[208:211], v139 offset:37888
	ds_read_b128 v[212:215], v139 offset:38912
	ds_read_b128 v[216:219], v139 offset:39936
	global_load_lds_dwordx4 v[232:233], off
	v_lshl_add_u64 v[232:233], s[48:49], 0, v[130:131]
	s_mov_b32 m0, s14
	s_nop 0
	global_load_lds_dwordx4 v[232:233], off
	s_bitcmp1_b32 s101, 0
	s_cbranch_scc0 .Lvw_697_4
	s_waitcnt vmcnt(8)
; #define PG8_STAGE(bufoff, gbase, voff) do { _Pragma("unroll") for (int _i = 0; _i < 2; ++_i) \
;         __builtin_amdgcn_global_load_lds((const unsigned*)((const char*)(gbase) + (voff)[_i]), (LAS unsigned*)(lds + (bufoff) + ldsw + _i * 8192), 16, 0, 0); } while (0)
; #define PG8_LDA(dst, b, h) do { _Pragma("unroll") for (int m = 0; m < 4; ++m) _Pragma("unroll") for (int k = 0; k < 2; ++k) dst[m][k] = *(const LAS bf16x8*)(lds + PG8_SA(b, h) + aoff + m * 2048 + k * 1024); } while (0)
; #define PG8_LDB(dst, b, h) do { _Pragma("unroll") for (int n = 0; n < 2; ++n) _Pragma("unroll") for (int k = 0; k < 2; ++k) dst[n][k] = *(const LAS bf16x8*)(lds + PG8_SB(b, h) + boff + n * 2048 + k * 1024); } while (0)
; #define PG8_MMA(ai, bj, At, Bt) do { __builtin_amdgcn_s_setprio(1); _Pragma("unroll") for (int m = 0; m < 4; ++m) _Pragma("unroll") for (int n = 0; n < 2; ++n) _Pragma("unroll") for (int k = 0; k < 2; ++k) \
;         acc[ai][bj][m][n] = __builtin_amdgcn_mfma_f32_16x16x32_bf16(Bt[n][k], At[m][k], acc[ai][bj][m][n], 0, 0, 0); __builtin_amdgcn_s_setprio(0); } while (0)
; #define PG8_WAIT_V(n) asm volatile("s_waitcnt vmcnt(" #n ")" ::: "memory")
; #define PG8_BAR __builtin_amdgcn_s_barrier()
; template <class Epi, class Sched, bool ALIGN_EPI>
; __device__ __forceinline__ void gemm_phase(LAS unsigned char* lds, const int wid, const int lda_, const int ldb_, const int K_, const Sched& S, const Epi& E) {
;     ...
;             PG8_WAIT_V(8); PG8_WAIT_L(0); PG8_BAR; PG8_MMA(1, 0, At, B0); PG8_MMA(1, 1, At, B1); PG8_BAR; PG8_SCHED;
;             PG8_LDB(B0, 1, 0); PG8_LDB(B1, 1, 1); PG8_SCHED; PG8_LDA(At, 1, 0); PG8_STAGE(PG8_SA(0, 1), a2 + hstepA, voffA);
;             PG8_WAIT_V(8); PG8_WAIT_L(0); PG8_BAR; PG8_MMA(0, 0, At, B0); PG8_MMA(0, 1, At, B1); PG8_BAR; PG8_SCHED;
;             PG8_LDA(At, 1, 1); PG8_STAGE(PG8_SB(1, 0), b3, voffB); PG8_STAGE(PG8_SB(1, 1), b3 + hstepB, voffB); PG8_STAGE(PG8_SA(1, 0), a3, voffA);
;             PG8_WAIT_V(8); PG8_WAIT_L(0); PG8_BAR; PG8_MMA(1, 0, At, B0); PG8_MMA(1, 1, At, B1); PG8_BAR; PG8_SCHED;
;     __device__ __forceinline__ void out(const pg8::Unit& u, char*& o, int& ldo, int& kind) const { const int g = u.pm >> 1, cs = u.pm & 1;
;         if (u.pn < 64) { const int b = u.pn >> 3, p0 = (u.pn & 7) * 256; o = (char*)ws + WS_PQT + (((size_t)(b * 2048 + g * 256)) * 4096 + (size_t)cs * 2048 + p0) * 2; ldo = 4096; }
.Lvw_697_4:
	s_waitcnt lgkmcnt(0)
	s_barrier
	s_waitcnt lgkmcnt(0)
	v_mfma_f32_16x16x32_bf16 v[124:127], v[152:155], v[188:191], v[124:127]
	v_mfma_f32_16x16x32_bf16 v[120:123], v[160:163], v[188:191], v[120:123]
	v_mfma_f32_16x16x32_bf16 v[116:119], v[152:155], v[196:199], v[116:119]
	v_mfma_f32_16x16x32_bf16 v[112:115], v[160:163], v[196:199], v[112:115]
	v_mfma_f32_16x16x32_bf16 v[100:103], v[152:155], v[204:207], v[100:103]
	v_mfma_f32_16x16x32_bf16 v[96:99], v[160:163], v[204:207], v[96:99]
	v_mfma_f32_16x16x32_bf16 v[84:87], v[152:155], v[212:215], v[84:87]
	v_mfma_f32_16x16x32_bf16 v[80:83], v[160:163], v[212:215], v[80:83]
	v_mfma_f32_16x16x32_bf16 v[124:127], v[156:159], v[192:195], v[124:127]
	v_mfma_f32_16x16x32_bf16 v[120:123], v[164:167], v[192:195], v[120:123]
	v_mfma_f32_16x16x32_bf16 v[116:119], v[156:159], v[200:203], v[116:119]
	v_mfma_f32_16x16x32_bf16 v[112:115], v[164:167], v[200:203], v[112:115]
	v_mfma_f32_16x16x32_bf16 v[100:103], v[156:159], v[208:211], v[100:103]
	v_mfma_f32_16x16x32_bf16 v[96:99], v[164:167], v[208:211], v[96:99]
	v_mfma_f32_16x16x32_bf16 v[84:87], v[156:159], v[216:219], v[84:87]
	v_mfma_f32_16x16x32_bf16 v[80:83], v[164:167], v[216:219], v[80:83]
	v_mfma_f32_16x16x32_bf16 v[108:111], v[168:171], v[188:191], v[108:111]
	v_mfma_f32_16x16x32_bf16 v[104:107], v[180:183], v[188:191], v[104:107]
	v_mfma_f32_16x16x32_bf16 v[92:95], v[168:171], v[196:199], v[92:95]
	v_mfma_f32_16x16x32_bf16 v[88:91], v[180:183], v[196:199], v[88:91]
	v_mfma_f32_16x16x32_bf16 v[76:79], v[168:171], v[204:207], v[76:79]
	v_mfma_f32_16x16x32_bf16 v[72:75], v[180:183], v[204:207], v[72:75]
	v_mfma_f32_16x16x32_bf16 v[68:71], v[168:171], v[212:215], v[68:71]
	v_mfma_f32_16x16x32_bf16 v[64:67], v[180:183], v[212:215], v[64:67]
	v_mfma_f32_16x16x32_bf16 v[108:111], v[172:175], v[192:195], v[108:111]
	v_mfma_f32_16x16x32_bf16 v[104:107], v[184:187], v[192:195], v[104:107]
	v_mfma_f32_16x16x32_bf16 v[92:95], v[172:175], v[200:203], v[92:95]
	v_mfma_f32_16x16x32_bf16 v[88:91], v[184:187], v[200:203], v[88:91]
	v_mfma_f32_16x16x32_bf16 v[76:79], v[172:175], v[208:211], v[76:79]
	v_mfma_f32_16x16x32_bf16 v[72:75], v[184:187], v[208:211], v[72:75]
	v_mfma_f32_16x16x32_bf16 v[68:71], v[172:175], v[216:219], v[68:71]
	v_mfma_f32_16x16x32_bf16 v[64:67], v[184:187], v[216:219], v[64:67]
	s_waitcnt vmcnt(8)
	s_barrier
	s_mov_b32 m0, s77
	v_lshl_add_u64 v[220:221], v[220:221], 0, s[24:25]
	ds_read_b128 v[188:191], v139 offset:49152
	ds_read_b128 v[192:195], v139 offset:50176
	ds_read_b128 v[196:199], v139 offset:51200
	ds_read_b128 v[200:203], v139 offset:52224
	ds_read_b128 v[204:207], v139 offset:53248
	ds_read_b128 v[208:211], v139 offset:54272
	ds_read_b128 v[212:215], v139 offset:55296
	ds_read_b128 v[216:219], v139 offset:56320
	global_load_lds_dwordx4 v[220:221], off
	v_lshl_add_u64 v[220:221], v[222:223], 0, s[24:25]
	s_mov_b32 m0, s43
	s_nop 0
	global_load_lds_dwordx4 v[220:221], off
	v_lshl_add_u64 v[220:221], v[224:225], 0, s[24:25]
	s_mov_b32 m0, s93
	s_nop 0
	global_load_lds_dwordx4 v[220:221], off
	v_lshl_add_u64 v[220:221], v[226:227], 0, s[24:25]
	s_mov_b32 m0, s42
	s_nop 0
	global_load_lds_dwordx4 v[220:221], off
	v_lshl_add_u64 v[220:221], v[228:229], 0, s[24:25]
	s_mov_b32 m0, s15
	s_nop 0
	global_load_lds_dwordx4 v[220:221], off
	v_lshl_add_u64 v[220:221], v[230:231], 0, s[24:25]
	s_mov_b32 m0, s26
	s_nop 0
	global_load_lds_dwordx4 v[220:221], off
	s_bitcmp1_b32 s101, 0
	s_cbranch_scc0 .Lvw_697_5
	s_waitcnt vmcnt(8)
.Lvw_697_5:
	s_waitcnt lgkmcnt(0)
	s_barrier
	s_waitcnt lgkmcnt(0)
	v_mfma_f32_16x16x32_bf16 v[60:63], v[152:155], v[188:191], v[60:63]
	v_mfma_f32_16x16x32_bf16 v[56:59], v[160:163], v[188:191], v[56:59]
	v_mfma_f32_16x16x32_bf16 v[52:55], v[152:155], v[196:199], v[52:55]
	v_mfma_f32_16x16x32_bf16 v[48:51], v[160:163], v[196:199], v[48:51]
	v_mfma_f32_16x16x32_bf16 v[36:39], v[152:155], v[204:207], v[36:39]
	v_mfma_f32_16x16x32_bf16 v[32:35], v[160:163], v[204:207], v[32:35]
	v_mfma_f32_16x16x32_bf16 v[20:23], v[152:155], v[212:215], v[20:23]
	v_mfma_f32_16x16x32_bf16 v[16:19], v[160:163], v[212:215], v[16:19]
	v_mfma_f32_16x16x32_bf16 v[60:63], v[156:159], v[192:195], v[60:63]
	v_mfma_f32_16x16x32_bf16 v[56:59], v[164:167], v[192:195], v[56:59]
	v_mfma_f32_16x16x32_bf16 v[52:55], v[156:159], v[200:203], v[52:55]
	v_mfma_f32_16x16x32_bf16 v[48:51], v[164:167], v[200:203], v[48:51]
	v_mfma_f32_16x16x32_bf16 v[36:39], v[156:159], v[208:211], v[36:39]
	v_mfma_f32_16x16x32_bf16 v[32:35], v[164:167], v[208:211], v[32:35]
	v_mfma_f32_16x16x32_bf16 v[20:23], v[156:159], v[216:219], v[20:23]
	v_mfma_f32_16x16x32_bf16 v[16:19], v[164:167], v[216:219], v[16:19]
	v_mfma_f32_16x16x32_bf16 v[44:47], v[168:171], v[188:191], v[44:47]
	v_mfma_f32_16x16x32_bf16 v[40:43], v[180:183], v[188:191], v[40:43]
	v_mfma_f32_16x16x32_bf16 v[28:31], v[168:171], v[196:199], v[28:31]
	v_mfma_f32_16x16x32_bf16 v[24:27], v[180:183], v[196:199], v[24:27]
	v_mfma_f32_16x16x32_bf16 v[12:15], v[168:171], v[204:207], v[12:15]
	v_mfma_f32_16x16x32_bf16 v[8:11], v[180:183], v[204:207], v[8:11]
	v_mfma_f32_16x16x32_bf16 v[4:7], v[168:171], v[212:215], v[4:7]
	v_mfma_f32_16x16x32_bf16 v[0:3], v[180:183], v[212:215], v[0:3]
	v_mfma_f32_16x16x32_bf16 v[44:47], v[172:175], v[192:195], v[44:47]
	v_mfma_f32_16x16x32_bf16 v[40:43], v[184:187], v[192:195], v[40:43]
	v_mfma_f32_16x16x32_bf16 v[28:31], v[172:175], v[200:203], v[28:31]
	v_mfma_f32_16x16x32_bf16 v[24:27], v[184:187], v[200:203], v[24:27]
	v_mfma_f32_16x16x32_bf16 v[12:15], v[172:175], v[208:211], v[12:15]
	v_mfma_f32_16x16x32_bf16 v[8:11], v[184:187], v[208:211], v[8:11]
	v_mfma_f32_16x16x32_bf16 v[4:7], v[172:175], v[216:219], v[4:7]
	v_mfma_f32_16x16x32_bf16 v[0:3], v[184:187], v[216:219], v[0:3]
	s_waitcnt vmcnt(8)
	s_barrier
	s_andn2_b64 vcc, exec, s[46:47]
	s_mov_b64 s[48:49], -1
	s_mov_b64 s[46:47], 0
	s_mov_b64 s[50:51], 0x100
	s_cbranch_vccz .LBB0_697
	s_setprio 2
	s_ashr_i32 s43, s75, 1
	s_and_b32 s42, s75, 1
	s_cmp_gt_i32 s74, 63
	s_mov_b64 s[40:41], -1
	s_cbranch_scc0 .LBB0_700
	s_lshl_b32 s4, s74, 11
	s_lshl_b32 s5, s43, 8
	s_add_i32 s4, s4, s5
	s_add_i32 s4, s4, 0xfffe0000
	s_ashr_i32 s5, s4, 31
	s_lshl_b32 s31, s42, 9
	s_lshl_b64 s[4:5], s[4:5], 10
	v_readlane_b32 s17, v254, 2
	s_add_u32 s4, s17, s4
	v_readlane_b32 s17, v254, 3
	s_addc_u32 s5, s17, s5
	s_add_u32 s4, s4, s31
	s_addc_u32 s5, s5, 0
	s_mov_b64 s[40:41], 0

; #define PG8_STAGE(bufoff, gbase, voff) do { _Pragma("unroll") for (int _i = 0; _i < 2; ++_i) \
;         __builtin_amdgcn_global_load_lds((const unsigned*)((const char*)(gbase) + (voff)[_i]), (LAS unsigned*)(lds + (bufoff) + ldsw + _i * 8192), 16, 0, 0); } while (0)
; #define PG8_LDA(dst, b, h) do { _Pragma("unroll") for (int m = 0; m < 4; ++m) _Pragma("unroll") for (int k = 0; k < 2; ++k) dst[m][k] = *(const LAS bf16x8*)(lds + PG8_SA(b, h) + aoff + m * 2048 + k * 1024); } while (0)
; #define PG8_LDB(dst, b, h) do { _Pragma("unroll") for (int n = 0; n < 2; ++n) _Pragma("unroll") for (int k = 0; k < 2; ++k) dst[n][k] = *(const LAS bf16x8*)(lds + PG8_SB(b, h) + boff + n * 2048 + k * 1024); } while (0)
; #define PG8_MMA(ai, bj, At, Bt) do { __builtin_amdgcn_s_setprio(1); _Pragma("unroll") for (int m = 0; m < 4; ++m) _Pragma("unroll") for (int n = 0; n < 2; ++n) _Pragma("unroll") for (int k = 0; k < 2; ++k) \
;         acc[ai][bj][m][n] = __builtin_amdgcn_mfma_f32_16x16x32_bf16(Bt[n][k], At[m][k], acc[ai][bj][m][n], 0, 0, 0); __builtin_amdgcn_s_setprio(0); } while (0)
; template <class Epi, class Sched, bool ALIGN_EPI>
; __device__ __forceinline__ void gemm_phase(LAS unsigned char* lds, const int wid, const int lda_, const int ldb_, const int K_, const Sched& S, const Epi& E) {
;     ...
;         const bool has_next = S.next(ui + 1, nxt);
;         const int nt = S.nt(cur);
;         const char* nA = has_next ? S.a(nxt) : cA; const char* nB = has_next ? S.b(nxt) : cB;
; #pragma unroll 1
;         for (int t = 0; t < nt; t += 2) {
;             const bool last = (t == nt - 2);
;             const char* a1 = cA + (size_t)(t + 1) * kstep;
;             const char* a2 = last ? nA : cA + (size_t)(t + 2) * kstep; const char* b2 = last ? nB : cB + (size_t)(t + 2) * kstep;
;             const char* a3 = a2 + kstep; const char* b3 = b2 + kstep;
;             PG8_LDB(B0, 0, 0); PG8_LDB(B1, 0, 1); PG8_SCHED; PG8_LDA(At, 0, 0); PG8_STAGE(PG8_SA(1, 1), a1 + hstepA, voffA);
;             PG8_WAIT_V(8); PG8_WAIT_L(0); PG8_BAR; PG8_MMA(0, 0, At, B0); PG8_MMA(0, 1, At, B1); PG8_BAR; PG8_SCHED;
;             PG8_LDA(At, 0, 1); PG8_STAGE(PG8_SB(0, 0), b2, voffB); PG8_STAGE(PG8_SB(0, 1), b2 + hstepB, voffB); PG8_STAGE(PG8_SA(0, 0), a2, voffA);
;             PG8_WAIT_V(8); PG8_WAIT_L(0); PG8_BAR; PG8_MMA(1, 0, At, B0); PG8_MMA(1, 1, At, B1); PG8_BAR; PG8_SCHED;
.LBB0_882:
	s_and_b64 s[4:5], s[4:5], exec
	s_cselect_b32 s4, s27, 0x380000
	s_add_u32 s44, s66, s4
	s_addc_u32 s45, s67, 0
	s_and_b64 s[4:5], s[50:51], exec
	s_cselect_b32 s4, s45, s47
	s_cselect_b32 s5, s44, s46
	s_add_u32 s42, s46, 0x80
	s_addc_u32 s43, s47, 0
	s_add_u32 s31, s48, 0x100
	v_lshl_add_u64 v[156:157], s[42:43], 0, v[152:153]
	v_lshl_add_u64 v[158:159], s[42:43], 0, v[154:155]
	s_addc_u32 s35, s49, 0
	s_mov_b32 s73, -2
	s_mov_b64 s[48:49], 0
	s_add_u32 s17, s46, s48
	s_addc_u32 s27, s47, s49
	s_add_u32 s17, s17, 0x100
	s_addc_u32 s27, s27, 0
	s_add_u32 s42, s31, s48
	s_addc_u32 s43, s35, s49
	s_add_i32 s74, 0, 0x10000
	s_cmpk_eq_i32 s48, 0x300
	s_cselect_b32 s51, s4, s27
	s_cselect_b32 s50, s5, s17
	v_add_u32_e32 v141, s74, v135
	s_cselect_b32 s43, s39, s43
	s_cselect_b32 s42, s38, s42
	s_add_i32 s17, 0, 0x14000
	ds_read_b128 v[160:163], v141
	ds_read_b128 v[164:167], v141 offset:1024
	ds_read_b128 v[168:171], v141 offset:2048
	ds_read_b128 v[172:175], v141 offset:3072
	v_add_u32_e32 v141, s17, v135
	ds_read_b128 v[180:183], v141
	ds_read_b128 v[184:187], v141 offset:1024
	ds_read_b128 v[188:191], v141 offset:2048
	ds_read_b128 v[192:195], v141 offset:3072
	v_lshl_add_u64 v[228:229], v[158:159], 0, s[48:49]
	s_add_i32 m0, s16, 0xc000
	ds_read_b128 v[196:199], v139
	ds_read_b128 v[200:203], v139 offset:1024
	ds_read_b128 v[204:207], v139 offset:2048
	ds_read_b128 v[208:211], v139 offset:3072
	ds_read_b128 v[212:215], v139 offset:4096
	ds_read_b128 v[216:219], v139 offset:5120
	ds_read_b128 v[220:223], v139 offset:6144
	ds_read_b128 v[224:227], v139 offset:7168
	global_load_lds_dwordx4 v[228:229], off
	v_lshl_add_u64 v[228:229], v[156:157], 0, s[48:49]
	s_add_i32 m0, s16, 0xe000
	s_nop 0
	global_load_lds_dwordx4 v[228:229], off
	v_readlane_b32 s101, v252, 58
	s_nop 3
	s_bitcmp1_b32 s101, 0
	s_cbranch_scc0 .Lvw_883_0
	s_waitcnt vmcnt(8)
.Lvw_883_0:
	s_waitcnt lgkmcnt(0)
	s_barrier
	s_setprio 0
	s_waitcnt lgkmcnt(0)
	v_mfma_f32_16x16x32_bf16 v[124:127], v[160:163], v[196:199], 0
	v_mfma_f32_16x16x32_bf16 v[120:123], v[168:171], v[196:199], 0
	v_mfma_f32_16x16x32_bf16 v[116:119], v[160:163], v[204:207], 0
	v_mfma_f32_16x16x32_bf16 v[112:115], v[168:171], v[204:207], 0
	v_mfma_f32_16x16x32_bf16 v[100:103], v[160:163], v[212:215], 0
	v_mfma_f32_16x16x32_bf16 v[96:99], v[168:171], v[212:215], 0
	v_mfma_f32_16x16x32_bf16 v[84:87], v[160:163], v[220:223], 0
	v_mfma_f32_16x16x32_bf16 v[80:83], v[168:171], v[220:223], 0
	v_mfma_f32_16x16x32_bf16 v[124:127], v[164:167], v[200:203], v[124:127]
	v_mfma_f32_16x16x32_bf16 v[120:123], v[172:175], v[200:203], v[120:123]
	v_mfma_f32_16x16x32_bf16 v[116:119], v[164:167], v[208:211], v[116:119]
	v_mfma_f32_16x16x32_bf16 v[112:115], v[172:175], v[208:211], v[112:115]
	v_mfma_f32_16x16x32_bf16 v[100:103], v[164:167], v[216:219], v[100:103]
	v_mfma_f32_16x16x32_bf16 v[96:99], v[172:175], v[216:219], v[96:99]
	v_mfma_f32_16x16x32_bf16 v[84:87], v[164:167], v[224:227], v[84:87]
	v_mfma_f32_16x16x32_bf16 v[80:83], v[172:175], v[224:227], v[80:83]
	v_mfma_f32_16x16x32_bf16 v[108:111], v[180:183], v[196:199], 0
	v_mfma_f32_16x16x32_bf16 v[104:107], v[188:191], v[196:199], 0
	v_mfma_f32_16x16x32_bf16 v[92:95], v[180:183], v[204:207], 0
	v_mfma_f32_16x16x32_bf16 v[88:91], v[188:191], v[204:207], 0
	v_mfma_f32_16x16x32_bf16 v[76:79], v[180:183], v[212:215], 0
	v_mfma_f32_16x16x32_bf16 v[72:75], v[188:191], v[212:215], 0
	v_mfma_f32_16x16x32_bf16 v[68:71], v[180:183], v[220:223], 0
	v_mfma_f32_16x16x32_bf16 v[64:67], v[188:191], v[220:223], 0
	v_mfma_f32_16x16x32_bf16 v[108:111], v[184:187], v[200:203], v[108:111]
	v_mfma_f32_16x16x32_bf16 v[104:107], v[192:195], v[200:203], v[104:107]
	v_mfma_f32_16x16x32_bf16 v[92:95], v[184:187], v[208:211], v[92:95]
	v_mfma_f32_16x16x32_bf16 v[88:91], v[192:195], v[208:211], v[88:91]
	v_mfma_f32_16x16x32_bf16 v[76:79], v[184:187], v[216:219], v[76:79]
	v_mfma_f32_16x16x32_bf16 v[72:75], v[192:195], v[216:219], v[72:75]
	v_mfma_f32_16x16x32_bf16 v[68:71], v[184:187], v[224:227], v[68:71]
	v_mfma_f32_16x16x32_bf16 v[64:67], v[192:195], v[224:227], v[64:67]
	s_waitcnt vmcnt(8)
	s_barrier
	s_add_i32 s27, s74, s3
	v_lshl_add_u64 v[228:229], s[42:43], 0, v[176:177]
	s_mov_b32 m0, s27
	ds_read_b128 v[196:199], v139 offset:16384
	ds_read_b128 v[200:203], v139 offset:17408
	ds_read_b128 v[204:207], v139 offset:18432
	ds_read_b128 v[208:211], v139 offset:19456
	ds_read_b128 v[212:215], v139 offset:20480
	ds_read_b128 v[216:219], v139 offset:21504
	ds_read_b128 v[220:223], v139 offset:22528
	ds_read_b128 v[224:227], v139 offset:23552
	global_load_lds_dwordx4 v[228:229], off
	s_add_i32 m0, s27, 0x2000
	v_lshl_add_u64 v[230:231], s[42:43], 0, v[132:133]
	s_add_u32 s42, s42, s10
	s_addc_u32 s43, s43, s11
	s_add_i32 s17, s17, s3
	global_load_lds_dwordx4 v[230:231], off
	v_lshl_add_u64 v[232:233], s[42:43], 0, v[176:177]
	s_mov_b32 m0, s17
	v_lshl_add_u64 v[234:235], s[42:43], 0, v[132:133]
	global_load_lds_dwordx4 v[232:233], off
	s_add_i32 m0, s17, 0x2000
	v_lshl_add_u64 v[236:237], s[50:51], 0, v[128:129]
	global_load_lds_dwordx4 v[234:235], off
	s_mov_b32 m0, s16
	v_lshl_add_u64 v[246:247], s[50:51], 0, v[130:131]
	global_load_lds_dwordx4 v[236:237], off
	s_mov_b32 m0, s6
	s_nop 0
	global_load_lds_dwordx4 v[246:247], off
	s_bitcmp1_b32 s101, 0
	s_cbranch_scc0 .Lvw_883_1
	s_waitcnt vmcnt(8)

; #define PG8_STAGE(bufoff, gbase, voff) do { _Pragma("unroll") for (int _i = 0; _i < 2; ++_i) \
;         __builtin_amdgcn_global_load_lds((const unsigned*)((const char*)(gbase) + (voff)[_i]), (LAS unsigned*)(lds + (bufoff) + ldsw + _i * 8192), 16, 0, 0); } while (0)
; #define PG8_LDA(dst, b, h) do { _Pragma("unroll") for (int m = 0; m < 4; ++m) _Pragma("unroll") for (int k = 0; k < 2; ++k) dst[m][k] = *(const LAS bf16x8*)(lds + PG8_SA(b, h) + aoff + m * 2048 + k * 1024); } while (0)
; #define PG8_LDB(dst, b, h) do { _Pragma("unroll") for (int n = 0; n < 2; ++n) _Pragma("unroll") for (int k = 0; k < 2; ++k) dst[n][k] = *(const LAS bf16x8*)(lds + PG8_SB(b, h) + boff + n * 2048 + k * 1024); } while (0)
; #define PG8_MMA(ai, bj, At, Bt) do { __builtin_amdgcn_s_setprio(1); _Pragma("unroll") for (int m = 0; m < 4; ++m) _Pragma("unroll") for (int n = 0; n < 2; ++n) _Pragma("unroll") for (int k = 0; k < 2; ++k) \
;         acc[ai][bj][m][n] = __builtin_amdgcn_mfma_f32_16x16x32_bf16(Bt[n][k], At[m][k], acc[ai][bj][m][n], 0, 0, 0); __builtin_amdgcn_s_setprio(0); } while (0)
; #define PG8_WAIT_V(n) asm volatile("s_waitcnt vmcnt(" #n ")" ::: "memory")
; #define PG8_WAIT_L(n) asm volatile("s_waitcnt lgkmcnt(" #n ")" ::: "memory")
; #define PG8_BAR __builtin_amdgcn_s_barrier()
; #define PG8_SCHED __builtin_amdgcn_sched_barrier(0)
; template <class Epi, class Sched, bool ALIGN_EPI>
; __device__ __forceinline__ void gemm_phase(LAS unsigned char* lds, const int wid, const int lda_, const int ldb_, const int K_, const Sched& S, const Epi& E) {
;     ...
;             const bool last = (t == nt - 2);
;             const char* a1 = cA + (size_t)(t + 1) * kstep;
;             const char* a2 = last ? nA : cA + (size_t)(t + 2) * kstep; const char* b2 = last ? nB : cB + (size_t)(t + 2) * kstep;
;             const char* a3 = a2 + kstep; const char* b3 = b2 + kstep;
;             PG8_LDB(B0, 0, 0); PG8_LDB(B1, 0, 1); PG8_SCHED; PG8_LDA(At, 0, 0); PG8_STAGE(PG8_SA(1, 1), a1 + hstepA, voffA);
;             PG8_WAIT_V(8); PG8_WAIT_L(0); PG8_BAR; PG8_MMA(0, 0, At, B0); PG8_MMA(0, 1, At, B1); PG8_BAR; PG8_SCHED;
;             PG8_LDA(At, 0, 1); PG8_STAGE(PG8_SB(0, 0), b2, voffB); PG8_STAGE(PG8_SB(0, 1), b2 + hstepB, voffB); PG8_STAGE(PG8_SA(0, 0), a2, voffA);
;             PG8_WAIT_V(8); PG8_WAIT_L(0); PG8_BAR; PG8_MMA(1, 0, At, B0); PG8_MMA(1, 1, At, B1); PG8_BAR; PG8_SCHED;
.LBB0_883:
	s_add_u32 s17, s46, s48
	s_addc_u32 s27, s47, s49
	s_add_u32 s17, s17, 0x100
	s_addc_u32 s27, s27, 0
	s_add_u32 s42, s31, s48
	s_addc_u32 s43, s35, s49
	s_add_i32 s74, 0, 0x10000
	s_cmpk_eq_i32 s48, 0x300
	s_cselect_b32 s51, s4, s27
	s_cselect_b32 s50, s5, s17
	v_add_u32_e32 v141, s74, v135
	s_cselect_b32 s43, s39, s43
	s_cselect_b32 s42, s38, s42
	s_add_i32 s17, 0, 0x14000
	ds_read_b128 v[160:163], v141
	ds_read_b128 v[164:167], v141 offset:1024
	ds_read_b128 v[168:171], v141 offset:2048
	ds_read_b128 v[172:175], v141 offset:3072
	v_add_u32_e32 v141, s17, v135
	ds_read_b128 v[180:183], v141
	ds_read_b128 v[184:187], v141 offset:1024
	ds_read_b128 v[188:191], v141 offset:2048
	ds_read_b128 v[192:195], v141 offset:3072
	v_lshl_add_u64 v[228:229], v[158:159], 0, s[48:49]
	s_add_i32 m0, s16, 0xc000
	ds_read_b128 v[196:199], v139
	ds_read_b128 v[200:203], v139 offset:1024
	ds_read_b128 v[204:207], v139 offset:2048
	ds_read_b128 v[208:211], v139 offset:3072
	ds_read_b128 v[212:215], v139 offset:4096
	ds_read_b128 v[216:219], v139 offset:5120
	ds_read_b128 v[220:223], v139 offset:6144
	ds_read_b128 v[224:227], v139 offset:7168
	global_load_lds_dwordx4 v[228:229], off
	v_lshl_add_u64 v[228:229], v[156:157], 0, s[48:49]
	s_add_i32 m0, s16, 0xe000
	s_nop 0
	global_load_lds_dwordx4 v[228:229], off
	s_bitcmp1_b32 s101, 0
	s_cbranch_scc0 .Lvw_883_2
	s_waitcnt vmcnt(8)
.Lvw_883_2:
	s_waitcnt lgkmcnt(0)
	s_barrier
	s_waitcnt lgkmcnt(0)
	v_mfma_f32_16x16x32_bf16 v[124:127], v[160:163], v[196:199], v[124:127]
	v_mfma_f32_16x16x32_bf16 v[120:123], v[168:171], v[196:199], v[120:123]
	v_mfma_f32_16x16x32_bf16 v[116:119], v[160:163], v[204:207], v[116:119]
	v_mfma_f32_16x16x32_bf16 v[112:115], v[168:171], v[204:207], v[112:115]
	v_mfma_f32_16x16x32_bf16 v[100:103], v[160:163], v[212:215], v[100:103]
	v_mfma_f32_16x16x32_bf16 v[96:99], v[168:171], v[212:215], v[96:99]
	v_mfma_f32_16x16x32_bf16 v[84:87], v[160:163], v[220:223], v[84:87]
	v_mfma_f32_16x16x32_bf16 v[80:83], v[168:171], v[220:223], v[80:83]
	v_mfma_f32_16x16x32_bf16 v[124:127], v[164:167], v[200:203], v[124:127]
	v_mfma_f32_16x16x32_bf16 v[120:123], v[172:175], v[200:203], v[120:123]
	v_mfma_f32_16x16x32_bf16 v[116:119], v[164:167], v[208:211], v[116:119]
	v_mfma_f32_16x16x32_bf16 v[112:115], v[172:175], v[208:211], v[112:115]
	v_mfma_f32_16x16x32_bf16 v[100:103], v[164:167], v[216:219], v[100:103]
	v_mfma_f32_16x16x32_bf16 v[96:99], v[172:175], v[216:219], v[96:99]
	v_mfma_f32_16x16x32_bf16 v[84:87], v[164:167], v[224:227], v[84:87]
	v_mfma_f32_16x16x32_bf16 v[80:83], v[172:175], v[224:227], v[80:83]
	v_mfma_f32_16x16x32_bf16 v[108:111], v[180:183], v[196:199], v[108:111]
	v_mfma_f32_16x16x32_bf16 v[104:107], v[188:191], v[196:199], v[104:107]
	v_mfma_f32_16x16x32_bf16 v[92:95], v[180:183], v[204:207], v[92:95]
	v_mfma_f32_16x16x32_bf16 v[88:91], v[188:191], v[204:207], v[88:91]
	v_mfma_f32_16x16x32_bf16 v[76:79], v[180:183], v[212:215], v[76:79]
	v_mfma_f32_16x16x32_bf16 v[72:75], v[188:191], v[212:215], v[72:75]
	v_mfma_f32_16x16x32_bf16 v[68:71], v[180:183], v[220:223], v[68:71]
	v_mfma_f32_16x16x32_bf16 v[64:67], v[188:191], v[220:223], v[64:67]
	v_mfma_f32_16x16x32_bf16 v[108:111], v[184:187], v[200:203], v[108:111]
	v_mfma_f32_16x16x32_bf16 v[104:107], v[192:195], v[200:203], v[104:107]
	v_mfma_f32_16x16x32_bf16 v[92:95], v[184:187], v[208:211], v[92:95]
	v_mfma_f32_16x16x32_bf16 v[88:91], v[192:195], v[208:211], v[88:91]
	v_mfma_f32_16x16x32_bf16 v[76:79], v[184:187], v[216:219], v[76:79]
	v_mfma_f32_16x16x32_bf16 v[72:75], v[192:195], v[216:219], v[72:75]
	v_mfma_f32_16x16x32_bf16 v[68:71], v[184:187], v[224:227], v[68:71]
	v_mfma_f32_16x16x32_bf16 v[64:67], v[192:195], v[224:227], v[64:67]
	s_waitcnt vmcnt(8)
	s_barrier
	s_add_i32 s27, s74, s3
	v_lshl_add_u64 v[228:229], s[42:43], 0, v[176:177]
	s_mov_b32 m0, s27
	ds_read_b128 v[196:199], v139 offset:16384
	ds_read_b128 v[200:203], v139 offset:17408
	ds_read_b128 v[204:207], v139 offset:18432
	ds_read_b128 v[208:211], v139 offset:19456
	ds_read_b128 v[212:215], v139 offset:20480
	ds_read_b128 v[216:219], v139 offset:21504
	ds_read_b128 v[220:223], v139 offset:22528
	ds_read_b128 v[224:227], v139 offset:23552
	global_load_lds_dwordx4 v[228:229], off
	s_add_i32 m0, s27, 0x2000
	v_lshl_add_u64 v[230:231], s[42:43], 0, v[132:133]
	s_add_u32 s42, s42, s10
	s_addc_u32 s43, s43, s11
	s_add_i32 s17, s17, s3
	global_load_lds_dwordx4 v[230:231], off
	v_lshl_add_u64 v[232:233], s[42:43], 0, v[176:177]
	s_mov_b32 m0, s17
	v_lshl_add_u64 v[234:235], s[42:43], 0, v[132:133]
	global_load_lds_dwordx4 v[232:233], off
	s_add_i32 m0, s17, 0x2000
	v_lshl_add_u64 v[236:237], s[50:51], 0, v[128:129]
	global_load_lds_dwordx4 v[234:235], off
	s_mov_b32 m0, s16
	v_lshl_add_u64 v[246:247], s[50:51], 0, v[130:131]
	global_load_lds_dwordx4 v[236:237], off
	s_mov_b32 m0, s6
	s_nop 0
	global_load_lds_dwordx4 v[246:247], off
	s_bitcmp1_b32 s101, 0
	s_cbranch_scc0 .Lvw_883_3
	s_waitcnt vmcnt(8)

; #define PG8_STAGE(bufoff, gbase, voff) do { _Pragma("unroll") for (int _i = 0; _i < 2; ++_i) \
;         __builtin_amdgcn_global_load_lds((const unsigned*)((const char*)(gbase) + (voff)[_i]), (LAS unsigned*)(lds + (bufoff) + ldsw + _i * 8192), 16, 0, 0); } while (0)
; #define PG8_LDA(dst, b, h) do { _Pragma("unroll") for (int m = 0; m < 4; ++m) _Pragma("unroll") for (int k = 0; k < 2; ++k) dst[m][k] = *(const LAS bf16x8*)(lds + PG8_SA(b, h) + aoff + m * 2048 + k * 1024); } while (0)
; #define PG8_LDB(dst, b, h) do { _Pragma("unroll") for (int n = 0; n < 2; ++n) _Pragma("unroll") for (int k = 0; k < 2; ++k) dst[n][k] = *(const LAS bf16x8*)(lds + PG8_SB(b, h) + boff + n * 2048 + k * 1024); } while (0)
; #define PG8_MMA(ai, bj, At, Bt) do { __builtin_amdgcn_s_setprio(1); _Pragma("unroll") for (int m = 0; m < 4; ++m) _Pragma("unroll") for (int n = 0; n < 2; ++n) _Pragma("unroll") for (int k = 0; k < 2; ++k) \
;         acc[ai][bj][m][n] = __builtin_amdgcn_mfma_f32_16x16x32_bf16(Bt[n][k], At[m][k], acc[ai][bj][m][n], 0, 0, 0); __builtin_amdgcn_s_setprio(0); } while (0)
; #define PG8_WAIT_V(n) asm volatile("s_waitcnt vmcnt(" #n ")" ::: "memory")
; #define PG8_WAIT_L(n) asm volatile("s_waitcnt lgkmcnt(" #n ")" ::: "memory")
; #define PG8_BAR __builtin_amdgcn_s_barrier()
; #define PG8_SCHED __builtin_amdgcn_sched_barrier(0)
; template <class Epi, class Sched, bool ALIGN_EPI>
; __device__ __forceinline__ void gemm_phase(LAS unsigned char* lds, const int wid, const int lda_, const int ldb_, const int K_, const Sched& S, const Epi& E) {
;     ...
;             PG8_LDB(B0, 1, 0); PG8_LDB(B1, 1, 1); PG8_SCHED; PG8_LDA(At, 1, 0); PG8_STAGE(PG8_SA(0, 1), a2 + hstepA, voffA);
;             PG8_WAIT_V(8); PG8_WAIT_L(0); PG8_BAR; PG8_MMA(0, 0, At, B0); PG8_MMA(0, 1, At, B1); PG8_BAR; PG8_SCHED;
;             PG8_LDA(At, 1, 1); PG8_STAGE(PG8_SB(1, 0), b3, voffB); PG8_STAGE(PG8_SB(1, 1), b3 + hstepB, voffB); PG8_STAGE(PG8_SA(1, 0), a3, voffA);
;             PG8_WAIT_V(8); PG8_WAIT_L(0); PG8_BAR; PG8_MMA(1, 0, At, B0); PG8_MMA(1, 1, At, B1); PG8_BAR; PG8_SCHED;
.Lgemm_join_883:
	s_add_i32 s17, 0, 0x18000
	v_add_u32_e32 v141, s17, v135
	s_add_i32 s27, 0, 0x1c000
	ds_read_b128 v[160:163], v141
	ds_read_b128 v[164:167], v141 offset:1024
	ds_read_b128 v[168:171], v141 offset:2048
	ds_read_b128 v[172:175], v141 offset:3072
	v_add_u32_e32 v141, s27, v135
	ds_read_b128 v[180:183], v141
	ds_read_b128 v[184:187], v141 offset:1024
	ds_read_b128 v[188:191], v141 offset:2048
	ds_read_b128 v[192:195], v141 offset:3072
	s_add_u32 s42, s50, s0
	s_addc_u32 s43, s51, s1
	s_mov_b32 m0, s7
	v_lshl_add_u64 v[248:249], s[42:43], 0, v[128:129]
	ds_read_b128 v[196:199], v139 offset:32768
	ds_read_b128 v[200:203], v139 offset:33792
	ds_read_b128 v[204:207], v139 offset:34816
	ds_read_b128 v[208:211], v139 offset:35840
	ds_read_b128 v[212:215], v139 offset:36864
	ds_read_b128 v[216:219], v139 offset:37888
	ds_read_b128 v[220:223], v139 offset:38912
	ds_read_b128 v[224:227], v139 offset:39936
	global_load_lds_dwordx4 v[248:249], off
	v_lshl_add_u64 v[248:249], s[42:43], 0, v[130:131]
	s_mov_b32 m0, s14
	s_nop 0
	global_load_lds_dwordx4 v[248:249], off
	s_bitcmp1_b32 s101, 0
	s_cbranch_scc0 .Lvw_883_4
	s_waitcnt vmcnt(8)
.Lvw_883_4:
	s_waitcnt lgkmcnt(0)
	s_barrier
	s_waitcnt lgkmcnt(0)
	v_mfma_f32_16x16x32_bf16 v[124:127], v[160:163], v[196:199], v[124:127]
	v_mfma_f32_16x16x32_bf16 v[120:123], v[168:171], v[196:199], v[120:123]
	v_mfma_f32_16x16x32_bf16 v[116:119], v[160:163], v[204:207], v[116:119]
	v_mfma_f32_16x16x32_bf16 v[112:115], v[168:171], v[204:207], v[112:115]
	v_mfma_f32_16x16x32_bf16 v[100:103], v[160:163], v[212:215], v[100:103]
	v_mfma_f32_16x16x32_bf16 v[96:99], v[168:171], v[212:215], v[96:99]
	v_mfma_f32_16x16x32_bf16 v[84:87], v[160:163], v[220:223], v[84:87]
	v_mfma_f32_16x16x32_bf16 v[80:83], v[168:171], v[220:223], v[80:83]
	v_mfma_f32_16x16x32_bf16 v[124:127], v[164:167], v[200:203], v[124:127]
	v_mfma_f32_16x16x32_bf16 v[120:123], v[172:175], v[200:203], v[120:123]
	v_mfma_f32_16x16x32_bf16 v[116:119], v[164:167], v[208:211], v[116:119]
	v_mfma_f32_16x16x32_bf16 v[112:115], v[172:175], v[208:211], v[112:115]
	v_mfma_f32_16x16x32_bf16 v[100:103], v[164:167], v[216:219], v[100:103]
	v_mfma_f32_16x16x32_bf16 v[96:99], v[172:175], v[216:219], v[96:99]
	v_mfma_f32_16x16x32_bf16 v[84:87], v[164:167], v[224:227], v[84:87]
	v_mfma_f32_16x16x32_bf16 v[80:83], v[172:175], v[224:227], v[80:83]
	v_mfma_f32_16x16x32_bf16 v[108:111], v[180:183], v[196:199], v[108:111]
	v_mfma_f32_16x16x32_bf16 v[104:107], v[188:191], v[196:199], v[104:107]
	v_mfma_f32_16x16x32_bf16 v[92:95], v[180:183], v[204:207], v[92:95]
	v_mfma_f32_16x16x32_bf16 v[88:91], v[188:191], v[204:207], v[88:91]
	v_mfma_f32_16x16x32_bf16 v[76:79], v[180:183], v[212:215], v[76:79]
	v_mfma_f32_16x16x32_bf16 v[72:75], v[188:191], v[212:215], v[72:75]
	v_mfma_f32_16x16x32_bf16 v[68:71], v[180:183], v[220:223], v[68:71]
	v_mfma_f32_16x16x32_bf16 v[64:67], v[188:191], v[220:223], v[64:67]
	v_mfma_f32_16x16x32_bf16 v[108:111], v[184:187], v[200:203], v[108:111]
	v_mfma_f32_16x16x32_bf16 v[104:107], v[192:195], v[200:203], v[104:107]
	v_mfma_f32_16x16x32_bf16 v[92:95], v[184:187], v[208:211], v[92:95]
	v_mfma_f32_16x16x32_bf16 v[88:91], v[192:195], v[208:211], v[88:91]
	v_mfma_f32_16x16x32_bf16 v[76:79], v[184:187], v[216:219], v[76:79]
	v_mfma_f32_16x16x32_bf16 v[72:75], v[192:195], v[216:219], v[72:75]
	v_mfma_f32_16x16x32_bf16 v[68:71], v[184:187], v[224:227], v[68:71]
	v_mfma_f32_16x16x32_bf16 v[64:67], v[192:195], v[224:227], v[64:67]
	s_waitcnt vmcnt(8)
	s_barrier
	s_add_i32 s17, s17, s3
	v_lshl_add_u64 v[228:229], v[228:229], 0, s[24:25]
	s_mov_b32 m0, s17
	ds_read_b128 v[196:199], v139 offset:49152
	ds_read_b128 v[200:203], v139 offset:50176
	ds_read_b128 v[204:207], v139 offset:51200
	ds_read_b128 v[208:211], v139 offset:52224
	ds_read_b128 v[212:215], v139 offset:53248
	ds_read_b128 v[216:219], v139 offset:54272
	ds_read_b128 v[220:223], v139 offset:55296
	ds_read_b128 v[224:227], v139 offset:56320
	global_load_lds_dwordx4 v[228:229], off
	v_lshl_add_u64 v[228:229], v[230:231], 0, s[24:25]
	s_add_i32 m0, s17, 0x2000
	s_add_i32 s17, s27, s3
	global_load_lds_dwordx4 v[228:229], off
	v_lshl_add_u64 v[228:229], v[232:233], 0, s[24:25]
	s_mov_b32 m0, s17
	s_nop 0
	global_load_lds_dwordx4 v[228:229], off
	v_lshl_add_u64 v[228:229], v[234:235], 0, s[24:25]
	s_add_i32 m0, s17, 0x2000
	s_nop 0
	global_load_lds_dwordx4 v[228:229], off
	v_lshl_add_u64 v[228:229], v[236:237], 0, s[24:25]
	s_mov_b32 m0, s15
	s_nop 0
	global_load_lds_dwordx4 v[228:229], off
	v_lshl_add_u64 v[228:229], v[246:247], 0, s[24:25]
	s_mov_b32 m0, s26
	s_nop 0
	global_load_lds_dwordx4 v[228:229], off
	s_bitcmp1_b32 s101, 0
	s_cbranch_scc0 .Lvw_883_5
	s_waitcnt vmcnt(8)
; #define PG8_MMA(ai, bj, At, Bt) do { __builtin_amdgcn_s_setprio(1); _Pragma("unroll") for (int m = 0; m < 4; ++m) _Pragma("unroll") for (int n = 0; n < 2; ++n) _Pragma("unroll") for (int k = 0; k < 2; ++k) \
;         acc[ai][bj][m][n] = __builtin_amdgcn_mfma_f32_16x16x32_bf16(Bt[n][k], At[m][k], acc[ai][bj][m][n], 0, 0, 0); __builtin_amdgcn_s_setprio(0); } while (0)
; #define PG8_WAIT_V(n) asm volatile("s_waitcnt vmcnt(" #n ")" ::: "memory")
; #define PG8_WAIT_L(n) asm volatile("s_waitcnt lgkmcnt(" #n ")" ::: "memory")
; #define PG8_BAR __builtin_amdgcn_s_barrier()
; #define PG8_SCHED __builtin_amdgcn_sched_barrier(0)
; template <class Epi, class Sched, bool ALIGN_EPI>
; __device__ __forceinline__ void gemm_phase(LAS unsigned char* lds, const int wid, const int lda_, const int ldb_, const int K_, const Sched& S, const Epi& E) {
;     ...
;             PG8_WAIT_V(8); PG8_WAIT_L(0); PG8_BAR; PG8_MMA(1, 0, At, B0); PG8_MMA(1, 1, At, B1); PG8_BAR; PG8_SCHED;
;         }
.Lvw_883_5:
	s_waitcnt lgkmcnt(0)
	s_barrier
	s_waitcnt lgkmcnt(0)
	v_mfma_f32_16x16x32_bf16 v[60:63], v[160:163], v[196:199], v[60:63]
	v_mfma_f32_16x16x32_bf16 v[56:59], v[168:171], v[196:199], v[56:59]
	v_mfma_f32_16x16x32_bf16 v[52:55], v[160:163], v[204:207], v[52:55]
	v_mfma_f32_16x16x32_bf16 v[48:51], v[168:171], v[204:207], v[48:51]
	v_mfma_f32_16x16x32_bf16 v[36:39], v[160:163], v[212:215], v[36:39]
	v_mfma_f32_16x16x32_bf16 v[32:35], v[168:171], v[212:215], v[32:35]
	v_mfma_f32_16x16x32_bf16 v[20:23], v[160:163], v[220:223], v[20:23]
	v_mfma_f32_16x16x32_bf16 v[16:19], v[168:171], v[220:223], v[16:19]
	v_mfma_f32_16x16x32_bf16 v[60:63], v[164:167], v[200:203], v[60:63]
	v_mfma_f32_16x16x32_bf16 v[56:59], v[172:175], v[200:203], v[56:59]
	v_mfma_f32_16x16x32_bf16 v[52:55], v[164:167], v[208:211], v[52:55]
	v_mfma_f32_16x16x32_bf16 v[48:51], v[172:175], v[208:211], v[48:51]
	v_mfma_f32_16x16x32_bf16 v[36:39], v[164:167], v[216:219], v[36:39]
	v_mfma_f32_16x16x32_bf16 v[32:35], v[172:175], v[216:219], v[32:35]
	v_mfma_f32_16x16x32_bf16 v[20:23], v[164:167], v[224:227], v[20:23]
	v_mfma_f32_16x16x32_bf16 v[16:19], v[172:175], v[224:227], v[16:19]
	v_mfma_f32_16x16x32_bf16 v[44:47], v[180:183], v[196:199], v[44:47]
	v_mfma_f32_16x16x32_bf16 v[40:43], v[188:191], v[196:199], v[40:43]
	v_mfma_f32_16x16x32_bf16 v[28:31], v[180:183], v[204:207], v[28:31]
	v_mfma_f32_16x16x32_bf16 v[24:27], v[188:191], v[204:207], v[24:27]
	v_mfma_f32_16x16x32_bf16 v[12:15], v[180:183], v[212:215], v[12:15]
	v_mfma_f32_16x16x32_bf16 v[8:11], v[188:191], v[212:215], v[8:11]
	v_mfma_f32_16x16x32_bf16 v[4:7], v[180:183], v[220:223], v[4:7]
	v_mfma_f32_16x16x32_bf16 v[0:3], v[188:191], v[220:223], v[0:3]
	v_mfma_f32_16x16x32_bf16 v[44:47], v[184:187], v[200:203], v[44:47]
	v_mfma_f32_16x16x32_bf16 v[40:43], v[192:195], v[200:203], v[40:43]
	v_mfma_f32_16x16x32_bf16 v[28:31], v[184:187], v[208:211], v[28:31]
	v_mfma_f32_16x16x32_bf16 v[24:27], v[192:195], v[208:211], v[24:27]
	v_mfma_f32_16x16x32_bf16 v[12:15], v[184:187], v[216:219], v[12:15]
	v_mfma_f32_16x16x32_bf16 v[8:11], v[192:195], v[216:219], v[8:11]
	v_mfma_f32_16x16x32_bf16 v[4:7], v[184:187], v[224:227], v[4:7]
	v_mfma_f32_16x16x32_bf16 v[0:3], v[192:195], v[224:227], v[0:3]
	s_waitcnt vmcnt(8)
	s_barrier
	s_add_i32 s73, s73, 2
	s_add_u32 s48, s48, 0x100
	s_addc_u32 s49, s49, 0
	s_cmp_gt_u32 s73, 5
	s_cbranch_scc0 .LBB0_883
; __device__ __forceinline__ unsigned cvt_pk_bf16(float lo, float hi) { const f32x2 v = {lo, hi}; return __builtin_bit_cast(unsigned, __builtin_convertvector(v, bf16x2_t)); }
;     template <class Sched> __device__ __forceinline__ void operator()(const f32x4 (&acc)[2][2][4][2], const Unit& u, const Sched& S, int wr, int wc, int fr, int fq) const {
;     ...
;         if (kind == 0) {
;             bf16_t* base = (bf16_t*)uo;
; #pragma unroll
;             for (int ai = 0; ai < 2; ++ai)
; #pragma unroll
;                 for (int m = 0; m < 4; ++m) { bf16_t* rowp = base + (size_t)(rl0 + ai * HALF + m * 16) * ldo + cl0;
; #pragma unroll
;                     for (int bj = 0; bj < 2; ++bj) { const f32x4 v0 = acc[ai][bj][m][0], v1 = acc[ai][bj][m][1];
;                         u32x4 w; w.x = cvt_pk_bf16(v0[0], v0[1]); w.y = cvt_pk_bf16(v0[2], v0[3]); w.z = cvt_pk_bf16(v1[0], v1[1]); w.w = cvt_pk_bf16(v1[2], v1[3]);
;                         *(u32x4*)(rowp + bj * HALF) = w; } }
;         if (u.pm < 64) { o = (char*)ws + WS_F + (((size_t)((u.pm >> 3) * 2048 + (u.pm & 7))) * D + (size_t)u.pn * 256) * 2; ldo = 8 * D; }
;         else { o = (char*)ws + WS_F + (((size_t)(MLAT + (u.pm - 64) * 256)) * D + (size_t)u.pn * 256) * 2; ldo = D; } }
	s_setprio 2
	s_lshl_b32 s4, s41, 8
	s_and_b32 s5, s4, 0xfffff800
	s_and_b32 s17, s41, 7
	s_or_b32 s17, s5, s17
	s_ashr_i32 s5, s17, 31
	s_cmp_lt_i32 s41, 64
	s_cselect_b32 s4, s17, s4
	s_movk_i32 s17, 0x800
	s_cselect_b32 s5, s5, 0
	s_cselect_b32 s17, 0x4000, s17
	s_ashr_i32 s41, s40, 31
	s_lshl_b64 s[40:41], s[40:41], 9
	s_lshl_b64 s[4:5], s[4:5], 12
	v_readlane_b32 s27, v254, 19
	s_add_u32 s4, s27, s4
	v_readlane_b32 s27, v254, 20
	s_addc_u32 s5, s27, s5
	s_add_u32 s4, s4, s40
	s_addc_u32 s5, s5, s41
	v_lshl_add_u64 v[156:157], v[136:137], 1, s[4:5]
	v_mad_i64_i32 v[158:159], s[4:5], s17, v134, 0
	v_lshl_add_u64 v[158:159], v[158:159], 1, v[156:157]
	v_cvt_pk_bf16_f32 v108, v108, v109
	v_cvt_pk_bf16_f32 v109, v110, v111
	v_cvt_pk_bf16_f32 v110, v104, v105
	v_cvt_pk_bf16_f32 v111, v106, v107
	v_mad_i64_i32 v[104:105], s[4:5], s17, v138, 0
	v_cvt_pk_bf16_f32 v124, v124, v125
	v_cvt_pk_bf16_f32 v125, v126, v127
	v_cvt_pk_bf16_f32 v126, v120, v121
	v_cvt_pk_bf16_f32 v127, v122, v123
	global_store_dwordx4 v[158:159], v[108:111], off offset:256
	v_cvt_pk_bf16_f32 v92, v92, v93
	v_cvt_pk_bf16_f32 v93, v94, v95
	v_lshl_add_u64 v[108:109], v[104:105], 1, v[156:157]
	v_cvt_pk_bf16_f32 v94, v88, v89
	v_cvt_pk_bf16_f32 v95, v90, v91
	v_mad_i64_i32 v[88:89], s[4:5], s17, v140, 0
	global_store_dwordx4 v[158:159], v[124:127], off
	v_cvt_pk_bf16_f32 v104, v116, v117
	v_cvt_pk_bf16_f32 v105, v118, v119
	v_cvt_pk_bf16_f32 v106, v112, v113
	v_cvt_pk_bf16_f32 v107, v114, v115
	global_store_dwordx4 v[108:109], v[92:95], off offset:256
	v_cvt_pk_bf16_f32 v76, v76, v77
	v_cvt_pk_bf16_f32 v77, v78, v79
	v_lshl_add_u64 v[92:93], v[88:89], 1, v[156:157]
	v_cvt_pk_bf16_f32 v78, v72, v73
	v_cvt_pk_bf16_f32 v79, v74, v75
	v_mad_i64_i32 v[72:73], s[4:5], s17, v142, 0
	v_cvt_pk_bf16_f32 v68, v68, v69
	v_cvt_pk_bf16_f32 v69, v70, v71
	v_cvt_pk_bf16_f32 v70, v64, v65
	v_mad_i64_i32 v[64:65], s[4:5], s17, v144, 0
	global_store_dwordx4 v[108:109], v[104:107], off
	v_cvt_pk_bf16_f32 v88, v100, v101
	v_cvt_pk_bf16_f32 v89, v102, v103
	v_cvt_pk_bf16_f32 v90, v96, v97
	v_cvt_pk_bf16_f32 v91, v98, v99
	global_store_dwordx4 v[92:93], v[76:79], off offset:256
	v_cvt_pk_bf16_f32 v74, v80, v81
	v_cvt_pk_bf16_f32 v75, v82, v83
	v_lshl_add_u64 v[76:77], v[72:73], 1, v[156:157]
	v_cvt_pk_bf16_f32 v72, v84, v85
	v_cvt_pk_bf16_f32 v73, v86, v87
	v_cvt_pk_bf16_f32 v71, v66, v67
	v_lshl_add_u64 v[64:65], v[64:65], 1, v[156:157]
	v_cvt_pk_bf16_f32 v44, v44, v45
	v_cvt_pk_bf16_f32 v45, v46, v47
	v_cvt_pk_bf16_f32 v46, v40, v41
	v_cvt_pk_bf16_f32 v47, v42, v43
	v_mad_i64_i32 v[40:41], s[4:5], s17, v146, 0
	global_store_dwordx4 v[92:93], v[88:91], off
	global_store_dwordx4 v[76:77], v[72:75], off
	global_store_dwordx4 v[76:77], v[68:71], off offset:256
	v_cvt_pk_bf16_f32 v60, v60, v61
	v_cvt_pk_bf16_f32 v61, v62, v63
	v_cvt_pk_bf16_f32 v62, v56, v57
	v_cvt_pk_bf16_f32 v63, v58, v59
	global_store_dwordx4 v[64:65], v[44:47], off offset:256
	v_cvt_pk_bf16_f32 v28, v28, v29
	v_cvt_pk_bf16_f32 v29, v30, v31
	v_lshl_add_u64 v[44:45], v[40:41], 1, v[156:157]
	v_cvt_pk_bf16_f32 v30, v24, v25
	v_cvt_pk_bf16_f32 v31, v26, v27
	v_mad_i64_i32 v[24:25], s[4:5], s17, v148, 0
	global_store_dwordx4 v[64:65], v[60:63], off
	v_cvt_pk_bf16_f32 v40, v52, v53
	v_cvt_pk_bf16_f32 v41, v54, v55
	v_cvt_pk_bf16_f32 v42, v48, v49
	v_cvt_pk_bf16_f32 v43, v50, v51
	global_store_dwordx4 v[44:45], v[28:31], off offset:256
	v_cvt_pk_bf16_f32 v12, v12, v13
	v_cvt_pk_bf16_f32 v13, v14, v15
	v_lshl_add_u64 v[28:29], v[24:25], 1, v[156:157]
	v_cvt_pk_bf16_f32 v14, v8, v9
	v_cvt_pk_bf16_f32 v15, v10, v11
	v_mad_i64_i32 v[8:9], s[4:5], s17, v150, 0
	global_store_dwordx4 v[44:45], v[40:43], off
	v_cvt_pk_bf16_f32 v24, v36, v37
	v_cvt_pk_bf16_f32 v25, v38, v39
	v_cvt_pk_bf16_f32 v26, v32, v33
	v_cvt_pk_bf16_f32 v27, v34, v35
	global_store_dwordx4 v[28:29], v[12:15], off offset:256
	v_cvt_pk_bf16_f32 v10, v16, v17
	v_cvt_pk_bf16_f32 v11, v18, v19
	v_lshl_add_u64 v[12:13], v[8:9], 1, v[156:157]
	v_cvt_pk_bf16_f32 v8, v20, v21
	v_cvt_pk_bf16_f32 v9, v22, v23
	v_cvt_pk_bf16_f32 v4, v4, v5
	v_cvt_pk_bf16_f32 v5, v6, v7
	v_cvt_pk_bf16_f32 v6, v0, v1
	v_cvt_pk_bf16_f32 v7, v2, v3
	s_and_b64 vcc, exec, s[36:37]
	s_mov_b32 s40, s30
	s_mov_b32 s41, s34
	s_mov_b64 s[48:49], s[38:39]
	s_mov_b64 s[46:47], s[44:45]
	global_store_dwordx4 v[28:29], v[24:27], off
	global_store_dwordx4 v[12:13], v[8:11], off
	global_store_dwordx4 v[12:13], v[4:7], off offset:256
	s_cbranch_vccz .LBB0_868
	v_readlane_b32 s0, v253, 1
	s_waitcnt vmcnt(0)
	v_readlane_b32 s1, v253, 2
	v_readlane_b32 s72, v255, 28
	s_andn2_b64 vcc, exec, s[0:1]
	v_readlane_b32 s73, v255, 29
	s_cbranch_vccnz .LBB0_887
	s_barrier

; #define PG8_STAGE(bufoff, gbase, voff) do { _Pragma("unroll") for (int _i = 0; _i < 2; ++_i) \
;         __builtin_amdgcn_global_load_lds((const unsigned*)((const char*)(gbase) + (voff)[_i]), (LAS unsigned*)(lds + (bufoff) + ldsw + _i * 8192), 16, 0, 0); } while (0)
; #define PG8_WAIT_V(n) asm volatile("s_waitcnt vmcnt(" #n ")" ::: "memory")
; #define PG8_BAR __builtin_amdgcn_s_barrier()
; template <class Epi, class Sched, bool ALIGN_EPI>
; __device__ __forceinline__ void gemm_phase(LAS unsigned char* lds, const int wid, const int lda_, const int ldb_, const int K_, const Sched& S, const Epi& E) {
;     ...
;         const bool has_next = S.next(ui + 1, nxt);
;         const int nt = S.nt(cur);
;         const char* nA = has_next ? S.a(nxt) : cA; const char* nB = has_next ? S.b(nxt) : cB;
; #pragma unroll 1
;         for (int t = 0; t < nt; t += 2) {
;             const bool last = (t == nt - 2);
;             const char* a1 = cA + (size_t)(t + 1) * kstep;
;             const char* a2 = last ? nA : cA + (size_t)(t + 2) * kstep; const char* b2 = last ? nB : cB + (size_t)(t + 2) * kstep;
;             const char* a3 = a2 + kstep; const char* b3 = b2 + kstep;
;             PG8_LDB(B0, 0, 0); PG8_LDB(B1, 0, 1); PG8_SCHED; PG8_LDA(At, 0, 0); PG8_STAGE(PG8_SA(1, 1), a1 + hstepA, voffA);
;             PG8_WAIT_V(8); PG8_WAIT_L(0); PG8_BAR; PG8_MMA(0, 0, At, B0); PG8_MMA(0, 1, At, B1); PG8_BAR; PG8_SCHED;
;             PG8_LDA(At, 0, 1); PG8_STAGE(PG8_SB(0, 0), b2, voffB); PG8_STAGE(PG8_SB(0, 1), b2 + hstepB, voffB); PG8_STAGE(PG8_SA(0, 0), a2, voffA);
;             PG8_WAIT_V(8); PG8_WAIT_L(0); PG8_BAR; PG8_MMA(1, 0, At, B0); PG8_MMA(1, 1, At, B1); PG8_BAR; PG8_SCHED;
;     __device__ __forceinline__ void out(const pg8::Unit& u, char*& o, int& ldo, int& kind) const { ldo = D;
;         if (u.kq < 0) { o = (char*)ws + YOFF + ((size_t)u.pm * 256 * D + (size_t)u.pn * 256) * 2; kind = 0; }
;         else { o = (char*)ws + WS_PART + (((size_t)u.kq * MCTX + (size_t)(u.pm - 64) * 256) * D + (size_t)u.pn * 256) * 2; kind = 0; } }
;     __device__ __forceinline__ const char* a(const pg8::Unit& u) const { return (const char*)ws + aoff + (size_t)u.pm * 256 * K_ * 2 + (u.kq < 0 ? 0 : u.kq * (K_ / 4) * 2); }
;     __device__ __forceinline__ const char* b(const pg8::Unit& u) const { return (const char*)ws + boff + (size_t)u.pn * 256 * K_ * 2 + (u.kq < 0 ? 0 : u.kq * (K_ / 4) * 2); }
.LBB0_961:
	s_xor_b64 s[36:37], s[4:5], -1
	s_cmp_gt_i32 s48, -1
	s_cselect_b64 s[50:51], -1, 0
	s_cmp_lt_i32 s48, 0
	s_cselect_b32 s45, 32, 8
	s_max_i32 s17, s75, 0
	s_ashr_i32 s35, s34, 31
	s_lshl_b32 s17, s17, 10
	s_lshl_b64 s[38:39], s[34:35], 20
	v_readlane_b32 s27, v254, 19
	s_add_u32 s27, s27, s38
	v_readlane_b32 s31, v254, 20
	s_addc_u32 s31, s31, s39
	s_add_u32 s38, s27, s17
	s_addc_u32 s39, s31, 0
	s_and_b64 s[40:41], s[4:5], exec
	s_cselect_b32 s35, s39, s95
	s_cselect_b32 s47, s38, s94
	s_ashr_i32 s31, s30, 31
	s_lshl_b64 s[40:41], s[30:31], 20
	s_add_u32 s27, s6, s40
	s_addc_u32 s31, s7, s41
	s_add_u32 s40, s27, s17
	s_addc_u32 s41, s31, 0
	s_and_b64 s[4:5], s[4:5], exec
	s_cselect_b32 s4, s41, s97
	s_cselect_b32 s5, s40, s96
	s_add_i32 s31, s45, -2
	s_add_u32 s94, s94, 0x80
	s_addc_u32 s95, s95, 0
	s_add_u32 s49, s96, 0x100
	s_mov_b32 s77, 0
	s_addc_u32 s76, s97, 0
	s_add_i32 s78, s77, 2
	s_add_u32 s17, s94, 0x80
	s_addc_u32 s27, s95, 0
	s_add_i32 s79, 0, 0x10000
	s_cmp_eq_u32 s31, s77
	s_cselect_b32 s97, s35, s27
	s_cselect_b32 s96, s47, s17
	v_add_u32_e32 v141, s79, v135
	s_cselect_b32 s43, s4, s76
	s_cselect_b32 s42, s5, s49
	s_add_i32 s17, 0, 0x14000
	ds_read_b128 v[156:159], v141
	ds_read_b128 v[160:163], v141 offset:1024
	ds_read_b128 v[164:167], v141 offset:2048
	ds_read_b128 v[168:171], v141 offset:3072
	v_add_u32_e32 v141, s17, v135
	ds_read_b128 v[172:175], v141
	ds_read_b128 v[180:183], v141 offset:1024
	ds_read_b128 v[184:187], v141 offset:2048
	ds_read_b128 v[188:191], v141 offset:3072
	v_lshl_add_u64 v[224:225], s[94:95], 0, v[152:153]
	s_add_i32 m0, s16, 0xc000
	ds_read_b128 v[192:195], v139
	ds_read_b128 v[196:199], v139 offset:1024
	ds_read_b128 v[200:203], v139 offset:2048
	ds_read_b128 v[204:207], v139 offset:3072
	ds_read_b128 v[208:211], v139 offset:4096
	ds_read_b128 v[212:215], v139 offset:5120
	ds_read_b128 v[216:219], v139 offset:6144
	ds_read_b128 v[220:223], v139 offset:7168
	global_load_lds_dwordx4 v[224:225], off
	v_lshl_add_u64 v[224:225], s[94:95], 0, v[154:155]
	s_add_i32 m0, s16, 0xe000
	s_nop 0
	global_load_lds_dwordx4 v[224:225], off
	v_readlane_b32 s101, v252, 58
	s_nop 3
	s_bitcmp1_b32 s101, 0
	s_cbranch_scc0 .Lvw_962_0
	s_waitcnt vmcnt(8)
.Lvw_962_0:
	s_waitcnt lgkmcnt(0)
	s_barrier
	s_setprio 0
	s_waitcnt lgkmcnt(0)
	v_mfma_f32_16x16x32_bf16 v[124:127], v[156:159], v[192:195], 0
	v_mfma_f32_16x16x32_bf16 v[120:123], v[164:167], v[192:195], 0
	v_mfma_f32_16x16x32_bf16 v[116:119], v[156:159], v[200:203], 0
	v_mfma_f32_16x16x32_bf16 v[112:115], v[164:167], v[200:203], 0
	v_mfma_f32_16x16x32_bf16 v[100:103], v[156:159], v[208:211], 0
	v_mfma_f32_16x16x32_bf16 v[96:99], v[164:167], v[208:211], 0
	v_mfma_f32_16x16x32_bf16 v[84:87], v[156:159], v[216:219], 0
	v_mfma_f32_16x16x32_bf16 v[80:83], v[164:167], v[216:219], 0
	v_mfma_f32_16x16x32_bf16 v[124:127], v[160:163], v[196:199], v[124:127]
	v_mfma_f32_16x16x32_bf16 v[120:123], v[168:171], v[196:199], v[120:123]
	v_mfma_f32_16x16x32_bf16 v[116:119], v[160:163], v[204:207], v[116:119]
	v_mfma_f32_16x16x32_bf16 v[112:115], v[168:171], v[204:207], v[112:115]
	v_mfma_f32_16x16x32_bf16 v[100:103], v[160:163], v[212:215], v[100:103]
	v_mfma_f32_16x16x32_bf16 v[96:99], v[168:171], v[212:215], v[96:99]
	v_mfma_f32_16x16x32_bf16 v[84:87], v[160:163], v[220:223], v[84:87]
	v_mfma_f32_16x16x32_bf16 v[80:83], v[168:171], v[220:223], v[80:83]
	v_mfma_f32_16x16x32_bf16 v[108:111], v[172:175], v[192:195], 0
	v_mfma_f32_16x16x32_bf16 v[104:107], v[184:187], v[192:195], 0
	v_mfma_f32_16x16x32_bf16 v[92:95], v[172:175], v[200:203], 0
	v_mfma_f32_16x16x32_bf16 v[88:91], v[184:187], v[200:203], 0
	v_mfma_f32_16x16x32_bf16 v[76:79], v[172:175], v[208:211], 0
	v_mfma_f32_16x16x32_bf16 v[72:75], v[184:187], v[208:211], 0
	v_mfma_f32_16x16x32_bf16 v[68:71], v[172:175], v[216:219], 0
	v_mfma_f32_16x16x32_bf16 v[64:67], v[184:187], v[216:219], 0
	v_mfma_f32_16x16x32_bf16 v[108:111], v[180:183], v[196:199], v[108:111]
	v_mfma_f32_16x16x32_bf16 v[104:107], v[188:191], v[196:199], v[104:107]
	v_mfma_f32_16x16x32_bf16 v[92:95], v[180:183], v[204:207], v[92:95]
	v_mfma_f32_16x16x32_bf16 v[88:91], v[188:191], v[204:207], v[88:91]
	v_mfma_f32_16x16x32_bf16 v[76:79], v[180:183], v[212:215], v[76:79]
	v_mfma_f32_16x16x32_bf16 v[72:75], v[188:191], v[212:215], v[72:75]
	v_mfma_f32_16x16x32_bf16 v[68:71], v[180:183], v[220:223], v[68:71]
	v_mfma_f32_16x16x32_bf16 v[64:67], v[188:191], v[220:223], v[64:67]
	s_waitcnt vmcnt(8)
	s_barrier
	s_add_i32 s27, s79, s3
	v_lshl_add_u64 v[224:225], s[42:43], 0, v[176:177]
	s_mov_b32 m0, s27
	ds_read_b128 v[192:195], v139 offset:16384
	ds_read_b128 v[196:199], v139 offset:17408
	ds_read_b128 v[200:203], v139 offset:18432
	ds_read_b128 v[204:207], v139 offset:19456
	ds_read_b128 v[208:211], v139 offset:20480
	ds_read_b128 v[212:215], v139 offset:21504
	ds_read_b128 v[216:219], v139 offset:22528
	ds_read_b128 v[220:223], v139 offset:23552
	global_load_lds_dwordx4 v[224:225], off
	s_add_i32 m0, s27, 0x2000
	v_lshl_add_u64 v[226:227], s[42:43], 0, v[128:129]
	s_add_u32 s42, s42, s10
	s_addc_u32 s43, s43, s11
	s_add_i32 s17, s17, s3
	global_load_lds_dwordx4 v[226:227], off
	v_lshl_add_u64 v[228:229], s[42:43], 0, v[176:177]
	s_mov_b32 m0, s17
	v_lshl_add_u64 v[230:231], s[42:43], 0, v[128:129]
	global_load_lds_dwordx4 v[228:229], off
	s_add_i32 m0, s17, 0x2000
	v_lshl_add_u64 v[232:233], s[96:97], 0, v[132:133]
	global_load_lds_dwordx4 v[230:231], off
	s_mov_b32 m0, s16
	v_lshl_add_u64 v[234:235], s[96:97], 0, v[130:131]
	global_load_lds_dwordx4 v[232:233], off
	s_mov_b32 m0, s14
	s_nop 0
	global_load_lds_dwordx4 v[234:235], off
	s_bitcmp1_b32 s101, 0
	s_cbranch_scc0 .Lvw_962_1
	s_waitcnt vmcnt(8)

; #define PG8_STAGE(bufoff, gbase, voff) do { _Pragma("unroll") for (int _i = 0; _i < 2; ++_i) \
;         __builtin_amdgcn_global_load_lds((const unsigned*)((const char*)(gbase) + (voff)[_i]), (LAS unsigned*)(lds + (bufoff) + ldsw + _i * 8192), 16, 0, 0); } while (0)
; #define PG8_LDA(dst, b, h) do { _Pragma("unroll") for (int m = 0; m < 4; ++m) _Pragma("unroll") for (int k = 0; k < 2; ++k) dst[m][k] = *(const LAS bf16x8*)(lds + PG8_SA(b, h) + aoff + m * 2048 + k * 1024); } while (0)
; #define PG8_LDB(dst, b, h) do { _Pragma("unroll") for (int n = 0; n < 2; ++n) _Pragma("unroll") for (int k = 0; k < 2; ++k) dst[n][k] = *(const LAS bf16x8*)(lds + PG8_SB(b, h) + boff + n * 2048 + k * 1024); } while (0)
; #define PG8_MMA(ai, bj, At, Bt) do { __builtin_amdgcn_s_setprio(1); _Pragma("unroll") for (int m = 0; m < 4; ++m) _Pragma("unroll") for (int n = 0; n < 2; ++n) _Pragma("unroll") for (int k = 0; k < 2; ++k) \
;         acc[ai][bj][m][n] = __builtin_amdgcn_mfma_f32_16x16x32_bf16(Bt[n][k], At[m][k], acc[ai][bj][m][n], 0, 0, 0); __builtin_amdgcn_s_setprio(0); } while (0)
; #define PG8_WAIT_V(n) asm volatile("s_waitcnt vmcnt(" #n ")" ::: "memory")
; #define PG8_WAIT_L(n) asm volatile("s_waitcnt lgkmcnt(" #n ")" ::: "memory")
; #define PG8_BAR __builtin_amdgcn_s_barrier()
; #define PG8_SCHED __builtin_amdgcn_sched_barrier(0)
; template <class Epi, class Sched, bool ALIGN_EPI>
; __device__ __forceinline__ void gemm_phase(LAS unsigned char* lds, const int wid, const int lda_, const int ldb_, const int K_, const Sched& S, const Epi& E) {
;     ...
;             const bool last = (t == nt - 2);
;             const char* a1 = cA + (size_t)(t + 1) * kstep;
;             const char* a2 = last ? nA : cA + (size_t)(t + 2) * kstep; const char* b2 = last ? nB : cB + (size_t)(t + 2) * kstep;
;             const char* a3 = a2 + kstep; const char* b3 = b2 + kstep;
;             PG8_LDB(B0, 0, 0); PG8_LDB(B1, 0, 1); PG8_SCHED; PG8_LDA(At, 0, 0); PG8_STAGE(PG8_SA(1, 1), a1 + hstepA, voffA);
;             PG8_WAIT_V(8); PG8_WAIT_L(0); PG8_BAR; PG8_MMA(0, 0, At, B0); PG8_MMA(0, 1, At, B1); PG8_BAR; PG8_SCHED;
;             PG8_LDA(At, 0, 1); PG8_STAGE(PG8_SB(0, 0), b2, voffB); PG8_STAGE(PG8_SB(0, 1), b2 + hstepB, voffB); PG8_STAGE(PG8_SA(0, 0), a2, voffA);
;             PG8_WAIT_V(8); PG8_WAIT_L(0); PG8_BAR; PG8_MMA(1, 0, At, B0); PG8_MMA(1, 1, At, B1); PG8_BAR; PG8_SCHED;
.LBB0_962:
	s_add_i32 s78, s77, 2
	s_add_u32 s17, s94, 0x80
	s_addc_u32 s27, s95, 0
	s_add_i32 s79, 0, 0x10000
	s_cmp_eq_u32 s31, s77
	s_cselect_b32 s97, s35, s27
	s_cselect_b32 s96, s47, s17
	v_add_u32_e32 v141, s79, v135
	s_cselect_b32 s43, s4, s76
	s_cselect_b32 s42, s5, s49
	s_add_i32 s17, 0, 0x14000
	ds_read_b128 v[156:159], v141
	ds_read_b128 v[160:163], v141 offset:1024
	ds_read_b128 v[164:167], v141 offset:2048
	ds_read_b128 v[168:171], v141 offset:3072
	v_add_u32_e32 v141, s17, v135
	ds_read_b128 v[172:175], v141
	ds_read_b128 v[180:183], v141 offset:1024
	ds_read_b128 v[184:187], v141 offset:2048
	ds_read_b128 v[188:191], v141 offset:3072
	v_lshl_add_u64 v[224:225], s[94:95], 0, v[152:153]
	s_add_i32 m0, s16, 0xc000
	ds_read_b128 v[192:195], v139
	ds_read_b128 v[196:199], v139 offset:1024
	ds_read_b128 v[200:203], v139 offset:2048
	ds_read_b128 v[204:207], v139 offset:3072
	ds_read_b128 v[208:211], v139 offset:4096
	ds_read_b128 v[212:215], v139 offset:5120
	ds_read_b128 v[216:219], v139 offset:6144
	ds_read_b128 v[220:223], v139 offset:7168
	global_load_lds_dwordx4 v[224:225], off
	v_lshl_add_u64 v[224:225], s[94:95], 0, v[154:155]
	s_add_i32 m0, s16, 0xe000
	s_nop 0
	global_load_lds_dwordx4 v[224:225], off
	s_bitcmp1_b32 s101, 0
	s_cbranch_scc0 .Lvw_962_2
	s_waitcnt vmcnt(8)
.Lvw_962_2:
	s_waitcnt lgkmcnt(0)
	s_barrier
	s_waitcnt lgkmcnt(0)
	v_mfma_f32_16x16x32_bf16 v[124:127], v[156:159], v[192:195], v[124:127]
	v_mfma_f32_16x16x32_bf16 v[120:123], v[164:167], v[192:195], v[120:123]
	v_mfma_f32_16x16x32_bf16 v[116:119], v[156:159], v[200:203], v[116:119]
	v_mfma_f32_16x16x32_bf16 v[112:115], v[164:167], v[200:203], v[112:115]
	v_mfma_f32_16x16x32_bf16 v[100:103], v[156:159], v[208:211], v[100:103]
	v_mfma_f32_16x16x32_bf16 v[96:99], v[164:167], v[208:211], v[96:99]
	v_mfma_f32_16x16x32_bf16 v[84:87], v[156:159], v[216:219], v[84:87]
	v_mfma_f32_16x16x32_bf16 v[80:83], v[164:167], v[216:219], v[80:83]
	v_mfma_f32_16x16x32_bf16 v[124:127], v[160:163], v[196:199], v[124:127]
	v_mfma_f32_16x16x32_bf16 v[120:123], v[168:171], v[196:199], v[120:123]
	v_mfma_f32_16x16x32_bf16 v[116:119], v[160:163], v[204:207], v[116:119]
	v_mfma_f32_16x16x32_bf16 v[112:115], v[168:171], v[204:207], v[112:115]
	v_mfma_f32_16x16x32_bf16 v[100:103], v[160:163], v[212:215], v[100:103]
	v_mfma_f32_16x16x32_bf16 v[96:99], v[168:171], v[212:215], v[96:99]
	v_mfma_f32_16x16x32_bf16 v[84:87], v[160:163], v[220:223], v[84:87]
	v_mfma_f32_16x16x32_bf16 v[80:83], v[168:171], v[220:223], v[80:83]
	v_mfma_f32_16x16x32_bf16 v[108:111], v[172:175], v[192:195], v[108:111]
	v_mfma_f32_16x16x32_bf16 v[104:107], v[184:187], v[192:195], v[104:107]
	v_mfma_f32_16x16x32_bf16 v[92:95], v[172:175], v[200:203], v[92:95]
	v_mfma_f32_16x16x32_bf16 v[88:91], v[184:187], v[200:203], v[88:91]
	v_mfma_f32_16x16x32_bf16 v[76:79], v[172:175], v[208:211], v[76:79]
	v_mfma_f32_16x16x32_bf16 v[72:75], v[184:187], v[208:211], v[72:75]
	v_mfma_f32_16x16x32_bf16 v[68:71], v[172:175], v[216:219], v[68:71]
	v_mfma_f32_16x16x32_bf16 v[64:67], v[184:187], v[216:219], v[64:67]
	v_mfma_f32_16x16x32_bf16 v[108:111], v[180:183], v[196:199], v[108:111]
	v_mfma_f32_16x16x32_bf16 v[104:107], v[188:191], v[196:199], v[104:107]
	v_mfma_f32_16x16x32_bf16 v[92:95], v[180:183], v[204:207], v[92:95]
	v_mfma_f32_16x16x32_bf16 v[88:91], v[188:191], v[204:207], v[88:91]
	v_mfma_f32_16x16x32_bf16 v[76:79], v[180:183], v[212:215], v[76:79]
	v_mfma_f32_16x16x32_bf16 v[72:75], v[188:191], v[212:215], v[72:75]
	v_mfma_f32_16x16x32_bf16 v[68:71], v[180:183], v[220:223], v[68:71]
	v_mfma_f32_16x16x32_bf16 v[64:67], v[188:191], v[220:223], v[64:67]
	s_waitcnt vmcnt(8)
	s_barrier
	s_add_i32 s27, s79, s3
	v_lshl_add_u64 v[224:225], s[42:43], 0, v[176:177]
	s_mov_b32 m0, s27
	ds_read_b128 v[192:195], v139 offset:16384
	ds_read_b128 v[196:199], v139 offset:17408
	ds_read_b128 v[200:203], v139 offset:18432
	ds_read_b128 v[204:207], v139 offset:19456
	ds_read_b128 v[208:211], v139 offset:20480
	ds_read_b128 v[212:215], v139 offset:21504
	ds_read_b128 v[216:219], v139 offset:22528
	ds_read_b128 v[220:223], v139 offset:23552
	global_load_lds_dwordx4 v[224:225], off
	s_add_i32 m0, s27, 0x2000
	v_lshl_add_u64 v[226:227], s[42:43], 0, v[128:129]
	s_add_u32 s42, s42, s10
	s_addc_u32 s43, s43, s11
	s_add_i32 s17, s17, s3
	global_load_lds_dwordx4 v[226:227], off
	v_lshl_add_u64 v[228:229], s[42:43], 0, v[176:177]
	s_mov_b32 m0, s17
	v_lshl_add_u64 v[230:231], s[42:43], 0, v[128:129]
	global_load_lds_dwordx4 v[228:229], off
	s_add_i32 m0, s17, 0x2000
	v_lshl_add_u64 v[232:233], s[96:97], 0, v[132:133]
	global_load_lds_dwordx4 v[230:231], off
	s_mov_b32 m0, s16
	v_lshl_add_u64 v[234:235], s[96:97], 0, v[130:131]
	global_load_lds_dwordx4 v[232:233], off
	s_mov_b32 m0, s14
	s_nop 0
	global_load_lds_dwordx4 v[234:235], off
	s_bitcmp1_b32 s101, 0
	s_cbranch_scc0 .Lvw_962_3
	s_waitcnt vmcnt(8)

; #define PG8_STAGE(bufoff, gbase, voff) do { _Pragma("unroll") for (int _i = 0; _i < 2; ++_i) \
;         __builtin_amdgcn_global_load_lds((const unsigned*)((const char*)(gbase) + (voff)[_i]), (LAS unsigned*)(lds + (bufoff) + ldsw + _i * 8192), 16, 0, 0); } while (0)
; #define PG8_LDA(dst, b, h) do { _Pragma("unroll") for (int m = 0; m < 4; ++m) _Pragma("unroll") for (int k = 0; k < 2; ++k) dst[m][k] = *(const LAS bf16x8*)(lds + PG8_SA(b, h) + aoff + m * 2048 + k * 1024); } while (0)
; #define PG8_LDB(dst, b, h) do { _Pragma("unroll") for (int n = 0; n < 2; ++n) _Pragma("unroll") for (int k = 0; k < 2; ++k) dst[n][k] = *(const LAS bf16x8*)(lds + PG8_SB(b, h) + boff + n * 2048 + k * 1024); } while (0)
; #define PG8_MMA(ai, bj, At, Bt) do { __builtin_amdgcn_s_setprio(1); _Pragma("unroll") for (int m = 0; m < 4; ++m) _Pragma("unroll") for (int n = 0; n < 2; ++n) _Pragma("unroll") for (int k = 0; k < 2; ++k) \
;         acc[ai][bj][m][n] = __builtin_amdgcn_mfma_f32_16x16x32_bf16(Bt[n][k], At[m][k], acc[ai][bj][m][n], 0, 0, 0); __builtin_amdgcn_s_setprio(0); } while (0)
; #define PG8_WAIT_V(n) asm volatile("s_waitcnt vmcnt(" #n ")" ::: "memory")
; #define PG8_WAIT_L(n) asm volatile("s_waitcnt lgkmcnt(" #n ")" ::: "memory")
; #define PG8_BAR __builtin_amdgcn_s_barrier()
; #define PG8_SCHED __builtin_amdgcn_sched_barrier(0)
; template <class Epi, class Sched, bool ALIGN_EPI>
; __device__ __forceinline__ void gemm_phase(LAS unsigned char* lds, const int wid, const int lda_, const int ldb_, const int K_, const Sched& S, const Epi& E) {
;     ...
;             PG8_LDB(B0, 1, 0); PG8_LDB(B1, 1, 1); PG8_SCHED; PG8_LDA(At, 1, 0); PG8_STAGE(PG8_SA(0, 1), a2 + hstepA, voffA);
;             PG8_WAIT_V(8); PG8_WAIT_L(0); PG8_BAR; PG8_MMA(0, 0, At, B0); PG8_MMA(0, 1, At, B1); PG8_BAR; PG8_SCHED;
.Lgemm_join_962:
	s_add_i32 s17, 0, 0x18000
	v_add_u32_e32 v141, s17, v135
	s_add_i32 s27, 0, 0x1c000
	ds_read_b128 v[156:159], v141
	ds_read_b128 v[160:163], v141 offset:1024
	ds_read_b128 v[164:167], v141 offset:2048
	ds_read_b128 v[168:171], v141 offset:3072
	v_add_u32_e32 v141, s27, v135
	ds_read_b128 v[172:175], v141
	ds_read_b128 v[180:183], v141 offset:1024
	ds_read_b128 v[184:187], v141 offset:2048
	ds_read_b128 v[188:191], v141 offset:3072
	s_add_u32 s42, s96, s0
	s_addc_u32 s43, s97, s1
	s_mov_b32 m0, s15
	v_lshl_add_u64 v[236:237], s[42:43], 0, v[132:133]
	ds_read_b128 v[192:195], v139 offset:32768
	ds_read_b128 v[196:199], v139 offset:33792
	ds_read_b128 v[200:203], v139 offset:34816
	ds_read_b128 v[204:207], v139 offset:35840
	ds_read_b128 v[208:211], v139 offset:36864
	ds_read_b128 v[212:215], v139 offset:37888
	ds_read_b128 v[216:219], v139 offset:38912
	ds_read_b128 v[220:223], v139 offset:39936
	global_load_lds_dwordx4 v[236:237], off
	v_lshl_add_u64 v[236:237], s[42:43], 0, v[130:131]
	s_mov_b32 m0, s26
	s_nop 0
	global_load_lds_dwordx4 v[236:237], off
	s_bitcmp1_b32 s101, 0
	s_cbranch_scc0 .Lvw_962_4
	s_waitcnt vmcnt(8)

; #define PG8_MMA(ai, bj, At, Bt) do { __builtin_amdgcn_s_setprio(1); _Pragma("unroll") for (int m = 0; m < 4; ++m) _Pragma("unroll") for (int n = 0; n < 2; ++n) _Pragma("unroll") for (int k = 0; k < 2; ++k) \
;         acc[ai][bj][m][n] = __builtin_amdgcn_mfma_f32_16x16x32_bf16(Bt[n][k], At[m][k], acc[ai][bj][m][n], 0, 0, 0); __builtin_amdgcn_s_setprio(0); } while (0)
; #define PG8_WAIT_V(n) asm volatile("s_waitcnt vmcnt(" #n ")" ::: "memory")
; #define PG8_WAIT_L(n) asm volatile("s_waitcnt lgkmcnt(" #n ")" ::: "memory")
; #define PG8_BAR __builtin_amdgcn_s_barrier()
; #define PG8_SCHED __builtin_amdgcn_sched_barrier(0)
; template <class Epi, class Sched, bool ALIGN_EPI>
; __device__ __forceinline__ void gemm_phase(LAS unsigned char* lds, const int wid, const int lda_, const int ldb_, const int K_, const Sched& S, const Epi& E) {
;     ...
;             PG8_WAIT_V(8); PG8_WAIT_L(0); PG8_BAR; PG8_MMA(1, 0, At, B0); PG8_MMA(1, 1, At, B1); PG8_BAR; PG8_SCHED;
;         }
;     __device__ __forceinline__ void out(const pg8::Unit& u, char*& o, int& ldo, int& kind) const { ldo = D;
;         if (u.kq < 0) { o = (char*)ws + YOFF + ((size_t)u.pm * 256 * D + (size_t)u.pn * 256) * 2; kind = 0; }
;         else { o = (char*)ws + WS_PART + (((size_t)u.kq * MCTX + (size_t)(u.pm - 64) * 256) * D + (size_t)u.pn * 256) * 2; kind = 0; } }
.Lvw_962_5:
	s_waitcnt lgkmcnt(0)
	s_barrier
	s_waitcnt lgkmcnt(0)
	v_mfma_f32_16x16x32_bf16 v[60:63], v[156:159], v[192:195], v[60:63]
	v_mfma_f32_16x16x32_bf16 v[56:59], v[164:167], v[192:195], v[56:59]
	v_mfma_f32_16x16x32_bf16 v[52:55], v[156:159], v[200:203], v[52:55]
	v_mfma_f32_16x16x32_bf16 v[48:51], v[164:167], v[200:203], v[48:51]
	v_mfma_f32_16x16x32_bf16 v[36:39], v[156:159], v[208:211], v[36:39]
	v_mfma_f32_16x16x32_bf16 v[32:35], v[164:167], v[208:211], v[32:35]
	v_mfma_f32_16x16x32_bf16 v[20:23], v[156:159], v[216:219], v[20:23]
	v_mfma_f32_16x16x32_bf16 v[16:19], v[164:167], v[216:219], v[16:19]
	v_mfma_f32_16x16x32_bf16 v[60:63], v[160:163], v[196:199], v[60:63]
	v_mfma_f32_16x16x32_bf16 v[56:59], v[168:171], v[196:199], v[56:59]
	v_mfma_f32_16x16x32_bf16 v[52:55], v[160:163], v[204:207], v[52:55]
	v_mfma_f32_16x16x32_bf16 v[48:51], v[168:171], v[204:207], v[48:51]
	v_mfma_f32_16x16x32_bf16 v[36:39], v[160:163], v[212:215], v[36:39]
	v_mfma_f32_16x16x32_bf16 v[32:35], v[168:171], v[212:215], v[32:35]
	v_mfma_f32_16x16x32_bf16 v[20:23], v[160:163], v[220:223], v[20:23]
	v_mfma_f32_16x16x32_bf16 v[16:19], v[168:171], v[220:223], v[16:19]
	v_mfma_f32_16x16x32_bf16 v[44:47], v[172:175], v[192:195], v[44:47]
	v_mfma_f32_16x16x32_bf16 v[40:43], v[184:187], v[192:195], v[40:43]
	v_mfma_f32_16x16x32_bf16 v[28:31], v[172:175], v[200:203], v[28:31]
	v_mfma_f32_16x16x32_bf16 v[24:27], v[184:187], v[200:203], v[24:27]
	v_mfma_f32_16x16x32_bf16 v[12:15], v[172:175], v[208:211], v[12:15]
	v_mfma_f32_16x16x32_bf16 v[8:11], v[184:187], v[208:211], v[8:11]
	v_mfma_f32_16x16x32_bf16 v[4:7], v[172:175], v[216:219], v[4:7]
	v_mfma_f32_16x16x32_bf16 v[0:3], v[184:187], v[216:219], v[0:3]
	v_mfma_f32_16x16x32_bf16 v[44:47], v[180:183], v[196:199], v[44:47]
	v_mfma_f32_16x16x32_bf16 v[40:43], v[188:191], v[196:199], v[40:43]
	v_mfma_f32_16x16x32_bf16 v[28:31], v[180:183], v[204:207], v[28:31]
	v_mfma_f32_16x16x32_bf16 v[24:27], v[188:191], v[204:207], v[24:27]
	v_mfma_f32_16x16x32_bf16 v[12:15], v[180:183], v[212:215], v[12:15]
	v_mfma_f32_16x16x32_bf16 v[8:11], v[188:191], v[212:215], v[8:11]
	v_mfma_f32_16x16x32_bf16 v[4:7], v[180:183], v[220:223], v[4:7]
	v_mfma_f32_16x16x32_bf16 v[0:3], v[188:191], v[220:223], v[0:3]
	s_waitcnt vmcnt(8)
	s_barrier
	s_add_u32 s94, s94, 0x100
	s_addc_u32 s95, s95, 0
	s_add_u32 s49, s49, 0x100
	s_addc_u32 s76, s76, 0
	s_cmp_ge_u32 s78, s45
	s_mov_b32 s77, s78
	s_cbranch_scc0 .LBB0_962
	s_setprio 2
	s_mov_b64 s[94:95], -1
	s_and_b64 vcc, exec, s[50:51]
	s_cbranch_vccz .LBB0_965
	s_mov_b32 s49, s92
	s_ashr_i32 s47, s46, 31
	s_ashr_i32 s45, s44, 31
	s_lshl_b64 s[4:5], s[46:47], 20
	s_lshl_b64 s[42:43], s[44:45], 9
	s_lshl_b64 s[48:49], s[48:49], 23
	v_readlane_b32 s50, v251, 28
	v_readlane_b32 s51, v251, 29
	s_add_u32 s17, s50, s42
	s_addc_u32 s27, s51, s43
	s_add_u32 s17, s17, s48
	s_addc_u32 s27, s27, s49
	s_add_u32 s4, s17, s4
	s_addc_u32 s5, s27, s5
	s_add_u32 s4, s4, 0xfc000000
	s_addc_u32 s5, s5, -1
	s_mov_b64 s[94:95], 0

; #define PG8_STAGE(bufoff, gbase, voff) do { _Pragma("unroll") for (int _i = 0; _i < 2; ++_i) \
;         __builtin_amdgcn_global_load_lds((const unsigned*)((const char*)(gbase) + (voff)[_i]), (LAS unsigned*)(lds + (bufoff) + ldsw + _i * 8192), 16, 0, 0); } while (0)
; #define PG8_LDA(dst, b, h) do { _Pragma("unroll") for (int m = 0; m < 4; ++m) _Pragma("unroll") for (int k = 0; k < 2; ++k) dst[m][k] = *(const LAS bf16x8*)(lds + PG8_SA(b, h) + aoff + m * 2048 + k * 1024); } while (0)
; #define PG8_LDB(dst, b, h) do { _Pragma("unroll") for (int n = 0; n < 2; ++n) _Pragma("unroll") for (int k = 0; k < 2; ++k) dst[n][k] = *(const LAS bf16x8*)(lds + PG8_SB(b, h) + boff + n * 2048 + k * 1024); } while (0)
; #define PG8_WAIT_V(n) asm volatile("s_waitcnt vmcnt(" #n ")" ::: "memory")
; #define PG8_BAR __builtin_amdgcn_s_barrier()
; template <class Epi, class Sched, bool ALIGN_EPI>
; __device__ __forceinline__ void gemm_phase(LAS unsigned char* lds, const int wid, const int lda_, const int ldb_, const int K_, const Sched& S, const Epi& E) {
;     ...
;         const bool has_next = S.next(ui + 1, nxt);
;         const int nt = S.nt(cur);
;         const char* nA = has_next ? S.a(nxt) : cA; const char* nB = has_next ? S.b(nxt) : cB;
; #pragma unroll 1
;         for (int t = 0; t < nt; t += 2) {
;             const bool last = (t == nt - 2);
;             const char* a1 = cA + (size_t)(t + 1) * kstep;
;             const char* a2 = last ? nA : cA + (size_t)(t + 2) * kstep; const char* b2 = last ? nB : cB + (size_t)(t + 2) * kstep;
;             const char* a3 = a2 + kstep; const char* b3 = b2 + kstep;
;             PG8_LDB(B0, 0, 0); PG8_LDB(B1, 0, 1); PG8_SCHED; PG8_LDA(At, 0, 0); PG8_STAGE(PG8_SA(1, 1), a1 + hstepA, voffA);
;             PG8_WAIT_V(8); PG8_WAIT_L(0); PG8_BAR; PG8_MMA(0, 0, At, B0); PG8_MMA(0, 1, At, B1); PG8_BAR; PG8_SCHED;
;             PG8_LDA(At, 0, 1); PG8_STAGE(PG8_SB(0, 0), b2, voffB); PG8_STAGE(PG8_SB(0, 1), b2 + hstepB, voffB); PG8_STAGE(PG8_SA(0, 0), a2, voffA);
;             PG8_WAIT_V(8); PG8_WAIT_L(0); PG8_BAR; PG8_MMA(1, 0, At, B0); PG8_MMA(1, 1, At, B1); PG8_BAR; PG8_SCHED;
;     __device__ __forceinline__ const char* a(const pg8::Unit& u) const { return (const char*)ws + WS_A + (size_t)u.pm * 256 * D * 2; }
;     __device__ __forceinline__ const char* b(const pg8::Unit& u) const { return (const char*)ws + boff + (size_t)u.pn * 256 * D * 2; }
.LBB0_1119:
	v_mov_b64_e32 v[0:1], s[0:1]
	s_ashr_i32 s45, s44, 31
	v_cmp_lt_i64_e32 vcc, s[4:5], v[0:1]
	s_lshl_b64 s[4:5], s[44:45], 20
	v_readlane_b32 s46, v253, 52
	v_readlane_b32 s47, v253, 53
	s_add_u32 s46, s46, s4
	s_addc_u32 s47, s47, s5
	s_and_b64 s[4:5], vcc, exec
	s_cselect_b32 s4, s47, s41
	s_cselect_b32 s5, s46, s40
	s_ashr_i32 s43, s42, 31
	s_lshl_b64 s[48:49], s[42:43], 20
	s_add_u32 s48, s15, s48
	s_addc_u32 s49, s26, s49
	s_and_b64 s[76:77], vcc, exec
	s_cselect_b32 s43, s49, s51
	s_cselect_b32 s45, s48, s50
	s_add_u32 s76, s40, 0x80
	s_addc_u32 s77, s41, 0
	v_lshl_add_u64 v[156:157], s[76:77], 0, v[152:153]
	v_lshl_add_u64 v[158:159], s[76:77], 0, v[154:155]
	s_add_u32 s76, s50, 0x100
	s_addc_u32 s77, s51, 0
	s_mov_b32 s78, -2
	s_mov_b64 s[50:51], 0
	s_add_u32 s17, s40, s50
	s_addc_u32 s27, s41, s51
	s_add_u32 s17, s17, 0x100
	s_addc_u32 s27, s27, 0
	s_add_u32 s79, s76, s50
	s_addc_u32 s80, s77, s51
	s_add_i32 s86, 0, 0x10000
	s_cmpk_eq_i32 s50, 0xf00
	s_cselect_b32 s95, s4, s27
	s_cselect_b32 s94, s5, s17
	v_add_u32_e32 v141, s86, v135
	s_cselect_b32 s81, s43, s80
	s_cselect_b32 s80, s45, s79
	s_add_i32 s17, 0, 0x14000
	ds_read_b128 v[160:163], v141
	ds_read_b128 v[164:167], v141 offset:1024
	ds_read_b128 v[168:171], v141 offset:2048
	ds_read_b128 v[172:175], v141 offset:3072
	v_add_u32_e32 v141, s17, v135
	ds_read_b128 v[180:183], v141
	ds_read_b128 v[184:187], v141 offset:1024
	ds_read_b128 v[188:191], v141 offset:2048
	ds_read_b128 v[192:195], v141 offset:3072
	v_lshl_add_u64 v[228:229], v[158:159], 0, s[50:51]
	s_add_i32 m0, s16, 0xc000
	ds_read_b128 v[196:199], v139
	ds_read_b128 v[200:203], v139 offset:1024
	ds_read_b128 v[204:207], v139 offset:2048
	ds_read_b128 v[208:211], v139 offset:3072
	ds_read_b128 v[212:215], v139 offset:4096
	ds_read_b128 v[216:219], v139 offset:5120
	ds_read_b128 v[220:223], v139 offset:6144
	ds_read_b128 v[224:227], v139 offset:7168
	global_load_lds_dwordx4 v[228:229], off
	v_lshl_add_u64 v[228:229], v[156:157], 0, s[50:51]
	s_add_i32 m0, s16, 0xe000
	s_nop 0
	global_load_lds_dwordx4 v[228:229], off
	v_readlane_b32 s101, v252, 58
	s_nop 3
	s_bitcmp1_b32 s101, 0
	s_cbranch_scc0 .Lvw_1120_0
	s_waitcnt vmcnt(8)
.Lvw_1120_0:
	s_waitcnt lgkmcnt(0)
	s_barrier
	s_setprio 0
	s_waitcnt lgkmcnt(0)
	v_mfma_f32_16x16x32_bf16 v[124:127], v[160:163], v[196:199], 0
	v_mfma_f32_16x16x32_bf16 v[120:123], v[168:171], v[196:199], 0
	v_mfma_f32_16x16x32_bf16 v[116:119], v[160:163], v[204:207], 0
	v_mfma_f32_16x16x32_bf16 v[112:115], v[168:171], v[204:207], 0
	v_mfma_f32_16x16x32_bf16 v[100:103], v[160:163], v[212:215], 0
	v_mfma_f32_16x16x32_bf16 v[96:99], v[168:171], v[212:215], 0
	v_mfma_f32_16x16x32_bf16 v[84:87], v[160:163], v[220:223], 0
	v_mfma_f32_16x16x32_bf16 v[80:83], v[168:171], v[220:223], 0
	v_mfma_f32_16x16x32_bf16 v[124:127], v[164:167], v[200:203], v[124:127]
	v_mfma_f32_16x16x32_bf16 v[120:123], v[172:175], v[200:203], v[120:123]
	v_mfma_f32_16x16x32_bf16 v[116:119], v[164:167], v[208:211], v[116:119]
	v_mfma_f32_16x16x32_bf16 v[112:115], v[172:175], v[208:211], v[112:115]
	v_mfma_f32_16x16x32_bf16 v[100:103], v[164:167], v[216:219], v[100:103]
	v_mfma_f32_16x16x32_bf16 v[96:99], v[172:175], v[216:219], v[96:99]
	v_mfma_f32_16x16x32_bf16 v[84:87], v[164:167], v[224:227], v[84:87]
	v_mfma_f32_16x16x32_bf16 v[80:83], v[172:175], v[224:227], v[80:83]
	v_mfma_f32_16x16x32_bf16 v[108:111], v[180:183], v[196:199], 0
	v_mfma_f32_16x16x32_bf16 v[104:107], v[188:191], v[196:199], 0
	v_mfma_f32_16x16x32_bf16 v[92:95], v[180:183], v[204:207], 0
	v_mfma_f32_16x16x32_bf16 v[88:91], v[188:191], v[204:207], 0
	v_mfma_f32_16x16x32_bf16 v[76:79], v[180:183], v[212:215], 0
	v_mfma_f32_16x16x32_bf16 v[72:75], v[188:191], v[212:215], 0
	v_mfma_f32_16x16x32_bf16 v[68:71], v[180:183], v[220:223], 0
	v_mfma_f32_16x16x32_bf16 v[64:67], v[188:191], v[220:223], 0
	v_mfma_f32_16x16x32_bf16 v[108:111], v[184:187], v[200:203], v[108:111]
	v_mfma_f32_16x16x32_bf16 v[104:107], v[192:195], v[200:203], v[104:107]
	v_mfma_f32_16x16x32_bf16 v[92:95], v[184:187], v[208:211], v[92:95]
	v_mfma_f32_16x16x32_bf16 v[88:91], v[192:195], v[208:211], v[88:91]
	v_mfma_f32_16x16x32_bf16 v[76:79], v[184:187], v[216:219], v[76:79]
	v_mfma_f32_16x16x32_bf16 v[72:75], v[192:195], v[216:219], v[72:75]
	v_mfma_f32_16x16x32_bf16 v[68:71], v[184:187], v[224:227], v[68:71]
	v_mfma_f32_16x16x32_bf16 v[64:67], v[192:195], v[224:227], v[64:67]
	s_waitcnt vmcnt(8)
	s_barrier
	s_add_i32 s27, s86, s3
	v_lshl_add_u64 v[228:229], s[80:81], 0, v[176:177]
	s_mov_b32 m0, s27
	ds_read_b128 v[196:199], v139 offset:16384
	ds_read_b128 v[200:203], v139 offset:17408
	ds_read_b128 v[204:207], v139 offset:18432
	ds_read_b128 v[208:211], v139 offset:19456
	ds_read_b128 v[212:215], v139 offset:20480
	ds_read_b128 v[216:219], v139 offset:21504
	ds_read_b128 v[220:223], v139 offset:22528
	ds_read_b128 v[224:227], v139 offset:23552
	global_load_lds_dwordx4 v[228:229], off
	s_add_i32 m0, s27, 0x2000
	v_lshl_add_u64 v[230:231], s[80:81], 0, v[128:129]
	s_add_u32 s80, s80, s30
	s_addc_u32 s81, s81, s31
	s_add_i32 s17, s17, s3
	global_load_lds_dwordx4 v[230:231], off
	v_lshl_add_u64 v[232:233], s[80:81], 0, v[176:177]
	s_mov_b32 m0, s17
	v_lshl_add_u64 v[234:235], s[80:81], 0, v[128:129]
	global_load_lds_dwordx4 v[232:233], off
	s_add_i32 m0, s17, 0x2000
	v_lshl_add_u64 v[236:237], s[94:95], 0, v[132:133]
	global_load_lds_dwordx4 v[234:235], off
	s_mov_b32 m0, s16
	v_lshl_add_u64 v[246:247], s[94:95], 0, v[130:131]
	global_load_lds_dwordx4 v[236:237], off
	s_mov_b32 m0, s35
	s_nop 0
	global_load_lds_dwordx4 v[246:247], off
	s_bitcmp1_b32 s101, 0
	s_cbranch_scc0 .Lvw_1120_1
	s_waitcnt vmcnt(8)

; #define PG8_STAGE(bufoff, gbase, voff) do { _Pragma("unroll") for (int _i = 0; _i < 2; ++_i) \
;         __builtin_amdgcn_global_load_lds((const unsigned*)((const char*)(gbase) + (voff)[_i]), (LAS unsigned*)(lds + (bufoff) + ldsw + _i * 8192), 16, 0, 0); } while (0)
; #define PG8_LDA(dst, b, h) do { _Pragma("unroll") for (int m = 0; m < 4; ++m) _Pragma("unroll") for (int k = 0; k < 2; ++k) dst[m][k] = *(const LAS bf16x8*)(lds + PG8_SA(b, h) + aoff + m * 2048 + k * 1024); } while (0)
; #define PG8_LDB(dst, b, h) do { _Pragma("unroll") for (int n = 0; n < 2; ++n) _Pragma("unroll") for (int k = 0; k < 2; ++k) dst[n][k] = *(const LAS bf16x8*)(lds + PG8_SB(b, h) + boff + n * 2048 + k * 1024); } while (0)
; #define PG8_MMA(ai, bj, At, Bt) do { __builtin_amdgcn_s_setprio(1); _Pragma("unroll") for (int m = 0; m < 4; ++m) _Pragma("unroll") for (int n = 0; n < 2; ++n) _Pragma("unroll") for (int k = 0; k < 2; ++k) \
;         acc[ai][bj][m][n] = __builtin_amdgcn_mfma_f32_16x16x32_bf16(Bt[n][k], At[m][k], acc[ai][bj][m][n], 0, 0, 0); __builtin_amdgcn_s_setprio(0); } while (0)
; #define PG8_WAIT_V(n) asm volatile("s_waitcnt vmcnt(" #n ")" ::: "memory")
; #define PG8_WAIT_L(n) asm volatile("s_waitcnt lgkmcnt(" #n ")" ::: "memory")
; #define PG8_BAR __builtin_amdgcn_s_barrier()
; #define PG8_SCHED __builtin_amdgcn_sched_barrier(0)
; template <class Epi, class Sched, bool ALIGN_EPI>
; __device__ __forceinline__ void gemm_phase(LAS unsigned char* lds, const int wid, const int lda_, const int ldb_, const int K_, const Sched& S, const Epi& E) {
;     ...
;             const bool last = (t == nt - 2);
;             const char* a1 = cA + (size_t)(t + 1) * kstep;
;             const char* a2 = last ? nA : cA + (size_t)(t + 2) * kstep; const char* b2 = last ? nB : cB + (size_t)(t + 2) * kstep;
;             const char* a3 = a2 + kstep; const char* b3 = b2 + kstep;
;             PG8_LDB(B0, 0, 0); PG8_LDB(B1, 0, 1); PG8_SCHED; PG8_LDA(At, 0, 0); PG8_STAGE(PG8_SA(1, 1), a1 + hstepA, voffA);
;             PG8_WAIT_V(8); PG8_WAIT_L(0); PG8_BAR; PG8_MMA(0, 0, At, B0); PG8_MMA(0, 1, At, B1); PG8_BAR; PG8_SCHED;
;             PG8_LDA(At, 0, 1); PG8_STAGE(PG8_SB(0, 0), b2, voffB); PG8_STAGE(PG8_SB(0, 1), b2 + hstepB, voffB); PG8_STAGE(PG8_SA(0, 0), a2, voffA);
;             PG8_WAIT_V(8); PG8_WAIT_L(0); PG8_BAR; PG8_MMA(1, 0, At, B0); PG8_MMA(1, 1, At, B1); PG8_BAR; PG8_SCHED;
.LBB0_1120:
	s_add_u32 s17, s40, s50
	s_addc_u32 s27, s41, s51
	s_add_u32 s17, s17, 0x100
	s_addc_u32 s27, s27, 0
	s_add_u32 s79, s76, s50
	s_addc_u32 s80, s77, s51
	s_add_i32 s86, 0, 0x10000
	s_cmpk_eq_i32 s50, 0xf00
	s_cselect_b32 s95, s4, s27
	s_cselect_b32 s94, s5, s17
	v_add_u32_e32 v141, s86, v135
	s_cselect_b32 s81, s43, s80
	s_cselect_b32 s80, s45, s79
	s_add_i32 s17, 0, 0x14000
	ds_read_b128 v[160:163], v141
	ds_read_b128 v[164:167], v141 offset:1024
	ds_read_b128 v[168:171], v141 offset:2048
	ds_read_b128 v[172:175], v141 offset:3072
	v_add_u32_e32 v141, s17, v135
	ds_read_b128 v[180:183], v141
	ds_read_b128 v[184:187], v141 offset:1024
	ds_read_b128 v[188:191], v141 offset:2048
	ds_read_b128 v[192:195], v141 offset:3072
	v_lshl_add_u64 v[228:229], v[158:159], 0, s[50:51]
	s_add_i32 m0, s16, 0xc000
	ds_read_b128 v[196:199], v139
	ds_read_b128 v[200:203], v139 offset:1024
	ds_read_b128 v[204:207], v139 offset:2048
	ds_read_b128 v[208:211], v139 offset:3072
	ds_read_b128 v[212:215], v139 offset:4096
	ds_read_b128 v[216:219], v139 offset:5120
	ds_read_b128 v[220:223], v139 offset:6144
	ds_read_b128 v[224:227], v139 offset:7168
	global_load_lds_dwordx4 v[228:229], off
	v_lshl_add_u64 v[228:229], v[156:157], 0, s[50:51]
	s_add_i32 m0, s16, 0xe000
	s_nop 0
	global_load_lds_dwordx4 v[228:229], off
	s_bitcmp1_b32 s101, 0
	s_cbranch_scc0 .Lvw_1120_2
	s_waitcnt vmcnt(8)
.Lvw_1120_2:
	s_waitcnt lgkmcnt(0)
	s_barrier
	s_waitcnt lgkmcnt(0)
	v_mfma_f32_16x16x32_bf16 v[124:127], v[160:163], v[196:199], v[124:127]
	v_mfma_f32_16x16x32_bf16 v[120:123], v[168:171], v[196:199], v[120:123]
	v_mfma_f32_16x16x32_bf16 v[116:119], v[160:163], v[204:207], v[116:119]
	v_mfma_f32_16x16x32_bf16 v[112:115], v[168:171], v[204:207], v[112:115]
	v_mfma_f32_16x16x32_bf16 v[100:103], v[160:163], v[212:215], v[100:103]
	v_mfma_f32_16x16x32_bf16 v[96:99], v[168:171], v[212:215], v[96:99]
	v_mfma_f32_16x16x32_bf16 v[84:87], v[160:163], v[220:223], v[84:87]
	v_mfma_f32_16x16x32_bf16 v[80:83], v[168:171], v[220:223], v[80:83]
	v_mfma_f32_16x16x32_bf16 v[124:127], v[164:167], v[200:203], v[124:127]
	v_mfma_f32_16x16x32_bf16 v[120:123], v[172:175], v[200:203], v[120:123]
	v_mfma_f32_16x16x32_bf16 v[116:119], v[164:167], v[208:211], v[116:119]
	v_mfma_f32_16x16x32_bf16 v[112:115], v[172:175], v[208:211], v[112:115]
	v_mfma_f32_16x16x32_bf16 v[100:103], v[164:167], v[216:219], v[100:103]
	v_mfma_f32_16x16x32_bf16 v[96:99], v[172:175], v[216:219], v[96:99]
	v_mfma_f32_16x16x32_bf16 v[84:87], v[164:167], v[224:227], v[84:87]
	v_mfma_f32_16x16x32_bf16 v[80:83], v[172:175], v[224:227], v[80:83]
	v_mfma_f32_16x16x32_bf16 v[108:111], v[180:183], v[196:199], v[108:111]
	v_mfma_f32_16x16x32_bf16 v[104:107], v[188:191], v[196:199], v[104:107]
	v_mfma_f32_16x16x32_bf16 v[92:95], v[180:183], v[204:207], v[92:95]
	v_mfma_f32_16x16x32_bf16 v[88:91], v[188:191], v[204:207], v[88:91]
	v_mfma_f32_16x16x32_bf16 v[76:79], v[180:183], v[212:215], v[76:79]
	v_mfma_f32_16x16x32_bf16 v[72:75], v[188:191], v[212:215], v[72:75]
	v_mfma_f32_16x16x32_bf16 v[68:71], v[180:183], v[220:223], v[68:71]
	v_mfma_f32_16x16x32_bf16 v[64:67], v[188:191], v[220:223], v[64:67]
	v_mfma_f32_16x16x32_bf16 v[108:111], v[184:187], v[200:203], v[108:111]
	v_mfma_f32_16x16x32_bf16 v[104:107], v[192:195], v[200:203], v[104:107]
	v_mfma_f32_16x16x32_bf16 v[92:95], v[184:187], v[208:211], v[92:95]
	v_mfma_f32_16x16x32_bf16 v[88:91], v[192:195], v[208:211], v[88:91]
	v_mfma_f32_16x16x32_bf16 v[76:79], v[184:187], v[216:219], v[76:79]
	v_mfma_f32_16x16x32_bf16 v[72:75], v[192:195], v[216:219], v[72:75]
	v_mfma_f32_16x16x32_bf16 v[68:71], v[184:187], v[224:227], v[68:71]
	v_mfma_f32_16x16x32_bf16 v[64:67], v[192:195], v[224:227], v[64:67]
	s_waitcnt vmcnt(8)
	s_barrier
	s_add_i32 s27, s86, s3
	v_lshl_add_u64 v[228:229], s[80:81], 0, v[176:177]
	s_mov_b32 m0, s27
	ds_read_b128 v[196:199], v139 offset:16384
	ds_read_b128 v[200:203], v139 offset:17408
	ds_read_b128 v[204:207], v139 offset:18432
	ds_read_b128 v[208:211], v139 offset:19456
	ds_read_b128 v[212:215], v139 offset:20480
	ds_read_b128 v[216:219], v139 offset:21504
	ds_read_b128 v[220:223], v139 offset:22528
	ds_read_b128 v[224:227], v139 offset:23552
	global_load_lds_dwordx4 v[228:229], off
	s_add_i32 m0, s27, 0x2000
	v_lshl_add_u64 v[230:231], s[80:81], 0, v[128:129]
	s_add_u32 s80, s80, s30
	s_addc_u32 s81, s81, s31
	s_add_i32 s17, s17, s3
	global_load_lds_dwordx4 v[230:231], off
	v_lshl_add_u64 v[232:233], s[80:81], 0, v[176:177]
	s_mov_b32 m0, s17
	v_lshl_add_u64 v[234:235], s[80:81], 0, v[128:129]
	global_load_lds_dwordx4 v[232:233], off
	s_add_i32 m0, s17, 0x2000
	v_lshl_add_u64 v[236:237], s[94:95], 0, v[132:133]
	global_load_lds_dwordx4 v[234:235], off
	s_mov_b32 m0, s16
	v_lshl_add_u64 v[246:247], s[94:95], 0, v[130:131]
	global_load_lds_dwordx4 v[236:237], off
	s_mov_b32 m0, s35
	s_nop 0
	global_load_lds_dwordx4 v[246:247], off
	s_bitcmp1_b32 s101, 0
	s_cbranch_scc0 .Lvw_1120_3
	s_waitcnt vmcnt(8)

; #define PG8_STAGE(bufoff, gbase, voff) do { _Pragma("unroll") for (int _i = 0; _i < 2; ++_i) \
;         __builtin_amdgcn_global_load_lds((const unsigned*)((const char*)(gbase) + (voff)[_i]), (LAS unsigned*)(lds + (bufoff) + ldsw + _i * 8192), 16, 0, 0); } while (0)
; #define PG8_LDA(dst, b, h) do { _Pragma("unroll") for (int m = 0; m < 4; ++m) _Pragma("unroll") for (int k = 0; k < 2; ++k) dst[m][k] = *(const LAS bf16x8*)(lds + PG8_SA(b, h) + aoff + m * 2048 + k * 1024); } while (0)
; #define PG8_LDB(dst, b, h) do { _Pragma("unroll") for (int n = 0; n < 2; ++n) _Pragma("unroll") for (int k = 0; k < 2; ++k) dst[n][k] = *(const LAS bf16x8*)(lds + PG8_SB(b, h) + boff + n * 2048 + k * 1024); } while (0)
; #define PG8_MMA(ai, bj, At, Bt) do { __builtin_amdgcn_s_setprio(1); _Pragma("unroll") for (int m = 0; m < 4; ++m) _Pragma("unroll") for (int n = 0; n < 2; ++n) _Pragma("unroll") for (int k = 0; k < 2; ++k) \
;         acc[ai][bj][m][n] = __builtin_amdgcn_mfma_f32_16x16x32_bf16(Bt[n][k], At[m][k], acc[ai][bj][m][n], 0, 0, 0); __builtin_amdgcn_s_setprio(0); } while (0)
; #define PG8_WAIT_V(n) asm volatile("s_waitcnt vmcnt(" #n ")" ::: "memory")
; #define PG8_WAIT_L(n) asm volatile("s_waitcnt lgkmcnt(" #n ")" ::: "memory")
; #define PG8_BAR __builtin_amdgcn_s_barrier()
; #define PG8_SCHED __builtin_amdgcn_sched_barrier(0)
; template <class Epi, class Sched, bool ALIGN_EPI>
; __device__ __forceinline__ void gemm_phase(LAS unsigned char* lds, const int wid, const int lda_, const int ldb_, const int K_, const Sched& S, const Epi& E) {
;     ...
;             PG8_LDB(B0, 1, 0); PG8_LDB(B1, 1, 1); PG8_SCHED; PG8_LDA(At, 1, 0); PG8_STAGE(PG8_SA(0, 1), a2 + hstepA, voffA);
;             PG8_WAIT_V(8); PG8_WAIT_L(0); PG8_BAR; PG8_MMA(0, 0, At, B0); PG8_MMA(0, 1, At, B1); PG8_BAR; PG8_SCHED;
.Lgemm_join_1120:
	s_add_i32 s17, 0, 0x18000
	v_add_u32_e32 v141, s17, v135
	s_add_i32 s27, 0, 0x1c000
	ds_read_b128 v[160:163], v141
	ds_read_b128 v[164:167], v141 offset:1024
	ds_read_b128 v[168:171], v141 offset:2048
	ds_read_b128 v[172:175], v141 offset:3072
	v_add_u32_e32 v141, s27, v135
	ds_read_b128 v[180:183], v141
	ds_read_b128 v[184:187], v141 offset:1024
	ds_read_b128 v[188:191], v141 offset:2048
	ds_read_b128 v[192:195], v141 offset:3072
	s_add_u32 s80, s94, s10
	s_addc_u32 s81, s95, s11
	s_mov_b32 m0, s39
	v_lshl_add_u64 v[248:249], s[80:81], 0, v[132:133]
	ds_read_b128 v[196:199], v139 offset:32768
	ds_read_b128 v[200:203], v139 offset:33792
	ds_read_b128 v[204:207], v139 offset:34816
	ds_read_b128 v[208:211], v139 offset:35840
	ds_read_b128 v[212:215], v139 offset:36864
	ds_read_b128 v[216:219], v139 offset:37888
	ds_read_b128 v[220:223], v139 offset:38912
	ds_read_b128 v[224:227], v139 offset:39936
	global_load_lds_dwordx4 v[248:249], off
	v_lshl_add_u64 v[248:249], s[80:81], 0, v[130:131]
	s_mov_b32 m0, s72
	s_nop 0
	global_load_lds_dwordx4 v[248:249], off
	s_bitcmp1_b32 s101, 0
	s_cbranch_scc0 .Lvw_1120_4
	s_waitcnt vmcnt(8)

; __device__ __forceinline__ unsigned cvt_pk_bf16(float lo, float hi) { const f32x2 v = {lo, hi}; return __builtin_bit_cast(unsigned, __builtin_convertvector(v, bf16x2_t)); }
;     template <class Sched> __device__ __forceinline__ void operator()(const f32x4 (&acc)[2][2][4][2], const Unit& u, const Sched& S, int wr, int wc, int fr, int fq) const {
;     ...
;         if (kind == 0) {
;             bf16_t* base = (bf16_t*)uo;
; #pragma unroll
;             for (int ai = 0; ai < 2; ++ai)
; #pragma unroll
;                 for (int m = 0; m < 4; ++m) { bf16_t* rowp = base + (size_t)(rl0 + ai * HALF + m * 16) * ldo + cl0;
; #pragma unroll
;                     for (int bj = 0; bj < 2; ++bj) { const f32x4 v0 = acc[ai][bj][m][0], v1 = acc[ai][bj][m][1];
;                         u32x4 w; w.x = cvt_pk_bf16(v0[0], v0[1]); w.y = cvt_pk_bf16(v0[2], v0[3]); w.z = cvt_pk_bf16(v1[0], v1[1]); w.w = cvt_pk_bf16(v1[2], v1[3]);
;                         *(u32x4*)(rowp + bj * HALF) = w; } }
.Lvw_1120_5:
	s_waitcnt lgkmcnt(0)
	s_barrier
	s_waitcnt lgkmcnt(0)
	v_mfma_f32_16x16x32_bf16 v[60:63], v[160:163], v[196:199], v[60:63]
	v_mfma_f32_16x16x32_bf16 v[56:59], v[168:171], v[196:199], v[56:59]
	v_mfma_f32_16x16x32_bf16 v[52:55], v[160:163], v[204:207], v[52:55]
	v_mfma_f32_16x16x32_bf16 v[48:51], v[168:171], v[204:207], v[48:51]
	v_mfma_f32_16x16x32_bf16 v[36:39], v[160:163], v[212:215], v[36:39]
	v_mfma_f32_16x16x32_bf16 v[32:35], v[168:171], v[212:215], v[32:35]
	v_mfma_f32_16x16x32_bf16 v[20:23], v[160:163], v[220:223], v[20:23]
	v_mfma_f32_16x16x32_bf16 v[16:19], v[168:171], v[220:223], v[16:19]
	v_mfma_f32_16x16x32_bf16 v[60:63], v[164:167], v[200:203], v[60:63]
	v_mfma_f32_16x16x32_bf16 v[56:59], v[172:175], v[200:203], v[56:59]
	v_mfma_f32_16x16x32_bf16 v[52:55], v[164:167], v[208:211], v[52:55]
	v_mfma_f32_16x16x32_bf16 v[48:51], v[172:175], v[208:211], v[48:51]
	v_mfma_f32_16x16x32_bf16 v[36:39], v[164:167], v[216:219], v[36:39]
	v_mfma_f32_16x16x32_bf16 v[32:35], v[172:175], v[216:219], v[32:35]
	v_mfma_f32_16x16x32_bf16 v[20:23], v[164:167], v[224:227], v[20:23]
	v_mfma_f32_16x16x32_bf16 v[16:19], v[172:175], v[224:227], v[16:19]
	v_mfma_f32_16x16x32_bf16 v[44:47], v[180:183], v[196:199], v[44:47]
	v_mfma_f32_16x16x32_bf16 v[40:43], v[188:191], v[196:199], v[40:43]
	v_mfma_f32_16x16x32_bf16 v[28:31], v[180:183], v[204:207], v[28:31]
	v_mfma_f32_16x16x32_bf16 v[24:27], v[188:191], v[204:207], v[24:27]
	v_mfma_f32_16x16x32_bf16 v[12:15], v[180:183], v[212:215], v[12:15]
	v_mfma_f32_16x16x32_bf16 v[8:11], v[188:191], v[212:215], v[8:11]
	v_mfma_f32_16x16x32_bf16 v[4:7], v[180:183], v[220:223], v[4:7]
	v_mfma_f32_16x16x32_bf16 v[0:3], v[188:191], v[220:223], v[0:3]
	v_mfma_f32_16x16x32_bf16 v[44:47], v[184:187], v[200:203], v[44:47]
	v_mfma_f32_16x16x32_bf16 v[40:43], v[192:195], v[200:203], v[40:43]
	v_mfma_f32_16x16x32_bf16 v[28:31], v[184:187], v[208:211], v[28:31]
	v_mfma_f32_16x16x32_bf16 v[24:27], v[192:195], v[208:211], v[24:27]
	v_mfma_f32_16x16x32_bf16 v[12:15], v[184:187], v[216:219], v[12:15]
	v_mfma_f32_16x16x32_bf16 v[8:11], v[192:195], v[216:219], v[8:11]
	v_mfma_f32_16x16x32_bf16 v[4:7], v[184:187], v[224:227], v[4:7]
	v_mfma_f32_16x16x32_bf16 v[0:3], v[192:195], v[224:227], v[0:3]
	s_waitcnt vmcnt(8)
	s_barrier
	s_add_i32 s78, s78, 2
	s_add_u32 s50, s50, 0x100
	s_addc_u32 s51, s51, 0
	s_cmp_gt_u32 s78, 29
	s_cbranch_scc0 .LBB0_1120
	s_setprio 2
	s_sub_i32 s4, s38, 22
	s_ashr_i32 s5, s38, 31
	s_cmp_lt_i32 s38, 22
	s_cselect_b32 s5, s5, 0
	s_cselect_b32 s4, s38, s4
	s_mov_b32 s17, 0x2bc00000
	s_cselect_b32 s17, 0x1f600000, s17
	s_lshl_b64 s[4:5], s[4:5], 9
	s_add_u32 s4, s66, s4
	s_addc_u32 s5, s67, s5
	s_add_u32 s4, s4, s17
	s_addc_u32 s5, s5, 0
	s_mul_i32 s27, s34, 0x2c0000
	s_mul_hi_i32 s17, s34, 0x2c0000
	s_add_u32 s4, s4, s27
	s_addc_u32 s5, s5, s17
	s_movk_i32 s17, 0x1600
	v_lshl_add_u64 v[156:157], v[136:137], 1, s[4:5]
	v_mad_i64_i32 v[158:159], s[4:5], s17, v134, 0
	v_lshl_add_u64 v[158:159], v[158:159], 1, v[156:157]
	v_cvt_pk_bf16_f32 v108, v108, v109
	v_cvt_pk_bf16_f32 v109, v110, v111
	v_cvt_pk_bf16_f32 v110, v104, v105
	v_cvt_pk_bf16_f32 v111, v106, v107
	v_mad_i64_i32 v[104:105], s[4:5], s17, v138, 0
	v_cvt_pk_bf16_f32 v124, v124, v125
	v_cvt_pk_bf16_f32 v125, v126, v127
	v_cvt_pk_bf16_f32 v126, v120, v121
	v_cvt_pk_bf16_f32 v127, v122, v123
	global_store_dwordx4 v[158:159], v[108:111], off offset:256
	v_cvt_pk_bf16_f32 v92, v92, v93
	v_cvt_pk_bf16_f32 v93, v94, v95
	v_lshl_add_u64 v[108:109], v[104:105], 1, v[156:157]
	v_cvt_pk_bf16_f32 v94, v88, v89
	v_cvt_pk_bf16_f32 v95, v90, v91
	v_mad_i64_i32 v[88:89], s[4:5], s17, v140, 0
	global_store_dwordx4 v[158:159], v[124:127], off
	v_cvt_pk_bf16_f32 v104, v116, v117
	v_cvt_pk_bf16_f32 v105, v118, v119
	v_cvt_pk_bf16_f32 v106, v112, v113
	v_cvt_pk_bf16_f32 v107, v114, v115
	global_store_dwordx4 v[108:109], v[92:95], off offset:256
	v_cvt_pk_bf16_f32 v76, v76, v77
	v_cvt_pk_bf16_f32 v77, v78, v79
	v_lshl_add_u64 v[92:93], v[88:89], 1, v[156:157]
	v_cvt_pk_bf16_f32 v78, v72, v73
	v_cvt_pk_bf16_f32 v79, v74, v75
	v_mad_i64_i32 v[72:73], s[4:5], s17, v142, 0
	v_cvt_pk_bf16_f32 v68, v68, v69
	v_cvt_pk_bf16_f32 v69, v70, v71
	v_cvt_pk_bf16_f32 v70, v64, v65
	v_mad_i64_i32 v[64:65], s[4:5], s17, v144, 0
	global_store_dwordx4 v[108:109], v[104:107], off
	v_cvt_pk_bf16_f32 v88, v100, v101
	v_cvt_pk_bf16_f32 v89, v102, v103
	v_cvt_pk_bf16_f32 v90, v96, v97
	v_cvt_pk_bf16_f32 v91, v98, v99
	global_store_dwordx4 v[92:93], v[76:79], off offset:256
	v_cvt_pk_bf16_f32 v74, v80, v81
	v_cvt_pk_bf16_f32 v75, v82, v83
	v_lshl_add_u64 v[76:77], v[72:73], 1, v[156:157]
	v_cvt_pk_bf16_f32 v72, v84, v85
	v_cvt_pk_bf16_f32 v73, v86, v87
	v_cvt_pk_bf16_f32 v71, v66, v67
	v_lshl_add_u64 v[64:65], v[64:65], 1, v[156:157]
	v_cvt_pk_bf16_f32 v44, v44, v45
	v_cvt_pk_bf16_f32 v45, v46, v47
	v_cvt_pk_bf16_f32 v46, v40, v41
	v_cvt_pk_bf16_f32 v47, v42, v43
	v_mad_i64_i32 v[40:41], s[4:5], s17, v146, 0
	global_store_dwordx4 v[92:93], v[88:91], off
	global_store_dwordx4 v[76:77], v[72:75], off
	global_store_dwordx4 v[76:77], v[68:71], off offset:256
	v_cvt_pk_bf16_f32 v60, v60, v61
	v_cvt_pk_bf16_f32 v61, v62, v63
	v_cvt_pk_bf16_f32 v62, v56, v57
	v_cvt_pk_bf16_f32 v63, v58, v59
	global_store_dwordx4 v[64:65], v[44:47], off offset:256
	v_cvt_pk_bf16_f32 v28, v28, v29
	v_cvt_pk_bf16_f32 v29, v30, v31
	v_lshl_add_u64 v[44:45], v[40:41], 1, v[156:157]
	v_cvt_pk_bf16_f32 v30, v24, v25
	v_cvt_pk_bf16_f32 v31, v26, v27
	v_mad_i64_i32 v[24:25], s[4:5], s17, v148, 0
	global_store_dwordx4 v[64:65], v[60:63], off
	v_cvt_pk_bf16_f32 v40, v52, v53
	v_cvt_pk_bf16_f32 v41, v54, v55
	v_cvt_pk_bf16_f32 v42, v48, v49
	v_cvt_pk_bf16_f32 v43, v50, v51
	global_store_dwordx4 v[44:45], v[28:31], off offset:256
	v_cvt_pk_bf16_f32 v12, v12, v13
	v_cvt_pk_bf16_f32 v13, v14, v15
	v_lshl_add_u64 v[28:29], v[24:25], 1, v[156:157]
	v_cvt_pk_bf16_f32 v14, v8, v9
	v_cvt_pk_bf16_f32 v15, v10, v11
	v_mad_i64_i32 v[8:9], s[4:5], s17, v150, 0
	global_store_dwordx4 v[44:45], v[40:43], off
	v_cvt_pk_bf16_f32 v24, v36, v37
	v_cvt_pk_bf16_f32 v25, v38, v39
	v_cvt_pk_bf16_f32 v26, v32, v33
	v_cvt_pk_bf16_f32 v27, v34, v35
	global_store_dwordx4 v[28:29], v[12:15], off offset:256
	v_cvt_pk_bf16_f32 v10, v16, v17
	v_cvt_pk_bf16_f32 v11, v18, v19
	v_lshl_add_u64 v[12:13], v[8:9], 1, v[156:157]
	v_cvt_pk_bf16_f32 v8, v20, v21
	v_cvt_pk_bf16_f32 v9, v22, v23
	v_cvt_pk_bf16_f32 v4, v4, v5
	v_cvt_pk_bf16_f32 v5, v6, v7
	v_cvt_pk_bf16_f32 v6, v0, v1
	v_cvt_pk_bf16_f32 v7, v2, v3
	s_and_b64 vcc, exec, s[36:37]
	s_mov_b32 s38, s42
	s_mov_b32 s34, s44
	s_mov_b64 s[50:51], s[48:49]
	s_mov_b64 s[40:41], s[46:47]
	global_store_dwordx4 v[28:29], v[24:27], off
	global_store_dwordx4 v[12:13], v[8:11], off
	global_store_dwordx4 v[12:13], v[4:7], off offset:256
	s_cbranch_vccz .LBB0_1117
	v_readlane_b32 s4, v253, 1
	s_waitcnt vmcnt(0)
	v_readlane_b32 s5, v253, 2
	s_andn2_b64 vcc, exec, s[4:5]
	s_cbranch_vccnz .LBB0_1124
	s_barrier

; #define PG8_STAGE(bufoff, gbase, voff) do { _Pragma("unroll") for (int _i = 0; _i < 2; ++_i) \
;         __builtin_amdgcn_global_load_lds((const unsigned*)((const char*)(gbase) + (voff)[_i]), (LAS unsigned*)(lds + (bufoff) + ldsw + _i * 8192), 16, 0, 0); } while (0)
; #define PG8_WAIT_V(n) asm volatile("s_waitcnt vmcnt(" #n ")" ::: "memory")
; #define PG8_BAR __builtin_amdgcn_s_barrier()
; template <class Epi, class Sched, bool ALIGN_EPI>
; __device__ __forceinline__ void gemm_phase(LAS unsigned char* lds, const int wid, const int lda_, const int ldb_, const int K_, const Sched& S, const Epi& E) {
;     ...
;         const bool has_next = S.next(ui + 1, nxt);
;         const int nt = S.nt(cur);
;         const char* nA = has_next ? S.a(nxt) : cA; const char* nB = has_next ? S.b(nxt) : cB;
; #pragma unroll 1
;         for (int t = 0; t < nt; t += 2) {
;             const bool last = (t == nt - 2);
;             const char* a1 = cA + (size_t)(t + 1) * kstep;
;             const char* a2 = last ? nA : cA + (size_t)(t + 2) * kstep; const char* b2 = last ? nB : cB + (size_t)(t + 2) * kstep;
;             const char* a3 = a2 + kstep; const char* b3 = b2 + kstep;
;             PG8_LDB(B0, 0, 0); PG8_LDB(B1, 0, 1); PG8_SCHED; PG8_LDA(At, 0, 0); PG8_STAGE(PG8_SA(1, 1), a1 + hstepA, voffA);
;             PG8_WAIT_V(8); PG8_WAIT_L(0); PG8_BAR; PG8_MMA(0, 0, At, B0); PG8_MMA(0, 1, At, B1); PG8_BAR; PG8_SCHED;
;             PG8_LDA(At, 0, 1); PG8_STAGE(PG8_SB(0, 0), b2, voffB); PG8_STAGE(PG8_SB(0, 1), b2 + hstepB, voffB); PG8_STAGE(PG8_SA(0, 0), a2, voffA);
;             PG8_WAIT_V(8); PG8_WAIT_L(0); PG8_BAR; PG8_MMA(1, 0, At, B0); PG8_MMA(1, 1, At, B1); PG8_BAR; PG8_SCHED;
;     __device__ __forceinline__ void out(const pg8::Unit& u, char*& o, int& ldo, int& kind) const { ldo = D;
;         if (u.kq < 0) { o = (char*)ws + YOFF + ((size_t)u.pm * 256 * D + (size_t)u.pn * 256) * 2; kind = 0; }
;         else { o = (char*)ws + WS_PART + (((size_t)u.kq * MCTX + (size_t)(u.pm - 64) * 256) * D + (size_t)u.pn * 256) * 2; kind = 0; } }
;     __device__ __forceinline__ const char* a(const pg8::Unit& u) const { return (const char*)ws + aoff + (size_t)u.pm * 256 * K_ * 2 + (u.kq < 0 ? 0 : u.kq * (K_ / 4) * 2); }
;     __device__ __forceinline__ const char* b(const pg8::Unit& u) const { return (const char*)ws + boff + (size_t)u.pn * 256 * K_ * 2 + (u.kq < 0 ? 0 : u.kq * (K_ / 4) * 2); }
.LBB0_1340:
	s_cmp_gt_i32 s38, -1
	s_cselect_b64 s[44:45], -1, 0
	s_cmp_lt_i32 s38, 0
	s_cselect_b32 s4, 0x58, 22
	s_add_i32 s5, s4, -2
	s_add_u32 s46, s46, 0x80
	s_addc_u32 s47, s47, 0
	s_add_u32 s31, s48, 0x100
	s_mov_b32 s39, 0
	s_addc_u32 s35, s49, 0
	s_add_i32 s76, s39, 2
	s_add_u32 s17, s46, 0x80
	s_addc_u32 s27, s47, 0
	s_add_i32 s77, 0, 0x10000
	s_cmp_eq_u32 s5, s39
	s_cselect_b32 s49, s43, s27
	s_cselect_b32 s48, s42, s17
	v_add_u32_e32 v141, s77, v135
	s_cselect_b32 s79, s37, s35
	s_cselect_b32 s78, s36, s31
	s_add_i32 s17, 0, 0x14000
	ds_read_b128 v[156:159], v141
	ds_read_b128 v[160:163], v141 offset:1024
	ds_read_b128 v[164:167], v141 offset:2048
	ds_read_b128 v[168:171], v141 offset:3072
	v_add_u32_e32 v141, s17, v135
	ds_read_b128 v[172:175], v141
	ds_read_b128 v[180:183], v141 offset:1024
	ds_read_b128 v[184:187], v141 offset:2048
	ds_read_b128 v[188:191], v141 offset:3072
	v_lshl_add_u64 v[224:225], s[46:47], 0, v[152:153]
	s_add_i32 m0, s16, 0xc000
	ds_read_b128 v[192:195], v139
	ds_read_b128 v[196:199], v139 offset:1024
	ds_read_b128 v[200:203], v139 offset:2048
	ds_read_b128 v[204:207], v139 offset:3072
	ds_read_b128 v[208:211], v139 offset:4096
	ds_read_b128 v[212:215], v139 offset:5120
	ds_read_b128 v[216:219], v139 offset:6144
	ds_read_b128 v[220:223], v139 offset:7168
	global_load_lds_dwordx4 v[224:225], off
	v_lshl_add_u64 v[224:225], s[46:47], 0, v[154:155]
	s_add_i32 m0, s16, 0xe000
	s_nop 0
	global_load_lds_dwordx4 v[224:225], off
	v_readlane_b32 s101, v252, 58
	s_nop 3
	s_bitcmp1_b32 s101, 0
	s_cbranch_scc0 .Lvw_1341_0
	s_waitcnt vmcnt(8)
.Lvw_1341_0:
	s_waitcnt lgkmcnt(0)
	s_barrier
	s_setprio 0
	s_waitcnt lgkmcnt(0)
	v_mfma_f32_16x16x32_bf16 v[124:127], v[156:159], v[192:195], 0
	v_mfma_f32_16x16x32_bf16 v[120:123], v[164:167], v[192:195], 0
	v_mfma_f32_16x16x32_bf16 v[116:119], v[156:159], v[200:203], 0
	v_mfma_f32_16x16x32_bf16 v[112:115], v[164:167], v[200:203], 0
	v_mfma_f32_16x16x32_bf16 v[100:103], v[156:159], v[208:211], 0
	v_mfma_f32_16x16x32_bf16 v[96:99], v[164:167], v[208:211], 0
	v_mfma_f32_16x16x32_bf16 v[84:87], v[156:159], v[216:219], 0
	v_mfma_f32_16x16x32_bf16 v[80:83], v[164:167], v[216:219], 0
	v_mfma_f32_16x16x32_bf16 v[124:127], v[160:163], v[196:199], v[124:127]
	v_mfma_f32_16x16x32_bf16 v[120:123], v[168:171], v[196:199], v[120:123]
	v_mfma_f32_16x16x32_bf16 v[116:119], v[160:163], v[204:207], v[116:119]
	v_mfma_f32_16x16x32_bf16 v[112:115], v[168:171], v[204:207], v[112:115]
	v_mfma_f32_16x16x32_bf16 v[100:103], v[160:163], v[212:215], v[100:103]
	v_mfma_f32_16x16x32_bf16 v[96:99], v[168:171], v[212:215], v[96:99]
	v_mfma_f32_16x16x32_bf16 v[84:87], v[160:163], v[220:223], v[84:87]
	v_mfma_f32_16x16x32_bf16 v[80:83], v[168:171], v[220:223], v[80:83]
	v_mfma_f32_16x16x32_bf16 v[108:111], v[172:175], v[192:195], 0
	v_mfma_f32_16x16x32_bf16 v[104:107], v[184:187], v[192:195], 0
	v_mfma_f32_16x16x32_bf16 v[92:95], v[172:175], v[200:203], 0
	v_mfma_f32_16x16x32_bf16 v[88:91], v[184:187], v[200:203], 0
	v_mfma_f32_16x16x32_bf16 v[76:79], v[172:175], v[208:211], 0
	v_mfma_f32_16x16x32_bf16 v[72:75], v[184:187], v[208:211], 0
	v_mfma_f32_16x16x32_bf16 v[68:71], v[172:175], v[216:219], 0
	v_mfma_f32_16x16x32_bf16 v[64:67], v[184:187], v[216:219], 0
	v_mfma_f32_16x16x32_bf16 v[108:111], v[180:183], v[196:199], v[108:111]
	v_mfma_f32_16x16x32_bf16 v[104:107], v[188:191], v[196:199], v[104:107]
	v_mfma_f32_16x16x32_bf16 v[92:95], v[180:183], v[204:207], v[92:95]
	v_mfma_f32_16x16x32_bf16 v[88:91], v[188:191], v[204:207], v[88:91]
	v_mfma_f32_16x16x32_bf16 v[76:79], v[180:183], v[212:215], v[76:79]
	v_mfma_f32_16x16x32_bf16 v[72:75], v[188:191], v[212:215], v[72:75]
	v_mfma_f32_16x16x32_bf16 v[68:71], v[180:183], v[220:223], v[68:71]
	v_mfma_f32_16x16x32_bf16 v[64:67], v[188:191], v[220:223], v[64:67]
	s_waitcnt vmcnt(8)
	s_barrier
	s_add_i32 s27, s77, s3
	v_lshl_add_u64 v[224:225], s[78:79], 0, v[176:177]
	s_mov_b32 m0, s27
	ds_read_b128 v[192:195], v139 offset:16384
	ds_read_b128 v[196:199], v139 offset:17408
	ds_read_b128 v[200:203], v139 offset:18432
	ds_read_b128 v[204:207], v139 offset:19456
	ds_read_b128 v[208:211], v139 offset:20480
	ds_read_b128 v[212:215], v139 offset:21504
	ds_read_b128 v[216:219], v139 offset:22528
	ds_read_b128 v[220:223], v139 offset:23552
	global_load_lds_dwordx4 v[224:225], off
	s_add_i32 m0, s27, 0x2000
	v_lshl_add_u64 v[226:227], s[78:79], 0, v[132:133]
	s_add_u32 s78, s78, s10
	s_addc_u32 s79, s79, s11
	s_add_i32 s17, s17, s3
	global_load_lds_dwordx4 v[226:227], off
	v_lshl_add_u64 v[228:229], s[78:79], 0, v[176:177]
	s_mov_b32 m0, s17
	v_lshl_add_u64 v[230:231], s[78:79], 0, v[132:133]
	global_load_lds_dwordx4 v[228:229], off
	s_add_i32 m0, s17, 0x2000
	v_lshl_add_u64 v[232:233], s[48:49], 0, v[128:129]
	global_load_lds_dwordx4 v[230:231], off
	s_mov_b32 m0, s16
	v_lshl_add_u64 v[234:235], s[48:49], 0, v[130:131]
	global_load_lds_dwordx4 v[232:233], off
	s_mov_b32 m0, s14
	s_nop 0
	global_load_lds_dwordx4 v[234:235], off
	s_bitcmp1_b32 s101, 0
	s_cbranch_scc0 .Lvw_1341_1
	s_waitcnt vmcnt(8)

; #define PG8_STAGE(bufoff, gbase, voff) do { _Pragma("unroll") for (int _i = 0; _i < 2; ++_i) \
;         __builtin_amdgcn_global_load_lds((const unsigned*)((const char*)(gbase) + (voff)[_i]), (LAS unsigned*)(lds + (bufoff) + ldsw + _i * 8192), 16, 0, 0); } while (0)
; #define PG8_LDA(dst, b, h) do { _Pragma("unroll") for (int m = 0; m < 4; ++m) _Pragma("unroll") for (int k = 0; k < 2; ++k) dst[m][k] = *(const LAS bf16x8*)(lds + PG8_SA(b, h) + aoff + m * 2048 + k * 1024); } while (0)
; #define PG8_LDB(dst, b, h) do { _Pragma("unroll") for (int n = 0; n < 2; ++n) _Pragma("unroll") for (int k = 0; k < 2; ++k) dst[n][k] = *(const LAS bf16x8*)(lds + PG8_SB(b, h) + boff + n * 2048 + k * 1024); } while (0)
; #define PG8_MMA(ai, bj, At, Bt) do { __builtin_amdgcn_s_setprio(1); _Pragma("unroll") for (int m = 0; m < 4; ++m) _Pragma("unroll") for (int n = 0; n < 2; ++n) _Pragma("unroll") for (int k = 0; k < 2; ++k) \
;         acc[ai][bj][m][n] = __builtin_amdgcn_mfma_f32_16x16x32_bf16(Bt[n][k], At[m][k], acc[ai][bj][m][n], 0, 0, 0); __builtin_amdgcn_s_setprio(0); } while (0)
; #define PG8_WAIT_V(n) asm volatile("s_waitcnt vmcnt(" #n ")" ::: "memory")
; #define PG8_WAIT_L(n) asm volatile("s_waitcnt lgkmcnt(" #n ")" ::: "memory")
; #define PG8_BAR __builtin_amdgcn_s_barrier()
; #define PG8_SCHED __builtin_amdgcn_sched_barrier(0)
; template <class Epi, class Sched, bool ALIGN_EPI>
; __device__ __forceinline__ void gemm_phase(LAS unsigned char* lds, const int wid, const int lda_, const int ldb_, const int K_, const Sched& S, const Epi& E) {
;     ...
;             const bool last = (t == nt - 2);
;             const char* a1 = cA + (size_t)(t + 1) * kstep;
;             const char* a2 = last ? nA : cA + (size_t)(t + 2) * kstep; const char* b2 = last ? nB : cB + (size_t)(t + 2) * kstep;
;             const char* a3 = a2 + kstep; const char* b3 = b2 + kstep;
;             PG8_LDB(B0, 0, 0); PG8_LDB(B1, 0, 1); PG8_SCHED; PG8_LDA(At, 0, 0); PG8_STAGE(PG8_SA(1, 1), a1 + hstepA, voffA);
;             PG8_WAIT_V(8); PG8_WAIT_L(0); PG8_BAR; PG8_MMA(0, 0, At, B0); PG8_MMA(0, 1, At, B1); PG8_BAR; PG8_SCHED;
;             PG8_LDA(At, 0, 1); PG8_STAGE(PG8_SB(0, 0), b2, voffB); PG8_STAGE(PG8_SB(0, 1), b2 + hstepB, voffB); PG8_STAGE(PG8_SA(0, 0), a2, voffA);
;             PG8_WAIT_V(8); PG8_WAIT_L(0); PG8_BAR; PG8_MMA(1, 0, At, B0); PG8_MMA(1, 1, At, B1); PG8_BAR; PG8_SCHED;
.LBB0_1341:
	s_add_i32 s76, s39, 2
	s_add_u32 s17, s46, 0x80
	s_addc_u32 s27, s47, 0
	s_add_i32 s77, 0, 0x10000
	s_cmp_eq_u32 s5, s39
	s_cselect_b32 s49, s43, s27
	s_cselect_b32 s48, s42, s17
	v_add_u32_e32 v141, s77, v135
	s_cselect_b32 s79, s37, s35
	s_cselect_b32 s78, s36, s31
	s_add_i32 s17, 0, 0x14000
	ds_read_b128 v[156:159], v141
	ds_read_b128 v[160:163], v141 offset:1024
	ds_read_b128 v[164:167], v141 offset:2048
	ds_read_b128 v[168:171], v141 offset:3072
	v_add_u32_e32 v141, s17, v135
	ds_read_b128 v[172:175], v141
	ds_read_b128 v[180:183], v141 offset:1024
	ds_read_b128 v[184:187], v141 offset:2048
	ds_read_b128 v[188:191], v141 offset:3072
	v_lshl_add_u64 v[224:225], s[46:47], 0, v[152:153]
	s_add_i32 m0, s16, 0xc000
	ds_read_b128 v[192:195], v139
	ds_read_b128 v[196:199], v139 offset:1024
	ds_read_b128 v[200:203], v139 offset:2048
	ds_read_b128 v[204:207], v139 offset:3072
	ds_read_b128 v[208:211], v139 offset:4096
	ds_read_b128 v[212:215], v139 offset:5120
	ds_read_b128 v[216:219], v139 offset:6144
	ds_read_b128 v[220:223], v139 offset:7168
	global_load_lds_dwordx4 v[224:225], off
	v_lshl_add_u64 v[224:225], s[46:47], 0, v[154:155]
	s_add_i32 m0, s16, 0xe000
	s_nop 0
	global_load_lds_dwordx4 v[224:225], off
	s_bitcmp1_b32 s101, 0
	s_cbranch_scc0 .Lvw_1341_2
	s_waitcnt vmcnt(8)
.Lvw_1341_2:
	s_waitcnt lgkmcnt(0)
	s_barrier
	s_waitcnt lgkmcnt(0)
	v_mfma_f32_16x16x32_bf16 v[124:127], v[156:159], v[192:195], v[124:127]
	v_mfma_f32_16x16x32_bf16 v[120:123], v[164:167], v[192:195], v[120:123]
	v_mfma_f32_16x16x32_bf16 v[116:119], v[156:159], v[200:203], v[116:119]
	v_mfma_f32_16x16x32_bf16 v[112:115], v[164:167], v[200:203], v[112:115]
	v_mfma_f32_16x16x32_bf16 v[100:103], v[156:159], v[208:211], v[100:103]
	v_mfma_f32_16x16x32_bf16 v[96:99], v[164:167], v[208:211], v[96:99]
	v_mfma_f32_16x16x32_bf16 v[84:87], v[156:159], v[216:219], v[84:87]
	v_mfma_f32_16x16x32_bf16 v[80:83], v[164:167], v[216:219], v[80:83]
	v_mfma_f32_16x16x32_bf16 v[124:127], v[160:163], v[196:199], v[124:127]
	v_mfma_f32_16x16x32_bf16 v[120:123], v[168:171], v[196:199], v[120:123]
	v_mfma_f32_16x16x32_bf16 v[116:119], v[160:163], v[204:207], v[116:119]
	v_mfma_f32_16x16x32_bf16 v[112:115], v[168:171], v[204:207], v[112:115]
	v_mfma_f32_16x16x32_bf16 v[100:103], v[160:163], v[212:215], v[100:103]
	v_mfma_f32_16x16x32_bf16 v[96:99], v[168:171], v[212:215], v[96:99]
	v_mfma_f32_16x16x32_bf16 v[84:87], v[160:163], v[220:223], v[84:87]
	v_mfma_f32_16x16x32_bf16 v[80:83], v[168:171], v[220:223], v[80:83]
	v_mfma_f32_16x16x32_bf16 v[108:111], v[172:175], v[192:195], v[108:111]
	v_mfma_f32_16x16x32_bf16 v[104:107], v[184:187], v[192:195], v[104:107]
	v_mfma_f32_16x16x32_bf16 v[92:95], v[172:175], v[200:203], v[92:95]
	v_mfma_f32_16x16x32_bf16 v[88:91], v[184:187], v[200:203], v[88:91]
	v_mfma_f32_16x16x32_bf16 v[76:79], v[172:175], v[208:211], v[76:79]
	v_mfma_f32_16x16x32_bf16 v[72:75], v[184:187], v[208:211], v[72:75]
	v_mfma_f32_16x16x32_bf16 v[68:71], v[172:175], v[216:219], v[68:71]
	v_mfma_f32_16x16x32_bf16 v[64:67], v[184:187], v[216:219], v[64:67]
	v_mfma_f32_16x16x32_bf16 v[108:111], v[180:183], v[196:199], v[108:111]
	v_mfma_f32_16x16x32_bf16 v[104:107], v[188:191], v[196:199], v[104:107]
	v_mfma_f32_16x16x32_bf16 v[92:95], v[180:183], v[204:207], v[92:95]
	v_mfma_f32_16x16x32_bf16 v[88:91], v[188:191], v[204:207], v[88:91]
	v_mfma_f32_16x16x32_bf16 v[76:79], v[180:183], v[212:215], v[76:79]
	v_mfma_f32_16x16x32_bf16 v[72:75], v[188:191], v[212:215], v[72:75]
	v_mfma_f32_16x16x32_bf16 v[68:71], v[180:183], v[220:223], v[68:71]
	v_mfma_f32_16x16x32_bf16 v[64:67], v[188:191], v[220:223], v[64:67]
	s_waitcnt vmcnt(8)
	s_barrier
	s_add_i32 s27, s77, s3
	v_lshl_add_u64 v[224:225], s[78:79], 0, v[176:177]
	s_mov_b32 m0, s27
	ds_read_b128 v[192:195], v139 offset:16384
	ds_read_b128 v[196:199], v139 offset:17408
	ds_read_b128 v[200:203], v139 offset:18432
	ds_read_b128 v[204:207], v139 offset:19456
	ds_read_b128 v[208:211], v139 offset:20480
	ds_read_b128 v[212:215], v139 offset:21504
	ds_read_b128 v[216:219], v139 offset:22528
	ds_read_b128 v[220:223], v139 offset:23552
	global_load_lds_dwordx4 v[224:225], off
	s_add_i32 m0, s27, 0x2000
	v_lshl_add_u64 v[226:227], s[78:79], 0, v[132:133]
	s_add_u32 s78, s78, s10
	s_addc_u32 s79, s79, s11
	s_add_i32 s17, s17, s3
	global_load_lds_dwordx4 v[226:227], off
	v_lshl_add_u64 v[228:229], s[78:79], 0, v[176:177]
	s_mov_b32 m0, s17
	v_lshl_add_u64 v[230:231], s[78:79], 0, v[132:133]
	global_load_lds_dwordx4 v[228:229], off
	s_add_i32 m0, s17, 0x2000
	v_lshl_add_u64 v[232:233], s[48:49], 0, v[128:129]
	global_load_lds_dwordx4 v[230:231], off
	s_mov_b32 m0, s16
	v_lshl_add_u64 v[234:235], s[48:49], 0, v[130:131]
	global_load_lds_dwordx4 v[232:233], off
	s_mov_b32 m0, s14
	s_nop 0
	global_load_lds_dwordx4 v[234:235], off
	s_bitcmp1_b32 s101, 0
	s_cbranch_scc0 .Lvw_1341_3
	s_waitcnt vmcnt(8)

; #define PG8_STAGE(bufoff, gbase, voff) do { _Pragma("unroll") for (int _i = 0; _i < 2; ++_i) \
;         __builtin_amdgcn_global_load_lds((const unsigned*)((const char*)(gbase) + (voff)[_i]), (LAS unsigned*)(lds + (bufoff) + ldsw + _i * 8192), 16, 0, 0); } while (0)
; #define PG8_LDA(dst, b, h) do { _Pragma("unroll") for (int m = 0; m < 4; ++m) _Pragma("unroll") for (int k = 0; k < 2; ++k) dst[m][k] = *(const LAS bf16x8*)(lds + PG8_SA(b, h) + aoff + m * 2048 + k * 1024); } while (0)
; #define PG8_LDB(dst, b, h) do { _Pragma("unroll") for (int n = 0; n < 2; ++n) _Pragma("unroll") for (int k = 0; k < 2; ++k) dst[n][k] = *(const LAS bf16x8*)(lds + PG8_SB(b, h) + boff + n * 2048 + k * 1024); } while (0)
; #define PG8_MMA(ai, bj, At, Bt) do { __builtin_amdgcn_s_setprio(1); _Pragma("unroll") for (int m = 0; m < 4; ++m) _Pragma("unroll") for (int n = 0; n < 2; ++n) _Pragma("unroll") for (int k = 0; k < 2; ++k) \
;         acc[ai][bj][m][n] = __builtin_amdgcn_mfma_f32_16x16x32_bf16(Bt[n][k], At[m][k], acc[ai][bj][m][n], 0, 0, 0); __builtin_amdgcn_s_setprio(0); } while (0)
; #define PG8_WAIT_V(n) asm volatile("s_waitcnt vmcnt(" #n ")" ::: "memory")
; #define PG8_WAIT_L(n) asm volatile("s_waitcnt lgkmcnt(" #n ")" ::: "memory")
; #define PG8_BAR __builtin_amdgcn_s_barrier()
; #define PG8_SCHED __builtin_amdgcn_sched_barrier(0)
; template <class Epi, class Sched, bool ALIGN_EPI>
; __device__ __forceinline__ void gemm_phase(LAS unsigned char* lds, const int wid, const int lda_, const int ldb_, const int K_, const Sched& S, const Epi& E) {
;     ...
;             PG8_LDB(B0, 1, 0); PG8_LDB(B1, 1, 1); PG8_SCHED; PG8_LDA(At, 1, 0); PG8_STAGE(PG8_SA(0, 1), a2 + hstepA, voffA);
;             PG8_WAIT_V(8); PG8_WAIT_L(0); PG8_BAR; PG8_MMA(0, 0, At, B0); PG8_MMA(0, 1, At, B1); PG8_BAR; PG8_SCHED;
;             PG8_LDA(At, 1, 1); PG8_STAGE(PG8_SB(1, 0), b3, voffB); PG8_STAGE(PG8_SB(1, 1), b3 + hstepB, voffB); PG8_STAGE(PG8_SA(1, 0), a3, voffA);
;             PG8_WAIT_V(8); PG8_WAIT_L(0); PG8_BAR; PG8_MMA(1, 0, At, B0); PG8_MMA(1, 1, At, B1); PG8_BAR; PG8_SCHED;
.Lgemm_join_1341:
	s_add_i32 s17, 0, 0x18000
	v_add_u32_e32 v141, s17, v135
	s_add_i32 s27, 0, 0x1c000
	ds_read_b128 v[156:159], v141
	ds_read_b128 v[160:163], v141 offset:1024
	ds_read_b128 v[164:167], v141 offset:2048
	ds_read_b128 v[168:171], v141 offset:3072
	v_add_u32_e32 v141, s27, v135
	ds_read_b128 v[172:175], v141
	ds_read_b128 v[180:183], v141 offset:1024
	ds_read_b128 v[184:187], v141 offset:2048
	ds_read_b128 v[188:191], v141 offset:3072
	s_add_u32 s48, s48, s0
	s_addc_u32 s49, s49, s1
	s_mov_b32 m0, s15
	v_lshl_add_u64 v[236:237], s[48:49], 0, v[128:129]
	ds_read_b128 v[192:195], v139 offset:32768
	ds_read_b128 v[196:199], v139 offset:33792
	ds_read_b128 v[200:203], v139 offset:34816
	ds_read_b128 v[204:207], v139 offset:35840
	ds_read_b128 v[208:211], v139 offset:36864
	ds_read_b128 v[212:215], v139 offset:37888
	ds_read_b128 v[216:219], v139 offset:38912
	ds_read_b128 v[220:223], v139 offset:39936
	global_load_lds_dwordx4 v[236:237], off
	v_lshl_add_u64 v[236:237], s[48:49], 0, v[130:131]
	s_mov_b32 m0, s26
	s_nop 0
	global_load_lds_dwordx4 v[236:237], off
	s_bitcmp1_b32 s101, 0
	s_cbranch_scc0 .Lvw_1341_4
	s_waitcnt vmcnt(8)
.Lvw_1341_4:
	s_waitcnt lgkmcnt(0)
	s_barrier
	s_waitcnt lgkmcnt(0)
	v_mfma_f32_16x16x32_bf16 v[124:127], v[156:159], v[192:195], v[124:127]
	v_mfma_f32_16x16x32_bf16 v[120:123], v[164:167], v[192:195], v[120:123]
	v_mfma_f32_16x16x32_bf16 v[116:119], v[156:159], v[200:203], v[116:119]
	v_mfma_f32_16x16x32_bf16 v[112:115], v[164:167], v[200:203], v[112:115]
	v_mfma_f32_16x16x32_bf16 v[100:103], v[156:159], v[208:211], v[100:103]
	v_mfma_f32_16x16x32_bf16 v[96:99], v[164:167], v[208:211], v[96:99]
	v_mfma_f32_16x16x32_bf16 v[84:87], v[156:159], v[216:219], v[84:87]
	v_mfma_f32_16x16x32_bf16 v[80:83], v[164:167], v[216:219], v[80:83]
	v_mfma_f32_16x16x32_bf16 v[124:127], v[160:163], v[196:199], v[124:127]
	v_mfma_f32_16x16x32_bf16 v[120:123], v[168:171], v[196:199], v[120:123]
	v_mfma_f32_16x16x32_bf16 v[116:119], v[160:163], v[204:207], v[116:119]
	v_mfma_f32_16x16x32_bf16 v[112:115], v[168:171], v[204:207], v[112:115]
	v_mfma_f32_16x16x32_bf16 v[100:103], v[160:163], v[212:215], v[100:103]
	v_mfma_f32_16x16x32_bf16 v[96:99], v[168:171], v[212:215], v[96:99]
	v_mfma_f32_16x16x32_bf16 v[84:87], v[160:163], v[220:223], v[84:87]
	v_mfma_f32_16x16x32_bf16 v[80:83], v[168:171], v[220:223], v[80:83]
	v_mfma_f32_16x16x32_bf16 v[108:111], v[172:175], v[192:195], v[108:111]
	v_mfma_f32_16x16x32_bf16 v[104:107], v[184:187], v[192:195], v[104:107]
	v_mfma_f32_16x16x32_bf16 v[92:95], v[172:175], v[200:203], v[92:95]
	v_mfma_f32_16x16x32_bf16 v[88:91], v[184:187], v[200:203], v[88:91]
	v_mfma_f32_16x16x32_bf16 v[76:79], v[172:175], v[208:211], v[76:79]
	v_mfma_f32_16x16x32_bf16 v[72:75], v[184:187], v[208:211], v[72:75]
	v_mfma_f32_16x16x32_bf16 v[68:71], v[172:175], v[216:219], v[68:71]
	v_mfma_f32_16x16x32_bf16 v[64:67], v[184:187], v[216:219], v[64:67]
	v_mfma_f32_16x16x32_bf16 v[108:111], v[180:183], v[196:199], v[108:111]
	v_mfma_f32_16x16x32_bf16 v[104:107], v[188:191], v[196:199], v[104:107]
	v_mfma_f32_16x16x32_bf16 v[92:95], v[180:183], v[204:207], v[92:95]
	v_mfma_f32_16x16x32_bf16 v[88:91], v[188:191], v[204:207], v[88:91]
	v_mfma_f32_16x16x32_bf16 v[76:79], v[180:183], v[212:215], v[76:79]
	v_mfma_f32_16x16x32_bf16 v[72:75], v[188:191], v[212:215], v[72:75]
	v_mfma_f32_16x16x32_bf16 v[68:71], v[180:183], v[220:223], v[68:71]
	v_mfma_f32_16x16x32_bf16 v[64:67], v[188:191], v[220:223], v[64:67]
	s_waitcnt vmcnt(8)
	s_barrier
	s_add_i32 s17, s17, s3
	v_lshl_add_u64 v[224:225], v[224:225], 0, s[24:25]
	s_mov_b32 m0, s17
	ds_read_b128 v[192:195], v139 offset:49152
	ds_read_b128 v[196:199], v139 offset:50176
	ds_read_b128 v[200:203], v139 offset:51200
	ds_read_b128 v[204:207], v139 offset:52224
	ds_read_b128 v[208:211], v139 offset:53248
	ds_read_b128 v[212:215], v139 offset:54272
	ds_read_b128 v[216:219], v139 offset:55296
	ds_read_b128 v[220:223], v139 offset:56320
	global_load_lds_dwordx4 v[224:225], off
	v_lshl_add_u64 v[224:225], v[226:227], 0, s[24:25]
	s_add_i32 m0, s17, 0x2000
	s_add_i32 s17, s27, s3
	global_load_lds_dwordx4 v[224:225], off
	v_lshl_add_u64 v[224:225], v[228:229], 0, s[24:25]
	s_mov_b32 m0, s17
	s_nop 0
	global_load_lds_dwordx4 v[224:225], off
	v_lshl_add_u64 v[224:225], v[230:231], 0, s[24:25]
	s_add_i32 m0, s17, 0x2000
	s_nop 0
	global_load_lds_dwordx4 v[224:225], off
	v_lshl_add_u64 v[224:225], v[232:233], 0, s[24:25]
	s_mov_b32 m0, s50
	s_nop 0
	global_load_lds_dwordx4 v[224:225], off
	v_lshl_add_u64 v[224:225], v[234:235], 0, s[24:25]
	s_mov_b32 m0, s51
	s_nop 0
	global_load_lds_dwordx4 v[224:225], off
	s_bitcmp1_b32 s101, 0
	s_cbranch_scc0 .Lvw_1341_5
	s_waitcnt vmcnt(8)
; #define PG8_MMA(ai, bj, At, Bt) do { __builtin_amdgcn_s_setprio(1); _Pragma("unroll") for (int m = 0; m < 4; ++m) _Pragma("unroll") for (int n = 0; n < 2; ++n) _Pragma("unroll") for (int k = 0; k < 2; ++k) \
;         acc[ai][bj][m][n] = __builtin_amdgcn_mfma_f32_16x16x32_bf16(Bt[n][k], At[m][k], acc[ai][bj][m][n], 0, 0, 0); __builtin_amdgcn_s_setprio(0); } while (0)
; #define PG8_WAIT_V(n) asm volatile("s_waitcnt vmcnt(" #n ")" ::: "memory")
; #define PG8_WAIT_L(n) asm volatile("s_waitcnt lgkmcnt(" #n ")" ::: "memory")
; #define PG8_BAR __builtin_amdgcn_s_barrier()
; #define PG8_SCHED __builtin_amdgcn_sched_barrier(0)
; template <class Epi, class Sched, bool ALIGN_EPI>
; __device__ __forceinline__ void gemm_phase(LAS unsigned char* lds, const int wid, const int lda_, const int ldb_, const int K_, const Sched& S, const Epi& E) {
;     ...
;             PG8_WAIT_V(8); PG8_WAIT_L(0); PG8_BAR; PG8_MMA(1, 0, At, B0); PG8_MMA(1, 1, At, B1); PG8_BAR; PG8_SCHED;
;         }
;     __device__ __forceinline__ void out(const pg8::Unit& u, char*& o, int& ldo, int& kind) const { ldo = D;
;         if (u.kq < 0) { o = (char*)ws + YOFF + ((size_t)u.pm * 256 * D + (size_t)u.pn * 256) * 2; kind = 0; }
;         else { o = (char*)ws + WS_PART + (((size_t)u.kq * MCTX + (size_t)(u.pm - 64) * 256) * D + (size_t)u.pn * 256) * 2; kind = 0; } }
.Lvw_1341_5:
	s_waitcnt lgkmcnt(0)
	s_barrier
	s_waitcnt lgkmcnt(0)
	v_mfma_f32_16x16x32_bf16 v[60:63], v[156:159], v[192:195], v[60:63]
	v_mfma_f32_16x16x32_bf16 v[56:59], v[164:167], v[192:195], v[56:59]
	v_mfma_f32_16x16x32_bf16 v[52:55], v[156:159], v[200:203], v[52:55]
	v_mfma_f32_16x16x32_bf16 v[48:51], v[164:167], v[200:203], v[48:51]
	v_mfma_f32_16x16x32_bf16 v[36:39], v[156:159], v[208:211], v[36:39]
	v_mfma_f32_16x16x32_bf16 v[32:35], v[164:167], v[208:211], v[32:35]
	v_mfma_f32_16x16x32_bf16 v[20:23], v[156:159], v[216:219], v[20:23]
	v_mfma_f32_16x16x32_bf16 v[16:19], v[164:167], v[216:219], v[16:19]
	v_mfma_f32_16x16x32_bf16 v[60:63], v[160:163], v[196:199], v[60:63]
	v_mfma_f32_16x16x32_bf16 v[56:59], v[168:171], v[196:199], v[56:59]
	v_mfma_f32_16x16x32_bf16 v[52:55], v[160:163], v[204:207], v[52:55]
	v_mfma_f32_16x16x32_bf16 v[48:51], v[168:171], v[204:207], v[48:51]
	v_mfma_f32_16x16x32_bf16 v[36:39], v[160:163], v[212:215], v[36:39]
	v_mfma_f32_16x16x32_bf16 v[32:35], v[168:171], v[212:215], v[32:35]
	v_mfma_f32_16x16x32_bf16 v[20:23], v[160:163], v[220:223], v[20:23]
	v_mfma_f32_16x16x32_bf16 v[16:19], v[168:171], v[220:223], v[16:19]
	v_mfma_f32_16x16x32_bf16 v[44:47], v[172:175], v[192:195], v[44:47]
	v_mfma_f32_16x16x32_bf16 v[40:43], v[184:187], v[192:195], v[40:43]
	v_mfma_f32_16x16x32_bf16 v[28:31], v[172:175], v[200:203], v[28:31]
	v_mfma_f32_16x16x32_bf16 v[24:27], v[184:187], v[200:203], v[24:27]
	v_mfma_f32_16x16x32_bf16 v[12:15], v[172:175], v[208:211], v[12:15]
	v_mfma_f32_16x16x32_bf16 v[8:11], v[184:187], v[208:211], v[8:11]
	v_mfma_f32_16x16x32_bf16 v[4:7], v[172:175], v[216:219], v[4:7]
	v_mfma_f32_16x16x32_bf16 v[0:3], v[184:187], v[216:219], v[0:3]
	v_mfma_f32_16x16x32_bf16 v[44:47], v[180:183], v[196:199], v[44:47]
	v_mfma_f32_16x16x32_bf16 v[40:43], v[188:191], v[196:199], v[40:43]
	v_mfma_f32_16x16x32_bf16 v[28:31], v[180:183], v[204:207], v[28:31]
	v_mfma_f32_16x16x32_bf16 v[24:27], v[188:191], v[204:207], v[24:27]
	v_mfma_f32_16x16x32_bf16 v[12:15], v[180:183], v[212:215], v[12:15]
	v_mfma_f32_16x16x32_bf16 v[8:11], v[188:191], v[212:215], v[8:11]
	v_mfma_f32_16x16x32_bf16 v[4:7], v[180:183], v[220:223], v[4:7]
	v_mfma_f32_16x16x32_bf16 v[0:3], v[188:191], v[220:223], v[0:3]
	s_waitcnt vmcnt(8)
	s_barrier
	s_add_u32 s46, s46, 0x100
	s_addc_u32 s47, s47, 0
	s_add_u32 s31, s31, 0x100
	s_addc_u32 s35, s35, 0
	s_cmp_ge_u32 s76, s4
	s_mov_b32 s39, s76
	s_cbranch_scc0 .LBB0_1341
	s_setprio 2
	s_mov_b64 s[46:47], -1
	s_and_b64 vcc, exec, s[44:45]
	s_cbranch_vccz .LBB0_1344
	s_mov_b32 s39, s92
	s_ashr_i32 s31, s30, 31
	s_ashr_i32 s35, s34, 31
	s_lshl_b64 s[4:5], s[30:31], 20
	s_lshl_b64 s[44:45], s[34:35], 9
	s_lshl_b64 s[38:39], s[38:39], 23
	v_readlane_b32 s46, v251, 28
	v_readlane_b32 s47, v251, 29
	s_add_u32 s17, s46, s44
	s_addc_u32 s27, s47, s45
	s_add_u32 s17, s17, s38
	s_addc_u32 s27, s27, s39
	s_add_u32 s4, s17, s4
	s_addc_u32 s5, s27, s5
	s_add_u32 s4, s4, 0xfc000000
	s_addc_u32 s5, s5, -1
	s_mov_b64 s[46:47], 0
